# speedup vs baseline: 1.0729x; 1.0729x over previous
.LBB0_348:
	s_cmpk_gt_i32 s16, 0xff
	s_mov_b64 s[4:5], -1
	s_cbranch_scc1 .LBB0_342
	s_ashr_i32 s4, s16, 31
	s_lshr_b32 s4, s4, 26
	s_add_i32 s4, s16, s4
	s_andn2_b32 s4, s4, 63
	s_sub_i32 s16, s16, s4
	s_ashr_i32 s5, s16, 3
	s_lshl_b32 s16, s16, 3
	s_and_b32 s16, s16, 56
	s_or_b32 s4, s4, s16
	s_mul_i32 s16, s5, 0x56000
	v_mov_b32_e32 v1, v170
	s_barrier
	s_or_b32 s4, s4, s18
	s_ashr_i32 s17, s16, 31
	s_lshl_b32 s4, s4, 8
	v_lshlrev_b32_e32 v145, 4, v1
	s_lshl_b64 s[16:17], s[16:17], 1
	v_add_u32_e32 v29, 0x1000, v145
	v_add_u32_e32 v30, 0x2000, v145
	v_add_u32_e32 v32, 0x3000, v145
	s_add_u32 s18, s20, s16
	v_and_b32_e32 v26, 32, v1
	v_bfe_u32 v27, v1, 2, 4
	v_ashrrev_i32_e32 v13, 2, v1
	v_ashrrev_i32_e32 v15, 6, v29
	v_ashrrev_i32_e32 v10, 6, v30
	v_ashrrev_i32_e32 v16, 6, v32
	s_addc_u32 s19, s21, s17
	v_lshrrev_b32_e32 v14, 2, v1
	v_bitop3_b32 v2, v145, v26, 48 bitop3:0x6c
	v_or_b32_e32 v12, s4, v27
	v_mov_b32_e32 v3, v0
	v_and_b32_e32 v6, -16, v13
	v_and_b32_e32 v8, -16, v15
	v_and_b32_e32 v31, -16, v10
	v_and_b32_e32 v33, -16, v16
	v_lshl_add_u64 v[4:5], s[38:39], 0, v[2:3]
	v_add_u32_e32 v6, v12, v6
	v_add_u32_e32 v8, v8, v12
	v_add_u32_e32 v10, v31, v12
	v_add_u32_e32 v12, v33, v12
	v_lshl_add_u64 v[2:3], s[18:19], 0, v[2:3]
	v_bfi_b32 v34, 15, v14, v13
	v_bfi_b32 v35, -16, v15, v14
	v_mad_i64_i32 v[6:7], s[26:27], v6, s3, v[4:5]
	v_mad_i64_i32 v[8:9], s[26:27], v8, s3, v[4:5]
	v_mad_i64_i32 v[10:11], s[26:27], v10, s3, v[4:5]
	v_mad_i64_i32 v[4:5], s[26:27], v12, s3, v[4:5]
	v_mad_i64_i32 v[12:13], s[18:19], v34, s3, v[2:3]
	v_mad_i64_i32 v[2:3], s[18:19], v35, s3, v[2:3]
	v_readfirstlane_b32 s18, v145
	s_waitcnt vmcnt(0)
	s_mov_b32 m0, s18
	v_readfirstlane_b32 s18, v29
	s_mov_b32 m0, s18
	v_readfirstlane_b32 s18, v30
	v_add_u32_e32 v36, 0x4000, v145
	s_mov_b32 m0, s18
	v_readfirstlane_b32 s18, v32
	v_add_u32_e32 v37, 0x5000, v145
	s_mov_b32 m0, s18
	v_readfirstlane_b32 s18, v36
	v_add_u32_e32 v38, 0x6000, v145
	s_mov_b32 m0, s18
	v_readfirstlane_b32 s18, v37
	v_and_b32_e32 v142, 15, v1
	v_bfe_u32 v143, v1, 4, 2
	v_lshlrev_b32_e32 v17, 6, v1
	v_lshlrev_b32_e32 v14, 2, v1
	v_add_u32_e32 v39, 0x7000, v145
	s_mov_b32 m0, s18
	v_readfirstlane_b32 s18, v38
	v_lshlrev_b32_e32 v16, 4, v143
	v_and_b32_e32 v18, 0x3c0, v17
	v_lshlrev_b32_e32 v19, 6, v142
	v_and_b32_e32 v20, 32, v14
	v_lshl_add_u64 v[14:15], v[6:7], 0, 64
	v_add_u32_e32 v40, 0x8000, v145
	s_mov_b32 m0, s18
	v_readfirstlane_b32 s18, v39
	v_add_u32_e32 v41, 0x9000, v145
	v_and_b32_e32 v147, 0xfffff000, v17
	v_bitop3_b32 v149, v16, v20, v18 bitop3:0x36
	v_bitop3_b32 v144, v16, v20, v19 bitop3:0x36
	v_lshl_add_u64 v[16:17], v[8:9], 0, 64
	s_mov_b32 m0, s18
	v_readfirstlane_b32 s18, v40
	v_add_u32_e32 v42, 0xa000, v145
	v_lshl_add_u64 v[18:19], v[10:11], 0, 64
	s_mov_b32 m0, s18
	v_readfirstlane_b32 s18, v41
	v_add_u32_e32 v43, 0xb000, v145
	v_lshl_add_u64 v[20:21], v[4:5], 0, 64
	s_mov_b32 m0, s18
	v_readfirstlane_b32 s18, v42
	v_lshl_add_u64 v[22:23], v[12:13], 0, 64
	s_mov_b32 m0, s18
	v_readfirstlane_b32 s18, v43
	v_lshl_add_u64 v[24:25], v[2:3], 0, 64
	s_mov_b32 m0, s18
	v_mov_b64_e32 v[2:3], s[16:17]
	v_and_b32_e32 v28, 48, v145
	v_mad_i64_i32 v[4:5], s[16:17], v35, s3, v[2:3]
	v_mad_i64_i32 v[2:3], s[16:17], v34, s3, v[2:3]
	v_bitop3_b32 v2, v2, v28, v26 bitop3:0xf6
	v_lshl_add_u64 v[132:133], s[12:13], 0, v[2:3]
	v_add_u32_e32 v2, s4, v33
	v_or_b32_e32 v2, v2, v27
	v_mad_i64_i32 v[2:3], s[16:17], v2, s3, 0
	v_bitop3_b32 v2, v2, v28, v26 bitop3:0xf6
	v_lshl_add_u64 v[134:135], s[14:15], 0, v[2:3]
	v_add_u32_e32 v2, s4, v31
	v_or_b32_e32 v2, v2, v27
	v_mad_i64_i32 v[2:3], s[16:17], v2, s3, 0
	v_bitop3_b32 v2, v2, v28, v26 bitop3:0xf6
	v_lshl_add_u64 v[136:137], s[14:15], 0, v[2:3]
	v_add_u32_e32 v2, s4, v35
	v_mad_i64_i32 v[2:3], s[16:17], v2, s3, 0
	v_bitop3_b32 v2, v2, v28, v26 bitop3:0xf6
	v_lshl_add_u64 v[138:139], s[14:15], 0, v[2:3]
	v_add_u32_e32 v2, s4, v34
	v_mad_i64_i32 v[2:3], s[16:17], v2, s3, 0
	v_bitop3_b32 v2, v2, v28, v26 bitop3:0xf6
	v_bitop3_b32 v4, v4, v28, v26 bitop3:0xf6
	v_lshl_add_u64 v[140:141], s[14:15], 0, v[2:3]
	v_mov_b32_e32 v2, 0
	v_lshl_add_u64 v[130:131], s[12:13], 0, v[4:5]
	s_mov_b32 s18, 0
	s_mov_b64 s[16:17], 0
	v_mov_b32_e32 v3, v2
	v_mov_b32_e32 v4, v2
	v_mov_b32_e32 v5, v2
	v_mov_b32_e32 v6, v2
	v_mov_b32_e32 v7, v2
	v_mov_b32_e32 v8, v2
	v_mov_b32_e32 v9, v2
	v_mov_b32_e32 v10, v2
	v_mov_b32_e32 v11, v2
	v_mov_b32_e32 v12, v2
	v_mov_b32_e32 v13, v2
	v_mov_b32_e32 v14, v2
	v_mov_b32_e32 v15, v2
	v_mov_b32_e32 v16, v2
	v_mov_b32_e32 v17, v2
	v_mov_b32_e32 v18, v2
	v_mov_b32_e32 v19, v2
	v_mov_b32_e32 v20, v2
	v_mov_b32_e32 v21, v2
	v_mov_b32_e32 v26, v2
	v_mov_b32_e32 v27, v2
	v_mov_b32_e32 v28, v2
	v_mov_b32_e32 v29, v2
	v_mov_b32_e32 v38, v2
	v_mov_b32_e32 v39, v2
	v_mov_b32_e32 v40, v2
	v_mov_b32_e32 v41, v2
	v_mov_b32_e32 v54, v2
	v_mov_b32_e32 v55, v2
	v_mov_b32_e32 v56, v2
	v_mov_b32_e32 v57, v2
	v_mov_b32_e32 v22, v2
	v_mov_b32_e32 v23, v2
	v_mov_b32_e32 v24, v2
	v_mov_b32_e32 v25, v2
	v_mov_b32_e32 v30, v2
	v_mov_b32_e32 v31, v2
	v_mov_b32_e32 v32, v2
	v_mov_b32_e32 v33, v2
	v_mov_b32_e32 v34, v2
	v_mov_b32_e32 v35, v2
	v_mov_b32_e32 v36, v2
	v_mov_b32_e32 v37, v2
	v_mov_b32_e32 v42, v2
	v_mov_b32_e32 v43, v2
	v_mov_b32_e32 v44, v2
	v_mov_b32_e32 v45, v2
	v_mov_b32_e32 v46, v2
	v_mov_b32_e32 v47, v2
	v_mov_b32_e32 v48, v2
	v_mov_b32_e32 v49, v2
	v_mov_b32_e32 v58, v2
	v_mov_b32_e32 v59, v2
	v_mov_b32_e32 v60, v2
	v_mov_b32_e32 v61, v2
	v_mov_b32_e32 v70, v2
	v_mov_b32_e32 v71, v2
	v_mov_b32_e32 v72, v2
	v_mov_b32_e32 v73, v2
	v_mov_b32_e32 v86, v2
	v_mov_b32_e32 v87, v2
	v_mov_b32_e32 v88, v2
	v_mov_b32_e32 v89, v2
	v_mov_b32_e32 v50, v2
	v_mov_b32_e32 v51, v2
	v_mov_b32_e32 v52, v2
	v_mov_b32_e32 v53, v2
	v_mov_b32_e32 v62, v2
	v_mov_b32_e32 v63, v2
	v_mov_b32_e32 v64, v2
	v_mov_b32_e32 v65, v2
	v_mov_b32_e32 v66, v2
	v_mov_b32_e32 v67, v2
	v_mov_b32_e32 v68, v2
	v_mov_b32_e32 v69, v2
	v_mov_b32_e32 v74, v2
	v_mov_b32_e32 v75, v2
	v_mov_b32_e32 v76, v2
	v_mov_b32_e32 v77, v2
	v_mov_b32_e32 v78, v2
	v_mov_b32_e32 v79, v2
	v_mov_b32_e32 v80, v2
	v_mov_b32_e32 v81, v2
	v_mov_b32_e32 v90, v2
	v_mov_b32_e32 v91, v2
	v_mov_b32_e32 v92, v2
	v_mov_b32_e32 v93, v2
	v_mov_b32_e32 v102, v2
	v_mov_b32_e32 v103, v2
	v_mov_b32_e32 v104, v2
	v_mov_b32_e32 v105, v2
	v_mov_b32_e32 v114, v2
	v_mov_b32_e32 v115, v2
	v_mov_b32_e32 v116, v2
	v_mov_b32_e32 v117, v2
	v_mov_b32_e32 v82, v2
	v_mov_b32_e32 v83, v2
	v_mov_b32_e32 v84, v2
	v_mov_b32_e32 v85, v2
	v_mov_b32_e32 v94, v2
	v_mov_b32_e32 v95, v2
	v_mov_b32_e32 v96, v2
	v_mov_b32_e32 v97, v2
	v_mov_b32_e32 v98, v2
	v_mov_b32_e32 v99, v2
	v_mov_b32_e32 v100, v2
	v_mov_b32_e32 v101, v2
	v_mov_b32_e32 v106, v2
	v_mov_b32_e32 v107, v2
	v_mov_b32_e32 v108, v2
	v_mov_b32_e32 v109, v2
	v_mov_b32_e32 v110, v2
	v_mov_b32_e32 v111, v2
	v_mov_b32_e32 v112, v2
	v_mov_b32_e32 v113, v2
	v_mov_b32_e32 v118, v2
	v_mov_b32_e32 v119, v2
	v_mov_b32_e32 v120, v2
	v_mov_b32_e32 v121, v2
	v_mov_b32_e32 v122, v2
	v_mov_b32_e32 v123, v2
	v_mov_b32_e32 v124, v2
	v_mov_b32_e32 v125, v2
	v_mov_b32_e32 v126, v2
	v_mov_b32_e32 v127, v2
	v_mov_b32_e32 v128, v2
	v_mov_b32_e32 v129, v2
	v_and_b32_e32 v154, 63, v170
	v_lshrrev_b32_e32 v155, 3, v154
	v_and_b32_e32 v156, 7, v154
	v_xor_b32_e32 v156, v156, v155
	v_lshrrev_b32_e32 v157, 6, v170
	v_lshl_add_u32 v158, v157, 6, v155
	v_add_u32_e32 v158, s4, v158
	v_mul_u32_u24_e32 v224, 0x1580, v158
	v_lshl_add_u32 v224, v156, 4, v224
	v_lshl_add_u32 v158, v157, 5, v155
	v_mul_u32_u24_e32 v225, 0x1580, v158
	v_lshl_add_u32 v225, v156, 4, v225
	v_and_b32_e32 v155, 15, v154
	v_lshrrev_b32_e32 v156, 4, v154
	v_and_b32_e32 v158, 7, v155
	v_xor_b32_e32 v156, v156, v158
	v_lshlrev_b32_e32 v156, 4, v156
	v_lshl_add_u32 v229, v155, 7, v156
	v_lshl_add_u32 v227, v157, 13, v229
	v_xor_b32_e32 v228, 64, v227
	v_add_u32_e32 v229, 0x8000, v229
	v_xor_b32_e32 v230, 64, v229
	s_mov_b32 s18, s38
	s_mov_b32 s19, s39
	s_mul_i32 s32, s5, 0xac000
	s_add_u32 s16, s20, s32
	s_addc_u32 s17, s21, 0
	s_mov_b32 s25, 0
	v_readfirstlane_b32 s32, v145
	s_lshl_b32 m0, s32, 3
	v_mov_b32_e32 v226, v224
	global_load_lds_dwordx4 v226, s[18:19]
	s_add_u32 m0, m0, 0x400
	v_add_u32_e32 v226, 0xac00, v224
	global_load_lds_dwordx4 v226, s[18:19]
	s_add_u32 m0, m0, 0x400
	v_add_u32_e32 v226, 0x15800, v224
	global_load_lds_dwordx4 v226, s[18:19]
	s_add_u32 m0, m0, 0x400
	v_add_u32_e32 v226, 0x20400, v224
	global_load_lds_dwordx4 v226, s[18:19]
	s_add_u32 m0, m0, 0x400
	v_add_u32_e32 v226, 0x2b000, v224
	global_load_lds_dwordx4 v226, s[18:19]
	s_add_u32 m0, m0, 0x400
	v_add_u32_e32 v226, 0x35c00, v224
	global_load_lds_dwordx4 v226, s[18:19]
	s_add_u32 m0, m0, 0x400
	v_add_u32_e32 v226, 0x40800, v224
	global_load_lds_dwordx4 v226, s[18:19]
	s_add_u32 m0, m0, 0x400
	v_add_u32_e32 v226, 0x4b400, v224
	global_load_lds_dwordx4 v226, s[18:19]
	v_readfirstlane_b32 s32, v145
	s_lshl_b32 s32, s32, 2
	s_add_u32 m0, s32, 0x8000
	v_mov_b32_e32 v226, v225
	global_load_lds_dwordx4 v226, s[16:17]
	s_add_u32 m0, m0, 0x400
	v_add_u32_e32 v226, 0xac00, v225
	global_load_lds_dwordx4 v226, s[16:17]
	s_add_u32 m0, m0, 0x400
	v_add_u32_e32 v226, 0x15800, v225
	global_load_lds_dwordx4 v226, s[16:17]
	s_add_u32 m0, m0, 0x400
	v_add_u32_e32 v226, 0x20400, v225
	global_load_lds_dwordx4 v226, s[16:17]
.Lbk64_350:
	s_waitcnt vmcnt(0)
	s_barrier
	ds_read_b128 v[192:195], v227
	ds_read_b128 v[196:199], v228
	ds_read_b128 v[200:203], v227 offset:2048
	ds_read_b128 v[204:207], v228 offset:2048
	ds_read_b128 v[208:211], v227 offset:4096
	ds_read_b128 v[212:215], v228 offset:4096
	ds_read_b128 v[216:219], v227 offset:6144
	ds_read_b128 v[220:223], v228 offset:6144
	s_add_u32 s18, s18, 0x80
	s_addc_u32 s19, s19, 0
	s_add_u32 s16, s16, 0x80
	s_addc_u32 s17, s17, 0
	s_waitcnt lgkmcnt(0)
	s_barrier
	ds_read_b128 v[154:157], v229 offset:0
	ds_read_b128 v[158:161], v230 offset:0
	ds_read_b128 v[162:165], v229 offset:2048
	ds_read_b128 v[166:169], v230 offset:2048
	s_waitcnt lgkmcnt(2)
	v_mfma_f32_16x16x32_bf16 v[126:129], v[192:195], v[154:157], v[126:129]
	v_mfma_f32_16x16x32_bf16 v[114:117], v[200:203], v[154:157], v[114:117]
	v_mfma_f32_16x16x32_bf16 v[86:89], v[208:211], v[154:157], v[86:89]
	v_mfma_f32_16x16x32_bf16 v[54:57], v[216:219], v[154:157], v[54:57]
	v_readfirstlane_b32 s32, v145
	s_lshl_b32 m0, s32, 3
	v_mov_b32_e32 v226, v224
	global_load_lds_dwordx4 v226, s[18:19]
	v_mfma_f32_16x16x32_bf16 v[126:129], v[196:199], v[158:161], v[126:129]
	v_mfma_f32_16x16x32_bf16 v[114:117], v[204:207], v[158:161], v[114:117]
	v_mfma_f32_16x16x32_bf16 v[86:89], v[212:215], v[158:161], v[86:89]
	v_mfma_f32_16x16x32_bf16 v[54:57], v[220:223], v[158:161], v[54:57]
	s_add_u32 m0, m0, 0x400
	v_add_u32_e32 v226, 0xac00, v224
	global_load_lds_dwordx4 v226, s[18:19]
	ds_read_b128 v[154:157], v229 offset:4096
	ds_read_b128 v[158:161], v230 offset:4096
	s_waitcnt lgkmcnt(2)
	v_mfma_f32_16x16x32_bf16 v[122:125], v[192:195], v[162:165], v[122:125]
	v_mfma_f32_16x16x32_bf16 v[102:105], v[200:203], v[162:165], v[102:105]
	v_mfma_f32_16x16x32_bf16 v[70:73], v[208:211], v[162:165], v[70:73]
	v_mfma_f32_16x16x32_bf16 v[38:41], v[216:219], v[162:165], v[38:41]
	s_add_u32 m0, m0, 0x400
	v_add_u32_e32 v226, 0x15800, v224
	global_load_lds_dwordx4 v226, s[18:19]
	v_mfma_f32_16x16x32_bf16 v[122:125], v[196:199], v[166:169], v[122:125]
	v_mfma_f32_16x16x32_bf16 v[102:105], v[204:207], v[166:169], v[102:105]
	v_mfma_f32_16x16x32_bf16 v[70:73], v[212:215], v[166:169], v[70:73]
	v_mfma_f32_16x16x32_bf16 v[38:41], v[220:223], v[166:169], v[38:41]
	s_add_u32 m0, m0, 0x400
	v_add_u32_e32 v226, 0x20400, v224
	global_load_lds_dwordx4 v226, s[18:19]
	ds_read_b128 v[162:165], v229 offset:6144
	ds_read_b128 v[166:169], v230 offset:6144
	s_waitcnt lgkmcnt(2)
	v_mfma_f32_16x16x32_bf16 v[118:121], v[192:195], v[154:157], v[118:121]
	v_mfma_f32_16x16x32_bf16 v[90:93], v[200:203], v[154:157], v[90:93]
	v_mfma_f32_16x16x32_bf16 v[58:61], v[208:211], v[154:157], v[58:61]
	v_mfma_f32_16x16x32_bf16 v[26:29], v[216:219], v[154:157], v[26:29]
	s_add_u32 m0, m0, 0x400
	v_add_u32_e32 v226, 0x2b000, v224
	global_load_lds_dwordx4 v226, s[18:19]
	v_mfma_f32_16x16x32_bf16 v[118:121], v[196:199], v[158:161], v[118:121]
	v_mfma_f32_16x16x32_bf16 v[90:93], v[204:207], v[158:161], v[90:93]
	v_mfma_f32_16x16x32_bf16 v[58:61], v[212:215], v[158:161], v[58:61]
	v_mfma_f32_16x16x32_bf16 v[26:29], v[220:223], v[158:161], v[26:29]
	s_add_u32 m0, m0, 0x400
	v_add_u32_e32 v226, 0x35c00, v224
	global_load_lds_dwordx4 v226, s[18:19]
	ds_read_b128 v[154:157], v229 offset:8192
	ds_read_b128 v[158:161], v230 offset:8192
	s_waitcnt lgkmcnt(2)
	v_mfma_f32_16x16x32_bf16 v[110:113], v[192:195], v[162:165], v[110:113]
	v_mfma_f32_16x16x32_bf16 v[78:81], v[200:203], v[162:165], v[78:81]
	v_mfma_f32_16x16x32_bf16 v[46:49], v[208:211], v[162:165], v[46:49]
	v_mfma_f32_16x16x32_bf16 v[18:21], v[216:219], v[162:165], v[18:21]
	s_add_u32 m0, m0, 0x400
	v_add_u32_e32 v226, 0x40800, v224
	global_load_lds_dwordx4 v226, s[18:19]
	v_mfma_f32_16x16x32_bf16 v[110:113], v[196:199], v[166:169], v[110:113]
	v_mfma_f32_16x16x32_bf16 v[78:81], v[204:207], v[166:169], v[78:81]
	v_mfma_f32_16x16x32_bf16 v[46:49], v[212:215], v[166:169], v[46:49]
	v_mfma_f32_16x16x32_bf16 v[18:21], v[220:223], v[166:169], v[18:21]
	s_add_u32 m0, m0, 0x400
	v_add_u32_e32 v226, 0x4b400, v224
	global_load_lds_dwordx4 v226, s[18:19]
	ds_read_b128 v[162:165], v229 offset:10240
	ds_read_b128 v[166:169], v230 offset:10240
	s_waitcnt lgkmcnt(2)
	v_mfma_f32_16x16x32_bf16 v[106:109], v[192:195], v[154:157], v[106:109]
	v_mfma_f32_16x16x32_bf16 v[74:77], v[200:203], v[154:157], v[74:77]
	v_mfma_f32_16x16x32_bf16 v[42:45], v[208:211], v[154:157], v[42:45]
	v_mfma_f32_16x16x32_bf16 v[14:17], v[216:219], v[154:157], v[14:17]
	s_add_u32 m0, s25, 43
	s_and_b32 m0, m0, 1
	s_lshl_b32 m0, m0, 14
	s_add_u32 m0, m0, 0x8000
	v_readfirstlane_b32 s32, v145
	s_lshl_b32 s32, s32, 2
	s_add_u32 m0, m0, s32
	v_mov_b32_e32 v226, v225
	global_load_lds_dwordx4 v226, s[16:17]
	v_mfma_f32_16x16x32_bf16 v[106:109], v[196:199], v[158:161], v[106:109]
	v_mfma_f32_16x16x32_bf16 v[74:77], v[204:207], v[158:161], v[74:77]
	v_mfma_f32_16x16x32_bf16 v[42:45], v[212:215], v[158:161], v[42:45]
	v_mfma_f32_16x16x32_bf16 v[14:17], v[220:223], v[158:161], v[14:17]
	s_add_u32 m0, m0, 0x400
	v_add_u32_e32 v226, 0xac00, v225
	global_load_lds_dwordx4 v226, s[16:17]
	ds_read_b128 v[154:157], v229 offset:12288
	ds_read_b128 v[158:161], v230 offset:12288
	s_waitcnt lgkmcnt(2)
	v_mfma_f32_16x16x32_bf16 v[98:101], v[192:195], v[162:165], v[98:101]
	v_mfma_f32_16x16x32_bf16 v[66:69], v[200:203], v[162:165], v[66:69]
	v_mfma_f32_16x16x32_bf16 v[34:37], v[208:211], v[162:165], v[34:37]
	v_mfma_f32_16x16x32_bf16 v[10:13], v[216:219], v[162:165], v[10:13]
	s_add_u32 m0, m0, 0x400
	v_add_u32_e32 v226, 0x15800, v225
	global_load_lds_dwordx4 v226, s[16:17]
	v_mfma_f32_16x16x32_bf16 v[98:101], v[196:199], v[166:169], v[98:101]
	v_mfma_f32_16x16x32_bf16 v[66:69], v[204:207], v[166:169], v[66:69]
	v_mfma_f32_16x16x32_bf16 v[34:37], v[212:215], v[166:169], v[34:37]
	v_mfma_f32_16x16x32_bf16 v[10:13], v[220:223], v[166:169], v[10:13]
	s_add_u32 m0, m0, 0x400
	v_add_u32_e32 v226, 0x20400, v225
	global_load_lds_dwordx4 v226, s[16:17]
	ds_read_b128 v[162:165], v229 offset:14336
	ds_read_b128 v[166:169], v230 offset:14336
	s_waitcnt lgkmcnt(2)
	v_mfma_f32_16x16x32_bf16 v[94:97], v[192:195], v[154:157], v[94:97]
	v_mfma_f32_16x16x32_bf16 v[62:65], v[200:203], v[154:157], v[62:65]
	v_mfma_f32_16x16x32_bf16 v[30:33], v[208:211], v[154:157], v[30:33]
	v_mfma_f32_16x16x32_bf16 v[6:9], v[216:219], v[154:157], v[6:9]
	v_mfma_f32_16x16x32_bf16 v[94:97], v[196:199], v[158:161], v[94:97]
	v_mfma_f32_16x16x32_bf16 v[62:65], v[204:207], v[158:161], v[62:65]
	v_mfma_f32_16x16x32_bf16 v[30:33], v[212:215], v[158:161], v[30:33]
	v_mfma_f32_16x16x32_bf16 v[6:9], v[220:223], v[158:161], v[6:9]
	s_waitcnt lgkmcnt(0)
	v_mfma_f32_16x16x32_bf16 v[82:85], v[192:195], v[162:165], v[82:85]
	v_mfma_f32_16x16x32_bf16 v[50:53], v[200:203], v[162:165], v[50:53]
	v_mfma_f32_16x16x32_bf16 v[22:25], v[208:211], v[162:165], v[22:25]
	v_mfma_f32_16x16x32_bf16 v[2:5], v[216:219], v[162:165], v[2:5]
	v_mfma_f32_16x16x32_bf16 v[82:85], v[196:199], v[166:169], v[82:85]
	v_mfma_f32_16x16x32_bf16 v[50:53], v[204:207], v[166:169], v[50:53]
	v_mfma_f32_16x16x32_bf16 v[22:25], v[212:215], v[166:169], v[22:25]
	v_mfma_f32_16x16x32_bf16 v[2:5], v[220:223], v[166:169], v[2:5]
	v_xor_b32_e32 v229, 0x4000, v229
	v_xor_b32_e32 v230, 0x4000, v230
	s_add_i32 s25, s25, 1
	s_cmp_lg_u32 s25, 41
	s_cbranch_scc1 .Lbk64_350
	s_waitcnt vmcnt(0)
	s_barrier
	ds_read_b128 v[192:195], v227
	ds_read_b128 v[196:199], v228
	ds_read_b128 v[200:203], v227 offset:2048
	ds_read_b128 v[204:207], v228 offset:2048
	ds_read_b128 v[208:211], v227 offset:4096
	ds_read_b128 v[212:215], v228 offset:4096
	ds_read_b128 v[216:219], v227 offset:6144
	ds_read_b128 v[220:223], v228 offset:6144
	s_waitcnt lgkmcnt(0)
	s_barrier
	ds_read_b128 v[154:157], v229 offset:0
	ds_read_b128 v[158:161], v230 offset:0
	ds_read_b128 v[162:165], v229 offset:2048
	ds_read_b128 v[166:169], v230 offset:2048
	s_waitcnt lgkmcnt(2)
	v_mfma_f32_16x16x32_bf16 v[126:129], v[192:195], v[154:157], v[126:129]
	v_mfma_f32_16x16x32_bf16 v[114:117], v[200:203], v[154:157], v[114:117]
	v_mfma_f32_16x16x32_bf16 v[86:89], v[208:211], v[154:157], v[86:89]
	v_mfma_f32_16x16x32_bf16 v[54:57], v[216:219], v[154:157], v[54:57]
	s_mov_b64 s[18:19], 0x1480
	v_readfirstlane_b32 s32, v145
	s_mov_b32 m0, s32
	v_lshl_add_u64 v[224:225], v[140:141], 0, s[18:19]
	global_load_lds_dwordx4 v[224:225], off
	v_mfma_f32_16x16x32_bf16 v[126:129], v[196:199], v[158:161], v[126:129]
	v_mfma_f32_16x16x32_bf16 v[114:117], v[204:207], v[158:161], v[114:117]
	v_mfma_f32_16x16x32_bf16 v[86:89], v[212:215], v[158:161], v[86:89]
	v_mfma_f32_16x16x32_bf16 v[54:57], v[220:223], v[158:161], v[54:57]
	s_add_u32 m0, m0, 0x1000
	v_lshl_add_u64 v[224:225], v[138:139], 0, s[18:19]
	global_load_lds_dwordx4 v[224:225], off
	ds_read_b128 v[154:157], v229 offset:4096
	ds_read_b128 v[158:161], v230 offset:4096
	s_waitcnt lgkmcnt(2)
	v_mfma_f32_16x16x32_bf16 v[122:125], v[192:195], v[162:165], v[122:125]
	v_mfma_f32_16x16x32_bf16 v[102:105], v[200:203], v[162:165], v[102:105]
	v_mfma_f32_16x16x32_bf16 v[70:73], v[208:211], v[162:165], v[70:73]
	v_mfma_f32_16x16x32_bf16 v[38:41], v[216:219], v[162:165], v[38:41]
	s_add_u32 m0, m0, 0x1000
	v_lshl_add_u64 v[224:225], v[136:137], 0, s[18:19]
	global_load_lds_dwordx4 v[224:225], off
	v_mfma_f32_16x16x32_bf16 v[122:125], v[196:199], v[166:169], v[122:125]
	v_mfma_f32_16x16x32_bf16 v[102:105], v[204:207], v[166:169], v[102:105]
	v_mfma_f32_16x16x32_bf16 v[70:73], v[212:215], v[166:169], v[70:73]
	v_mfma_f32_16x16x32_bf16 v[38:41], v[220:223], v[166:169], v[38:41]
	s_add_u32 m0, m0, 0x1000
	v_lshl_add_u64 v[224:225], v[134:135], 0, s[18:19]
	global_load_lds_dwordx4 v[224:225], off
	ds_read_b128 v[162:165], v229 offset:6144
	ds_read_b128 v[166:169], v230 offset:6144
	s_waitcnt lgkmcnt(2)
	v_mfma_f32_16x16x32_bf16 v[118:121], v[192:195], v[154:157], v[118:121]
	v_mfma_f32_16x16x32_bf16 v[90:93], v[200:203], v[154:157], v[90:93]
	v_mfma_f32_16x16x32_bf16 v[58:61], v[208:211], v[154:157], v[58:61]
	v_mfma_f32_16x16x32_bf16 v[26:29], v[216:219], v[154:157], v[26:29]
	s_add_u32 m0, m0, 0x1000
	v_lshl_add_u64 v[224:225], v[132:133], 0, s[18:19]
	global_load_lds_dwordx4 v[224:225], off
	v_mfma_f32_16x16x32_bf16 v[118:121], v[196:199], v[158:161], v[118:121]
	v_mfma_f32_16x16x32_bf16 v[90:93], v[204:207], v[158:161], v[90:93]
	v_mfma_f32_16x16x32_bf16 v[58:61], v[212:215], v[158:161], v[58:61]
	v_mfma_f32_16x16x32_bf16 v[26:29], v[220:223], v[158:161], v[26:29]
	s_add_u32 m0, m0, 0x1000
	v_lshl_add_u64 v[224:225], v[130:131], 0, s[18:19]
	global_load_lds_dwordx4 v[224:225], off
	ds_read_b128 v[154:157], v229 offset:8192
	ds_read_b128 v[158:161], v230 offset:8192
	s_waitcnt lgkmcnt(2)
	v_mfma_f32_16x16x32_bf16 v[110:113], v[192:195], v[162:165], v[110:113]
	v_mfma_f32_16x16x32_bf16 v[78:81], v[200:203], v[162:165], v[78:81]
	v_mfma_f32_16x16x32_bf16 v[46:49], v[208:211], v[162:165], v[46:49]
	v_mfma_f32_16x16x32_bf16 v[18:21], v[216:219], v[162:165], v[18:21]
	s_mov_b64 s[18:19], 0x14c0
	v_readfirstlane_b32 s32, v145
	s_add_u32 m0, s32, 0x6000
	v_lshl_add_u64 v[224:225], v[140:141], 0, s[18:19]
	global_load_lds_dwordx4 v[224:225], off
	v_mfma_f32_16x16x32_bf16 v[110:113], v[196:199], v[166:169], v[110:113]
	v_mfma_f32_16x16x32_bf16 v[78:81], v[204:207], v[166:169], v[78:81]
	v_mfma_f32_16x16x32_bf16 v[46:49], v[212:215], v[166:169], v[46:49]
	v_mfma_f32_16x16x32_bf16 v[18:21], v[220:223], v[166:169], v[18:21]
	s_add_u32 m0, m0, 0x1000
	v_lshl_add_u64 v[224:225], v[138:139], 0, s[18:19]
	global_load_lds_dwordx4 v[224:225], off
	ds_read_b128 v[162:165], v229 offset:10240
	ds_read_b128 v[166:169], v230 offset:10240
	s_waitcnt lgkmcnt(2)
	v_mfma_f32_16x16x32_bf16 v[106:109], v[192:195], v[154:157], v[106:109]
	v_mfma_f32_16x16x32_bf16 v[74:77], v[200:203], v[154:157], v[74:77]
	v_mfma_f32_16x16x32_bf16 v[42:45], v[208:211], v[154:157], v[42:45]
	v_mfma_f32_16x16x32_bf16 v[14:17], v[216:219], v[154:157], v[14:17]
	s_add_u32 m0, m0, 0x1000
	v_lshl_add_u64 v[224:225], v[136:137], 0, s[18:19]
	global_load_lds_dwordx4 v[224:225], off
	v_mfma_f32_16x16x32_bf16 v[106:109], v[196:199], v[158:161], v[106:109]
	v_mfma_f32_16x16x32_bf16 v[74:77], v[204:207], v[158:161], v[74:77]
	v_mfma_f32_16x16x32_bf16 v[42:45], v[212:215], v[158:161], v[42:45]
	v_mfma_f32_16x16x32_bf16 v[14:17], v[220:223], v[158:161], v[14:17]
	s_add_u32 m0, m0, 0x1000
	v_lshl_add_u64 v[224:225], v[134:135], 0, s[18:19]
	global_load_lds_dwordx4 v[224:225], off
	ds_read_b128 v[154:157], v229 offset:12288
	ds_read_b128 v[158:161], v230 offset:12288
	s_waitcnt lgkmcnt(2)
	v_mfma_f32_16x16x32_bf16 v[98:101], v[192:195], v[162:165], v[98:101]
	v_mfma_f32_16x16x32_bf16 v[66:69], v[200:203], v[162:165], v[66:69]
	v_mfma_f32_16x16x32_bf16 v[34:37], v[208:211], v[162:165], v[34:37]
	v_mfma_f32_16x16x32_bf16 v[10:13], v[216:219], v[162:165], v[10:13]
	s_add_u32 m0, m0, 0x1000
	v_lshl_add_u64 v[224:225], v[132:133], 0, s[18:19]
	global_load_lds_dwordx4 v[224:225], off
	v_mfma_f32_16x16x32_bf16 v[98:101], v[196:199], v[166:169], v[98:101]
	v_mfma_f32_16x16x32_bf16 v[66:69], v[204:207], v[166:169], v[66:69]
	v_mfma_f32_16x16x32_bf16 v[34:37], v[212:215], v[166:169], v[34:37]
	v_mfma_f32_16x16x32_bf16 v[10:13], v[220:223], v[166:169], v[10:13]
	s_add_u32 m0, m0, 0x1000
	v_lshl_add_u64 v[224:225], v[130:131], 0, s[18:19]
	global_load_lds_dwordx4 v[224:225], off
	ds_read_b128 v[162:165], v229 offset:14336
	ds_read_b128 v[166:169], v230 offset:14336
	s_waitcnt lgkmcnt(2)
	v_mfma_f32_16x16x32_bf16 v[94:97], v[192:195], v[154:157], v[94:97]
	v_mfma_f32_16x16x32_bf16 v[62:65], v[200:203], v[154:157], v[62:65]
	v_mfma_f32_16x16x32_bf16 v[30:33], v[208:211], v[154:157], v[30:33]
	v_mfma_f32_16x16x32_bf16 v[6:9], v[216:219], v[154:157], v[6:9]
	v_mfma_f32_16x16x32_bf16 v[94:97], v[196:199], v[158:161], v[94:97]
	v_mfma_f32_16x16x32_bf16 v[62:65], v[204:207], v[158:161], v[62:65]
	v_mfma_f32_16x16x32_bf16 v[30:33], v[212:215], v[158:161], v[30:33]
	v_mfma_f32_16x16x32_bf16 v[6:9], v[220:223], v[158:161], v[6:9]
	s_waitcnt lgkmcnt(0)
	v_mfma_f32_16x16x32_bf16 v[82:85], v[192:195], v[162:165], v[82:85]
	v_mfma_f32_16x16x32_bf16 v[50:53], v[200:203], v[162:165], v[50:53]
	v_mfma_f32_16x16x32_bf16 v[22:25], v[208:211], v[162:165], v[22:25]
	v_mfma_f32_16x16x32_bf16 v[2:5], v[216:219], v[162:165], v[2:5]
	v_mfma_f32_16x16x32_bf16 v[82:85], v[196:199], v[166:169], v[82:85]
	v_mfma_f32_16x16x32_bf16 v[50:53], v[204:207], v[166:169], v[50:53]
	v_mfma_f32_16x16x32_bf16 v[22:25], v[212:215], v[166:169], v[22:25]
	v_mfma_f32_16x16x32_bf16 v[2:5], v[220:223], v[166:169], v[2:5]
	s_waitcnt vmcnt(6)
	s_barrier
	v_add_u32_e32 v145, v149, v147
	ds_read_b128 v[130:133], v145
	ds_read_b128 v[134:137], v145 offset:1024
	ds_read_b128 v[138:141], v145 offset:2048
	ds_read_b128 v[154:157], v145 offset:3072
	ds_read_b128 v[158:161], v144 offset:16384
	ds_read_b128 v[162:165], v144 offset:17408
	ds_read_b128 v[166:169], v144 offset:18432
	ds_read_b128 v[180:183], v144 offset:19456
	ds_read_b128 v[192:195], v144 offset:20480
	ds_read_b128 v[196:199], v144 offset:21504
	ds_read_b128 v[200:203], v144 offset:22528
	ds_read_b128 v[204:207], v144 offset:23552
	s_waitcnt vmcnt(0)
	s_barrier
	s_waitcnt lgkmcnt(0)
	v_mfma_f32_16x16x32_bf16 v[126:129], v[130:133], v[158:161], v[126:129]
	s_lshl_b32 s16, s5, 7
	s_ashr_i32 s17, s16, 31
	s_lshl_b64 s[16:17], s[16:17], 1
	v_mfma_f32_16x16x32_bf16 v[114:117], v[134:137], v[158:161], v[114:117]
	v_and_b32_e32 v1, 0xfffffc0, v1
	v_lshl_or_b32 v1, v143, 2, v1
	v_mul_lo_u32 v1, v1, s33
	v_mfma_f32_16x16x32_bf16 v[86:89], v[138:141], v[158:161], v[86:89]
	v_lshl_or_b32 v1, v142, 2, v1
	s_lshl_b32 s18, s5, 1
	s_ashr_i32 s19, s18, 31
	v_mfma_f32_16x16x32_bf16 v[54:57], v[154:157], v[158:161], v[54:57]
	s_lshl_b64 s[18:19], s[18:19], 2
	s_add_i32 s24, s24, 1
	v_mfma_f32_16x16x32_bf16 v[122:125], v[130:133], v[162:165], v[122:125]
	v_mfma_f32_16x16x32_bf16 v[102:105], v[134:137], v[162:165], v[102:105]
	v_mfma_f32_16x16x32_bf16 v[70:73], v[138:141], v[162:165], v[70:73]
	v_mfma_f32_16x16x32_bf16 v[38:41], v[154:157], v[162:165], v[38:41]
	v_mfma_f32_16x16x32_bf16 v[118:121], v[130:133], v[166:169], v[118:121]
	v_mfma_f32_16x16x32_bf16 v[90:93], v[134:137], v[166:169], v[90:93]
	v_mfma_f32_16x16x32_bf16 v[58:61], v[138:141], v[166:169], v[58:61]
	v_mfma_f32_16x16x32_bf16 v[26:29], v[154:157], v[166:169], v[26:29]
	v_mfma_f32_16x16x32_bf16 v[110:113], v[130:133], v[180:183], v[110:113]
	v_mfma_f32_16x16x32_bf16 v[78:81], v[134:137], v[180:183], v[78:81]
	v_mfma_f32_16x16x32_bf16 v[46:49], v[138:141], v[180:183], v[46:49]
	v_mfma_f32_16x16x32_bf16 v[18:21], v[154:157], v[180:183], v[18:21]
	v_mfma_f32_16x16x32_bf16 v[106:109], v[130:133], v[192:195], v[106:109]
	v_mfma_f32_16x16x32_bf16 v[74:77], v[134:137], v[192:195], v[74:77]
	v_mfma_f32_16x16x32_bf16 v[42:45], v[138:141], v[192:195], v[42:45]
	v_mfma_f32_16x16x32_bf16 v[14:17], v[154:157], v[192:195], v[14:17]
	v_mfma_f32_16x16x32_bf16 v[98:101], v[130:133], v[196:199], v[98:101]
	v_mfma_f32_16x16x32_bf16 v[66:69], v[134:137], v[196:199], v[66:69]
	v_mfma_f32_16x16x32_bf16 v[34:37], v[138:141], v[196:199], v[34:37]
	v_mfma_f32_16x16x32_bf16 v[10:13], v[154:157], v[196:199], v[10:13]
	v_mfma_f32_16x16x32_bf16 v[94:97], v[130:133], v[200:203], v[94:97]
	v_mfma_f32_16x16x32_bf16 v[158:161], v[134:137], v[200:203], v[62:65]
	v_mfma_f32_16x16x32_bf16 v[162:165], v[138:141], v[200:203], v[30:33]
	v_mfma_f32_16x16x32_bf16 v[6:9], v[154:157], v[200:203], v[6:9]
	v_mfma_f32_16x16x32_bf16 v[82:85], v[130:133], v[204:207], v[82:85]
	v_mfma_f32_16x16x32_bf16 v[50:53], v[134:137], v[204:207], v[50:53]
	v_mfma_f32_16x16x32_bf16 v[130:133], v[138:141], v[204:207], v[22:25]
	v_mfma_f32_16x16x32_bf16 v[2:5], v[154:157], v[204:207], v[2:5]
	ds_read_b128 v[134:137], v145 offset:24576
	ds_read_b128 v[138:141], v145 offset:25600
	ds_read_b128 v[154:157], v145 offset:26624
	ds_read_b128 v[166:169], v145 offset:27648
	ds_read_b128 v[22:25], v144 offset:40960
	ds_read_b128 v[30:33], v144 offset:41984
	ds_read_b128 v[62:65], v144 offset:43008
	ds_read_b128 v[180:183], v144 offset:44032
	ds_read_b128 v[192:195], v144 offset:45056
	ds_read_b128 v[196:199], v144 offset:46080
	ds_read_b128 v[200:203], v144 offset:47104
	ds_read_b128 v[204:207], v144 offset:48128
	s_waitcnt lgkmcnt(0)
	v_mfma_f32_16x16x32_bf16 v[224:227], v[166:169], v[30:33], v[38:41]
	v_mfma_f32_16x16x32_bf16 v[38:41], v[154:157], v[196:199], v[34:37]
	v_mfma_f32_16x16x32_bf16 v[34:37], v[166:169], v[204:207], v[2:5]
	s_nop 2
	v_mov_b32_e32 v2, v170
	v_mfma_f32_16x16x32_bf16 v[208:211], v[138:141], v[22:25], v[114:117]
	v_add_u32_e32 v2, s4, v2
	v_ashrrev_i32_e32 v3, 31, v2
	v_lshlrev_b64 v[2:3], 11, v[2:3]
	v_lshl_add_u64 v[2:3], s[8:9], 0, v[2:3]
	v_lshl_add_u64 v[2:3], v[2:3], 0, s[16:17]
	v_mfma_f32_16x16x32_bf16 v[212:215], v[166:169], v[22:25], v[54:57]
	v_mfma_f32_16x16x32_bf16 v[216:219], v[134:137], v[30:33], v[122:125]
	v_mfma_f32_16x16x32_bf16 v[220:223], v[138:141], v[30:33], v[102:105]
	v_mfma_f32_16x16x32_bf16 v[228:231], v[134:137], v[62:65], v[118:121]
	v_mfma_f32_16x16x32_bf16 v[90:93], v[138:141], v[62:65], v[90:93]
	v_mfma_f32_16x16x32_bf16 v[232:235], v[154:157], v[62:65], v[58:61]
	v_mfma_f32_16x16x32_bf16 v[236:239], v[166:169], v[62:65], v[26:29]
	v_mfma_f32_16x16x32_bf16 v[240:243], v[134:137], v[180:183], v[110:113]
	v_mfma_f32_16x16x32_bf16 v[244:247], v[138:141], v[180:183], v[78:81]
	v_mfma_f32_16x16x32_bf16 v[248:251], v[154:157], v[180:183], v[46:49]
	v_mfma_f32_16x16x32_bf16 v[62:65], v[134:137], v[192:195], v[106:109]
	v_mfma_f32_16x16x32_bf16 v[46:49], v[138:141], v[192:195], v[74:77]
	v_mfma_f32_16x16x32_bf16 v[74:77], v[134:137], v[196:199], v[98:101]
	v_mfma_f32_16x16x32_bf16 v[54:57], v[138:141], v[196:199], v[66:69]
	v_mfma_f32_16x16x32_bf16 v[58:61], v[138:141], v[200:203], v[158:161]
	v_mfma_f32_16x16x32_bf16 v[66:69], v[138:141], v[204:207], v[50:53]
	flat_load_dwordx4 v[138:141], v[2:3]
	flat_load_dwordx4 v[122:125], v[2:3] offset:16
	flat_load_dwordx4 v[118:121], v[2:3] offset:32
	flat_load_dwordx4 v[114:117], v[2:3] offset:48
	flat_load_dwordx4 v[110:113], v[2:3] offset:64
	flat_load_dwordx4 v[106:109], v[2:3] offset:80
	flat_load_dwordx4 v[102:105], v[2:3] offset:96
	flat_load_dwordx4 v[98:101], v[2:3] offset:112
	s_waitcnt vmcnt(0) lgkmcnt(0)
	s_barrier
	v_mfma_f32_16x16x32_bf16 v[126:129], v[134:137], v[22:25], v[126:129]
	s_nop 7
	ds_write2_b32 v1, v126, v216 offset1:16
	ds_write2_b32 v1, v127, v217 offset0:68 offset1:84
	ds_write2_b32 v1, v128, v218 offset0:136 offset1:152
	ds_write2_b32 v1, v129, v219 offset0:204 offset1:220
	ds_write2_b32 v1, v228, v240 offset0:32 offset1:48
	ds_write2_b32 v1, v229, v241 offset0:100 offset1:116
	ds_write2_b32 v1, v230, v242 offset0:168 offset1:184
	ds_write2_b32 v1, v231, v243 offset0:236 offset1:252
	v_mfma_f32_16x16x32_bf16 v[86:89], v[154:157], v[22:25], v[86:89]
	v_mfma_f32_16x16x32_bf16 v[70:73], v[154:157], v[30:33], v[70:73]
	v_mfma_f32_16x16x32_bf16 v[180:183], v[166:169], v[180:183], v[18:21]
	v_mfma_f32_16x16x32_bf16 v[78:81], v[134:137], v[200:203], v[94:97]
	v_mfma_f32_16x16x32_bf16 v[82:85], v[134:137], v[204:207], v[82:85]
	v_add_u32_e32 v135, 0x3000, v1
	v_add_u32_e32 v134, 0x3400, v1
	v_mov_b32_e32 v136, v170
	v_mfma_f32_16x16x32_bf16 v[50:53], v[154:157], v[204:207], v[130:133]
	v_lshlrev_b32_e32 v137, 16, v138
	s_nop 1
	v_add_u32_e32 v130, 0x1000, v1
	v_add_u32_e32 v131, 0x1400, v1
	v_add_u32_e32 v132, 0x2000, v1
	v_add_u32_e32 v133, 0x2400, v1
	ds_write2_b32 v130, v208, v220 offset0:64 offset1:80
	ds_write2_b32 v130, v209, v221 offset0:132 offset1:148
	ds_write2_b32 v130, v210, v222 offset0:200 offset1:216
	ds_write2_b32 v131, v211, v223 offset0:12 offset1:28
	ds_write2_b32 v130, v90, v244 offset0:96 offset1:112
	ds_write2_b32 v130, v91, v245 offset0:164 offset1:180
	ds_write2_b32 v130, v92, v246 offset0:232 offset1:248
	ds_write2_b32 v131, v93, v247 offset0:44 offset1:60
	ds_write2_b32 v132, v86, v70 offset0:128 offset1:144
	ds_write2_b32 v132, v87, v71 offset0:196 offset1:212
	ds_write2_b32 v133, v88, v72 offset0:8 offset1:24
	ds_write2_b32 v133, v89, v73 offset0:76 offset1:92
	ds_write2_b32 v132, v232, v248 offset0:160 offset1:176
	ds_write2_b32 v132, v233, v249 offset0:228 offset1:244
	ds_write2_b32 v133, v234, v250 offset0:40 offset1:56
	ds_write2_b32 v133, v235, v251 offset0:108 offset1:124
	ds_write2_b32 v135, v212, v224 offset0:192 offset1:208
	ds_write2_b32 v134, v213, v225 offset0:4 offset1:20
	ds_write2_b32 v134, v214, v226 offset0:72 offset1:88
	ds_write2_b32 v134, v215, v227 offset0:140 offset1:156
	ds_write2_b32 v135, v236, v180 offset0:224 offset1:240
	ds_write2_b32 v134, v237, v181 offset0:36 offset1:52
	ds_write2_b32 v134, v238, v182 offset0:104 offset1:120
	ds_write2_b32 v134, v239, v183 offset0:172 offset1:188
	s_waitcnt lgkmcnt(0)
	s_barrier
	v_mfma_f32_16x16x32_bf16 v[30:33], v[154:157], v[192:195], v[42:45]
	v_add_u32_e32 v126, s4, v136
	v_ashrrev_i32_e32 v127, 31, v126
	v_lshlrev_b64 v[2:3], 11, v[126:127]
	v_lshl_add_u64 v[2:3], s[8:9], 0, v[2:3]
	v_lshl_add_u64 v[128:129], v[2:3], 0, s[16:17]
	v_mul_lo_u32 v136, v136, s33
	v_mfma_f32_16x16x32_bf16 v[18:21], v[166:169], v[192:195], v[14:17]
	v_and_b32_e32 v138, 0xffff0000, v138
	v_mfma_f32_16x16x32_bf16 v[22:25], v[166:169], v[196:199], v[10:13]
	v_mfma_f32_16x16x32_bf16 v[42:45], v[154:157], v[200:203], v[162:165]
	v_mfma_f32_16x16x32_bf16 v[26:29], v[166:169], v[200:203], v[6:9]
	flat_load_dwordx4 v[94:97], v[128:129] offset:128
	flat_load_dwordx4 v[90:93], v[128:129] offset:144
	flat_load_dwordx4 v[86:89], v[128:129] offset:160
	flat_load_dwordx4 v[70:73], v[128:129] offset:176
	flat_load_dwordx4 v[14:17], v[128:129] offset:192
	flat_load_dwordx4 v[10:13], v[128:129] offset:208
	flat_load_dwordx4 v[6:9], v[128:129] offset:224
	flat_load_dwordx4 v[2:5], v[128:129] offset:240
	ds_read_b128 v[142:145], v136
	ds_read_b128 v[154:157], v136 offset:16
	s_waitcnt lgkmcnt(0)
	v_add_f32_e32 v137, v142, v137
	v_add_f32_e32 v138, v143, v138
	v_cvt_pk_bf16_f32 v138, v137, v138
	v_lshlrev_b32_e32 v137, 16, v139
	v_and_b32_e32 v139, 0xffff0000, v139
	v_add_f32_e32 v137, v144, v137
	v_add_f32_e32 v139, v145, v139
	v_cvt_pk_bf16_f32 v139, v137, v139
	v_lshlrev_b32_e32 v137, 16, v140
	v_and_b32_e32 v140, 0xffff0000, v140
	v_add_f32_e32 v137, v154, v137
	v_add_f32_e32 v140, v155, v140
	v_cvt_pk_bf16_f32 v140, v137, v140
	v_lshlrev_b32_e32 v137, 16, v141
	v_and_b32_e32 v141, 0xffff0000, v141
	v_add_f32_e32 v137, v156, v137
	v_add_f32_e32 v141, v157, v141
	v_and_b32_e32 v142, 0xffff0000, v138
	v_cvt_pk_bf16_f32 v141, v137, v141
	v_lshlrev_b32_e32 v137, 16, v138
	v_mul_f32_e32 v153, v142, v142
	v_lshlrev_b32_e32 v143, 16, v139
	v_fmac_f32_e32 v153, v137, v137
	v_and_b32_e32 v144, 0xffff0000, v139
	v_fmac_f32_e32 v153, v143, v143
	v_lshlrev_b32_e32 v145, 16, v140
	v_fmac_f32_e32 v153, v144, v144
	flat_store_dwordx4 v[128:129], v[138:141]
	v_and_b32_e32 v147, 0xffff0000, v140
	v_lshlrev_b32_e32 v149, 16, v141
	v_and_b32_e32 v151, 0xffff0000, v141
	v_fmac_f32_e32 v153, v145, v145
	ds_read_b128 v[138:141], v136 offset:32
	ds_read_b128 v[142:145], v136 offset:48
	v_lshlrev_b32_e32 v137, 16, v122
	v_and_b32_e32 v122, 0xffff0000, v122
	v_fmac_f32_e32 v153, v147, v147
	s_waitcnt lgkmcnt(0)
	v_add_f32_e32 v137, v138, v137
	v_add_f32_e32 v122, v139, v122
	v_cvt_pk_bf16_f32 v122, v137, v122
	v_lshlrev_b32_e32 v137, 16, v123
	v_and_b32_e32 v123, 0xffff0000, v123
	v_add_f32_e32 v137, v140, v137
	v_add_f32_e32 v123, v141, v123
	v_cvt_pk_bf16_f32 v123, v137, v123
	v_lshlrev_b32_e32 v137, 16, v124
	v_and_b32_e32 v124, 0xffff0000, v124
	v_add_f32_e32 v137, v142, v137
	v_add_f32_e32 v124, v143, v124
	v_cvt_pk_bf16_f32 v124, v137, v124
	v_lshlrev_b32_e32 v137, 16, v125
	v_and_b32_e32 v125, 0xffff0000, v125
	v_add_f32_e32 v137, v144, v137
	v_add_f32_e32 v125, v145, v125
	v_and_b32_e32 v138, 0xffff0000, v122
	v_cvt_pk_bf16_f32 v125, v137, v125
	v_lshlrev_b32_e32 v137, 16, v122
	v_mul_f32_e32 v138, v138, v138
	v_lshlrev_b32_e32 v139, 16, v123
	v_fmac_f32_e32 v138, v137, v137
	v_and_b32_e32 v140, 0xffff0000, v123
	v_fmac_f32_e32 v138, v139, v139
	v_lshlrev_b32_e32 v141, 16, v124
	v_fmac_f32_e32 v138, v140, v140
	v_and_b32_e32 v142, 0xffff0000, v124
	v_fmac_f32_e32 v138, v141, v141
	v_lshlrev_b32_e32 v143, 16, v125
	v_fmac_f32_e32 v138, v142, v142
	v_fmac_f32_e32 v153, v149, v149
	v_and_b32_e32 v144, 0xffff0000, v125
	v_fmac_f32_e32 v138, v143, v143
	v_fmac_f32_e32 v153, v151, v151
	v_fmac_f32_e32 v138, v144, v144
	flat_store_dwordx4 v[128:129], v[122:125] offset:16
	v_add_f32_e32 v137, v153, v138
	ds_read_b128 v[122:125], v136 offset:64
	ds_read_b128 v[138:141], v136 offset:80
	v_lshlrev_b32_e32 v142, 16, v118
	v_and_b32_e32 v118, 0xffff0000, v118
	s_waitcnt lgkmcnt(0)
	v_add_f32_e32 v122, v122, v142
	v_add_f32_e32 v118, v123, v118
	v_cvt_pk_bf16_f32 v118, v122, v118
	v_lshlrev_b32_e32 v122, 16, v119
	v_and_b32_e32 v119, 0xffff0000, v119
	v_add_f32_e32 v122, v124, v122
	v_add_f32_e32 v119, v125, v119
	v_cvt_pk_bf16_f32 v119, v122, v119
	v_lshlrev_b32_e32 v122, 16, v120
	v_and_b32_e32 v120, 0xffff0000, v120
	v_add_f32_e32 v122, v138, v122
	v_add_f32_e32 v120, v139, v120
	v_cvt_pk_bf16_f32 v120, v122, v120
	v_lshlrev_b32_e32 v122, 16, v121
	v_and_b32_e32 v121, 0xffff0000, v121
	v_add_f32_e32 v122, v140, v122
	v_add_f32_e32 v121, v141, v121
	v_and_b32_e32 v123, 0xffff0000, v118
	v_cvt_pk_bf16_f32 v121, v122, v121
	v_lshlrev_b32_e32 v122, 16, v118
	v_mul_f32_e32 v123, v123, v123
	v_lshlrev_b32_e32 v124, 16, v119
	v_fmac_f32_e32 v123, v122, v122
	v_and_b32_e32 v125, 0xffff0000, v119
	v_fmac_f32_e32 v123, v124, v124
	v_lshlrev_b32_e32 v138, 16, v120
	v_fmac_f32_e32 v123, v125, v125
	v_and_b32_e32 v139, 0xffff0000, v120
	v_fmac_f32_e32 v123, v138, v138
	v_lshlrev_b32_e32 v140, 16, v121
	v_fmac_f32_e32 v123, v139, v139
	v_and_b32_e32 v141, 0xffff0000, v121
	v_fmac_f32_e32 v123, v140, v140
	v_fmac_f32_e32 v123, v141, v141
	flat_store_dwordx4 v[128:129], v[118:121] offset:32
	v_add_f32_e32 v137, v137, v123
	ds_read_b128 v[118:121], v136 offset:96
	ds_read_b128 v[122:125], v136 offset:112
	v_lshlrev_b32_e32 v138, 16, v114
	v_and_b32_e32 v114, 0xffff0000, v114
	s_waitcnt lgkmcnt(0)
	v_add_f32_e32 v118, v118, v138
	v_add_f32_e32 v114, v119, v114
	v_cvt_pk_bf16_f32 v114, v118, v114
	v_lshlrev_b32_e32 v118, 16, v115
	v_and_b32_e32 v115, 0xffff0000, v115
	v_add_f32_e32 v118, v120, v118
	v_add_f32_e32 v115, v121, v115
	v_cvt_pk_bf16_f32 v115, v118, v115
	v_lshlrev_b32_e32 v118, 16, v116
	v_and_b32_e32 v116, 0xffff0000, v116
	v_add_f32_e32 v118, v122, v118
	v_add_f32_e32 v116, v123, v116
	v_cvt_pk_bf16_f32 v116, v118, v116
	v_lshlrev_b32_e32 v118, 16, v117
	v_and_b32_e32 v117, 0xffff0000, v117
	v_add_f32_e32 v118, v124, v118
	v_add_f32_e32 v117, v125, v117
	v_and_b32_e32 v119, 0xffff0000, v114
	v_cvt_pk_bf16_f32 v117, v118, v117
	v_lshlrev_b32_e32 v118, 16, v114
	v_mul_f32_e32 v119, v119, v119
	v_lshlrev_b32_e32 v120, 16, v115
	v_fmac_f32_e32 v119, v118, v118
	v_and_b32_e32 v121, 0xffff0000, v115
	v_fmac_f32_e32 v119, v120, v120
	v_lshlrev_b32_e32 v122, 16, v116
	v_fmac_f32_e32 v119, v121, v121
	v_and_b32_e32 v123, 0xffff0000, v116
	v_fmac_f32_e32 v119, v122, v122
	v_lshlrev_b32_e32 v124, 16, v117
	v_fmac_f32_e32 v119, v123, v123
	v_and_b32_e32 v125, 0xffff0000, v117
	v_fmac_f32_e32 v119, v124, v124
	v_fmac_f32_e32 v119, v125, v125
	flat_store_dwordx4 v[128:129], v[114:117] offset:48
	v_add_f32_e32 v122, v137, v119
	ds_read_b128 v[114:117], v136 offset:128
	ds_read_b128 v[118:121], v136 offset:144
	v_lshlrev_b32_e32 v123, 16, v110
	v_and_b32_e32 v110, 0xffff0000, v110
	s_waitcnt lgkmcnt(0)
	v_add_f32_e32 v114, v114, v123
	v_add_f32_e32 v110, v115, v110
	v_cvt_pk_bf16_f32 v110, v114, v110
	v_lshlrev_b32_e32 v114, 16, v111
	v_and_b32_e32 v111, 0xffff0000, v111
	v_add_f32_e32 v114, v116, v114
	v_add_f32_e32 v111, v117, v111
	v_cvt_pk_bf16_f32 v111, v114, v111
	v_lshlrev_b32_e32 v114, 16, v112
	v_and_b32_e32 v112, 0xffff0000, v112
	v_add_f32_e32 v114, v118, v114
	v_add_f32_e32 v112, v119, v112
	v_cvt_pk_bf16_f32 v112, v114, v112
	v_lshlrev_b32_e32 v114, 16, v113
	v_and_b32_e32 v113, 0xffff0000, v113
	v_add_f32_e32 v114, v120, v114
	v_add_f32_e32 v113, v121, v113
	v_and_b32_e32 v115, 0xffff0000, v110
	v_cvt_pk_bf16_f32 v113, v114, v113
	v_lshlrev_b32_e32 v114, 16, v110
	v_mul_f32_e32 v115, v115, v115
	v_lshlrev_b32_e32 v116, 16, v111
	v_fmac_f32_e32 v115, v114, v114
	v_and_b32_e32 v117, 0xffff0000, v111
	v_fmac_f32_e32 v115, v116, v116
	v_lshlrev_b32_e32 v118, 16, v112
	v_fmac_f32_e32 v115, v117, v117
	v_and_b32_e32 v119, 0xffff0000, v112
	v_fmac_f32_e32 v115, v118, v118
	v_lshlrev_b32_e32 v120, 16, v113
	v_fmac_f32_e32 v115, v119, v119
	v_and_b32_e32 v121, 0xffff0000, v113
	v_fmac_f32_e32 v115, v120, v120
	v_fmac_f32_e32 v115, v121, v121
	flat_store_dwordx4 v[128:129], v[110:113] offset:64
	v_add_f32_e32 v118, v122, v115
	ds_read_b128 v[110:113], v136 offset:160
	ds_read_b128 v[114:117], v136 offset:176
	v_lshlrev_b32_e32 v119, 16, v106
	v_and_b32_e32 v106, 0xffff0000, v106
	s_waitcnt lgkmcnt(0)
	v_add_f32_e32 v110, v110, v119
	v_add_f32_e32 v106, v111, v106
	v_cvt_pk_bf16_f32 v106, v110, v106
	v_lshlrev_b32_e32 v110, 16, v107
	v_and_b32_e32 v107, 0xffff0000, v107
	v_add_f32_e32 v110, v112, v110
	v_add_f32_e32 v107, v113, v107
	v_cvt_pk_bf16_f32 v107, v110, v107
	v_lshlrev_b32_e32 v110, 16, v108
	v_and_b32_e32 v108, 0xffff0000, v108
	v_add_f32_e32 v110, v114, v110
	v_add_f32_e32 v108, v115, v108
	v_cvt_pk_bf16_f32 v108, v110, v108
	v_lshlrev_b32_e32 v110, 16, v109
	v_and_b32_e32 v109, 0xffff0000, v109
	v_add_f32_e32 v110, v116, v110
	v_add_f32_e32 v109, v117, v109
	v_and_b32_e32 v111, 0xffff0000, v106
	v_cvt_pk_bf16_f32 v109, v110, v109
	v_lshlrev_b32_e32 v110, 16, v106
	v_mul_f32_e32 v111, v111, v111
	v_lshlrev_b32_e32 v112, 16, v107
	v_fmac_f32_e32 v111, v110, v110
	v_and_b32_e32 v113, 0xffff0000, v107
	v_fmac_f32_e32 v111, v112, v112
	v_lshlrev_b32_e32 v114, 16, v108
	v_fmac_f32_e32 v111, v113, v113
	v_and_b32_e32 v115, 0xffff0000, v108
	v_fmac_f32_e32 v111, v114, v114
	v_lshlrev_b32_e32 v116, 16, v109
	v_fmac_f32_e32 v111, v115, v115
	v_and_b32_e32 v117, 0xffff0000, v109
	v_fmac_f32_e32 v111, v116, v116
	v_fmac_f32_e32 v111, v117, v117
	flat_store_dwordx4 v[128:129], v[106:109] offset:80
	v_add_f32_e32 v114, v118, v111
	ds_read_b128 v[106:109], v136 offset:192
	ds_read_b128 v[110:113], v136 offset:208
	v_lshlrev_b32_e32 v115, 16, v102
	v_and_b32_e32 v102, 0xffff0000, v102
	s_waitcnt lgkmcnt(0)
	v_add_f32_e32 v106, v106, v115
	v_add_f32_e32 v102, v107, v102
	v_cvt_pk_bf16_f32 v102, v106, v102
	v_lshlrev_b32_e32 v106, 16, v103
	v_and_b32_e32 v103, 0xffff0000, v103
	v_add_f32_e32 v106, v108, v106
	v_add_f32_e32 v103, v109, v103
	v_cvt_pk_bf16_f32 v103, v106, v103
	v_lshlrev_b32_e32 v106, 16, v104
	v_and_b32_e32 v104, 0xffff0000, v104
	v_add_f32_e32 v106, v110, v106
	v_add_f32_e32 v104, v111, v104
	v_cvt_pk_bf16_f32 v104, v106, v104
	v_lshlrev_b32_e32 v106, 16, v105
	v_and_b32_e32 v105, 0xffff0000, v105
	v_add_f32_e32 v106, v112, v106
	v_add_f32_e32 v105, v113, v105
	v_and_b32_e32 v107, 0xffff0000, v102
	v_cvt_pk_bf16_f32 v105, v106, v105
	v_lshlrev_b32_e32 v106, 16, v102
	v_mul_f32_e32 v107, v107, v107
	v_lshlrev_b32_e32 v108, 16, v103
	v_fmac_f32_e32 v107, v106, v106
	v_and_b32_e32 v109, 0xffff0000, v103
	v_fmac_f32_e32 v107, v108, v108
	v_lshlrev_b32_e32 v110, 16, v104
	v_fmac_f32_e32 v107, v109, v109
	v_and_b32_e32 v111, 0xffff0000, v104
	v_fmac_f32_e32 v107, v110, v110
	v_lshlrev_b32_e32 v112, 16, v105
	v_fmac_f32_e32 v107, v111, v111
	v_and_b32_e32 v113, 0xffff0000, v105
	v_fmac_f32_e32 v107, v112, v112
	v_fmac_f32_e32 v107, v113, v113
	flat_store_dwordx4 v[128:129], v[102:105] offset:96
	v_add_f32_e32 v110, v114, v107
	ds_read_b128 v[102:105], v136 offset:224
	ds_read_b128 v[106:109], v136 offset:240
	v_lshlrev_b32_e32 v111, 16, v98
	v_and_b32_e32 v98, 0xffff0000, v98
	s_waitcnt lgkmcnt(0)
	v_add_f32_e32 v102, v102, v111
	v_add_f32_e32 v98, v103, v98
	v_cvt_pk_bf16_f32 v98, v102, v98
	v_lshlrev_b32_e32 v102, 16, v99
	v_and_b32_e32 v99, 0xffff0000, v99
	v_add_f32_e32 v102, v104, v102
	v_add_f32_e32 v99, v105, v99
	v_cvt_pk_bf16_f32 v99, v102, v99
	v_lshlrev_b32_e32 v102, 16, v100
	v_and_b32_e32 v100, 0xffff0000, v100
	v_add_f32_e32 v102, v106, v102
	v_add_f32_e32 v100, v107, v100
	v_cvt_pk_bf16_f32 v100, v102, v100
	v_lshlrev_b32_e32 v102, 16, v101
	v_and_b32_e32 v101, 0xffff0000, v101
	v_add_f32_e32 v102, v108, v102
	v_add_f32_e32 v101, v109, v101
	v_and_b32_e32 v103, 0xffff0000, v98
	v_cvt_pk_bf16_f32 v101, v102, v101
	v_lshlrev_b32_e32 v102, 16, v98
	v_mul_f32_e32 v103, v103, v103
	v_lshlrev_b32_e32 v104, 16, v99
	v_fmac_f32_e32 v103, v102, v102
	v_and_b32_e32 v105, 0xffff0000, v99
	v_fmac_f32_e32 v103, v104, v104
	v_lshlrev_b32_e32 v106, 16, v100
	v_fmac_f32_e32 v103, v105, v105
	v_and_b32_e32 v107, 0xffff0000, v100
	v_fmac_f32_e32 v103, v106, v106
	v_lshlrev_b32_e32 v108, 16, v101
	v_fmac_f32_e32 v103, v107, v107
	v_and_b32_e32 v109, 0xffff0000, v101
	v_fmac_f32_e32 v103, v108, v108
	flat_store_dwordx4 v[128:129], v[98:101] offset:112
	v_fmac_f32_e32 v103, v109, v109
	v_add_f32_e32 v102, v110, v103
	v_lshlrev_b64 v[98:99], 6, v[126:127]
	v_lshl_add_u64 v[98:99], s[6:7], 0, v[98:99]
	v_lshl_add_u64 v[98:99], v[98:99], 0, s[18:19]
	flat_store_dword v[98:99], v102
	s_waitcnt lgkmcnt(0)
	s_barrier
	ds_write2_b32 v1, v62, v74 offset1:16
	ds_write2_b32 v1, v63, v75 offset0:68 offset1:84
	ds_write2_b32 v1, v64, v76 offset0:136 offset1:152
	ds_write2_b32 v1, v65, v77 offset0:204 offset1:220
	ds_write2_b32 v1, v78, v82 offset0:32 offset1:48
	ds_write2_b32 v1, v79, v83 offset0:100 offset1:116
	ds_write2_b32 v1, v80, v84 offset0:168 offset1:184
	ds_write2_b32 v1, v81, v85 offset0:236 offset1:252
	ds_write2_b32 v130, v46, v54 offset0:64 offset1:80
	ds_write2_b32 v130, v47, v55 offset0:132 offset1:148
	ds_write2_b32 v130, v48, v56 offset0:200 offset1:216
	ds_write2_b32 v131, v49, v57 offset0:12 offset1:28
	ds_write2_b32 v130, v58, v66 offset0:96 offset1:112
	ds_write2_b32 v130, v59, v67 offset0:164 offset1:180
	ds_write2_b32 v130, v60, v68 offset0:232 offset1:248
	ds_write2_b32 v131, v61, v69 offset0:44 offset1:60
	ds_write2_b32 v132, v30, v38 offset0:128 offset1:144
	ds_write2_b32 v132, v31, v39 offset0:196 offset1:212
	ds_write2_b32 v133, v32, v40 offset0:8 offset1:24
	ds_write2_b32 v133, v33, v41 offset0:76 offset1:92
	ds_write2_b32 v132, v42, v50 offset0:160 offset1:176
	ds_write2_b32 v132, v43, v51 offset0:228 offset1:244
	ds_write2_b32 v133, v44, v52 offset0:40 offset1:56
	ds_write2_b32 v133, v45, v53 offset0:108 offset1:124
	ds_write2_b32 v135, v18, v22 offset0:192 offset1:208
	ds_write2_b32 v134, v19, v23 offset0:4 offset1:20
	ds_write2_b32 v134, v20, v24 offset0:72 offset1:88
	ds_write2_b32 v134, v21, v25 offset0:140 offset1:156
	ds_write2_b32 v135, v26, v34 offset0:224 offset1:240
	ds_write2_b32 v134, v27, v35 offset0:36 offset1:52
	ds_write2_b32 v134, v28, v36 offset0:104 offset1:120
	ds_write2_b32 v134, v29, v37 offset0:172 offset1:188
	v_mov_b32_e32 v1, v170
	s_waitcnt lgkmcnt(0)
	s_barrier
	s_waitcnt vmcnt(0)
	v_lshlrev_b32_e32 v28, 16, v94
	v_add_u32_e32 v18, s4, v1
	v_ashrrev_i32_e32 v19, 31, v18
	v_lshlrev_b64 v[20:21], 11, v[18:19]
	v_lshl_add_u64 v[20:21], s[38:39], 0, v[20:21]
	v_mul_lo_u32 v1, v1, s33
	v_lshl_add_u64 v[32:33], v[20:21], 0, s[16:17]
	ds_read_b128 v[20:23], v1
	ds_read_b128 v[24:27], v1 offset:16
	s_mov_b64 s[4:5], 0
	s_waitcnt lgkmcnt(1)
	v_add_f32_e32 v20, v20, v28
	v_and_b32_e32 v28, 0xffff0000, v94
	v_add_f32_e32 v21, v21, v28
	v_cvt_pk_bf16_f32 v28, v20, v21
	v_and_b32_e32 v21, 0xffff0000, v95
	v_lshlrev_b32_e32 v20, 16, v95
	v_add_f32_e32 v21, v23, v21
	v_add_f32_e32 v20, v22, v20
	v_cvt_pk_bf16_f32 v29, v20, v21
	v_and_b32_e32 v21, 0xffff0000, v96
	v_lshlrev_b32_e32 v20, 16, v96
	s_waitcnt lgkmcnt(0)
	v_add_f32_e32 v21, v25, v21
	v_add_f32_e32 v20, v24, v20
	v_cvt_pk_bf16_f32 v30, v20, v21
	v_and_b32_e32 v21, 0xffff0000, v97
	v_lshlrev_b32_e32 v20, 16, v97
	v_add_f32_e32 v21, v27, v21
	v_add_f32_e32 v20, v26, v20
	v_cvt_pk_bf16_f32 v31, v20, v21
	v_and_b32_e32 v21, 0xffff0000, v28
	v_lshlrev_b32_e32 v20, 16, v28
	v_mul_f32_e32 v34, v21, v21
	v_lshlrev_b32_e32 v22, 16, v29
	v_fmac_f32_e32 v34, v20, v20
	v_and_b32_e32 v23, 0xffff0000, v29
	v_fmac_f32_e32 v34, v22, v22
	v_lshlrev_b32_e32 v24, 16, v30
	v_fmac_f32_e32 v34, v23, v23
	v_and_b32_e32 v25, 0xffff0000, v30
	v_fmac_f32_e32 v34, v24, v24
	v_add_co_u32_e32 v20, vcc, s90, v32
	v_lshlrev_b32_e32 v26, 16, v31
	v_fmac_f32_e32 v34, v25, v25
	v_addc_co_u32_e32 v21, vcc, 0, v33, vcc
	v_and_b32_e32 v27, 0xffff0000, v31
	v_fmac_f32_e32 v34, v26, v26
	flat_store_dwordx4 v[20:21], v[28:31] offset:128
	v_fmac_f32_e32 v34, v27, v27
	ds_read_b128 v[22:25], v1 offset:32
	ds_read_b128 v[26:29], v1 offset:48
	v_lshlrev_b32_e32 v30, 16, v90
	s_waitcnt lgkmcnt(0)
	v_add_f32_e32 v22, v22, v30
	v_and_b32_e32 v30, 0xffff0000, v90
	v_add_f32_e32 v23, v23, v30
	v_cvt_pk_bf16_f32 v22, v22, v23
	v_lshlrev_b32_e32 v23, 16, v91
	v_add_f32_e32 v23, v24, v23
	v_and_b32_e32 v24, 0xffff0000, v91
	v_add_f32_e32 v24, v25, v24
	v_cvt_pk_bf16_f32 v23, v23, v24
	v_lshlrev_b32_e32 v24, 16, v92
	v_and_b32_e32 v25, 0xffff0000, v92
	v_add_f32_e32 v24, v26, v24
	v_add_f32_e32 v25, v27, v25
	v_cvt_pk_bf16_f32 v24, v24, v25
	v_lshlrev_b32_e32 v25, 16, v93
	v_and_b32_e32 v26, 0xffff0000, v93
	v_add_f32_e32 v25, v28, v25
	v_add_f32_e32 v26, v29, v26
	v_and_b32_e32 v27, 0xffff0000, v22
	v_cvt_pk_bf16_f32 v25, v25, v26
	v_lshlrev_b32_e32 v26, 16, v22
	v_mul_f32_e32 v27, v27, v27
	v_lshlrev_b32_e32 v28, 16, v23
	v_fmac_f32_e32 v27, v26, v26
	v_and_b32_e32 v29, 0xffff0000, v23
	v_fmac_f32_e32 v27, v28, v28
	v_lshlrev_b32_e32 v30, 16, v24
	v_fmac_f32_e32 v27, v29, v29
	v_and_b32_e32 v31, 0xffff0000, v24
	v_fmac_f32_e32 v27, v30, v30
	v_lshlrev_b32_e32 v32, 16, v25
	v_fmac_f32_e32 v27, v31, v31
	v_and_b32_e32 v33, 0xffff0000, v25
	v_fmac_f32_e32 v27, v32, v32
	v_fmac_f32_e32 v27, v33, v33
	flat_store_dwordx4 v[20:21], v[22:25] offset:144
	v_add_f32_e32 v30, v34, v27
	ds_read_b128 v[22:25], v1 offset:64
	ds_read_b128 v[26:29], v1 offset:80
	v_lshlrev_b32_e32 v31, 16, v86
	s_waitcnt lgkmcnt(0)
	v_add_f32_e32 v22, v22, v31
	v_and_b32_e32 v31, 0xffff0000, v86
	v_add_f32_e32 v23, v23, v31
	v_cvt_pk_bf16_f32 v22, v22, v23
	v_lshlrev_b32_e32 v23, 16, v87
	v_add_f32_e32 v23, v24, v23
	v_and_b32_e32 v24, 0xffff0000, v87
	v_add_f32_e32 v24, v25, v24
	v_cvt_pk_bf16_f32 v23, v23, v24
	v_lshlrev_b32_e32 v24, 16, v88
	v_and_b32_e32 v25, 0xffff0000, v88
	v_add_f32_e32 v24, v26, v24
	v_add_f32_e32 v25, v27, v25
	v_cvt_pk_bf16_f32 v24, v24, v25
	v_lshlrev_b32_e32 v25, 16, v89
	v_and_b32_e32 v26, 0xffff0000, v89
	v_add_f32_e32 v25, v28, v25
	v_add_f32_e32 v26, v29, v26
	v_and_b32_e32 v27, 0xffff0000, v22
	v_cvt_pk_bf16_f32 v25, v25, v26
	v_lshlrev_b32_e32 v26, 16, v22
	v_mul_f32_e32 v27, v27, v27
	v_lshlrev_b32_e32 v28, 16, v23
	v_fmac_f32_e32 v27, v26, v26
	v_and_b32_e32 v29, 0xffff0000, v23
	v_fmac_f32_e32 v27, v28, v28
	v_lshlrev_b32_e32 v31, 16, v24
	v_fmac_f32_e32 v27, v29, v29
	v_and_b32_e32 v32, 0xffff0000, v24
	v_fmac_f32_e32 v27, v31, v31
	v_lshlrev_b32_e32 v33, 16, v25
	v_fmac_f32_e32 v27, v32, v32
	v_and_b32_e32 v34, 0xffff0000, v25
	v_fmac_f32_e32 v27, v33, v33
	v_fmac_f32_e32 v27, v34, v34
	flat_store_dwordx4 v[20:21], v[22:25] offset:160
	v_add_f32_e32 v30, v30, v27
	ds_read_b128 v[22:25], v1 offset:96
	ds_read_b128 v[26:29], v1 offset:112
	v_lshlrev_b32_e32 v31, 16, v70
	s_waitcnt lgkmcnt(0)
	v_add_f32_e32 v22, v22, v31
	v_and_b32_e32 v31, 0xffff0000, v70
	v_add_f32_e32 v23, v23, v31
	v_cvt_pk_bf16_f32 v22, v22, v23
	v_lshlrev_b32_e32 v23, 16, v71
	v_add_f32_e32 v23, v24, v23
	v_and_b32_e32 v24, 0xffff0000, v71
	v_add_f32_e32 v24, v25, v24
	v_cvt_pk_bf16_f32 v23, v23, v24
	v_lshlrev_b32_e32 v24, 16, v72
	v_and_b32_e32 v25, 0xffff0000, v72
	v_add_f32_e32 v24, v26, v24
	v_add_f32_e32 v25, v27, v25
	v_cvt_pk_bf16_f32 v24, v24, v25
	v_lshlrev_b32_e32 v25, 16, v73
	v_and_b32_e32 v26, 0xffff0000, v73
	v_add_f32_e32 v25, v28, v25
	v_add_f32_e32 v26, v29, v26
	v_and_b32_e32 v27, 0xffff0000, v22
	v_cvt_pk_bf16_f32 v25, v25, v26
	v_lshlrev_b32_e32 v26, 16, v22
	v_mul_f32_e32 v27, v27, v27
	v_lshlrev_b32_e32 v28, 16, v23
	v_fmac_f32_e32 v27, v26, v26
	v_and_b32_e32 v29, 0xffff0000, v23
	v_fmac_f32_e32 v27, v28, v28
	v_lshlrev_b32_e32 v31, 16, v24
	v_fmac_f32_e32 v27, v29, v29
	v_and_b32_e32 v32, 0xffff0000, v24
	v_fmac_f32_e32 v27, v31, v31
	v_lshlrev_b32_e32 v33, 16, v25
	v_fmac_f32_e32 v27, v32, v32
	v_and_b32_e32 v34, 0xffff0000, v25
	v_fmac_f32_e32 v27, v33, v33
	v_fmac_f32_e32 v27, v34, v34
	flat_store_dwordx4 v[20:21], v[22:25] offset:176
	v_add_f32_e32 v30, v30, v27
	ds_read_b128 v[22:25], v1 offset:128
	ds_read_b128 v[26:29], v1 offset:144
	v_lshlrev_b32_e32 v31, 16, v14
	v_and_b32_e32 v14, 0xffff0000, v14
	s_waitcnt lgkmcnt(0)
	v_add_f32_e32 v22, v22, v31
	v_add_f32_e32 v14, v23, v14
	v_cvt_pk_bf16_f32 v14, v22, v14
	v_lshlrev_b32_e32 v22, 16, v15
	v_and_b32_e32 v15, 0xffff0000, v15
	v_add_f32_e32 v22, v24, v22
	v_add_f32_e32 v15, v25, v15
	v_cvt_pk_bf16_f32 v15, v22, v15
	v_lshlrev_b32_e32 v22, 16, v16
	v_and_b32_e32 v16, 0xffff0000, v16
	v_add_f32_e32 v22, v26, v22
	v_add_f32_e32 v16, v27, v16
	v_cvt_pk_bf16_f32 v16, v22, v16
	v_lshlrev_b32_e32 v22, 16, v17
	v_and_b32_e32 v17, 0xffff0000, v17
	v_add_f32_e32 v22, v28, v22
	v_add_f32_e32 v17, v29, v17
	v_and_b32_e32 v23, 0xffff0000, v14
	v_cvt_pk_bf16_f32 v17, v22, v17
	v_lshlrev_b32_e32 v22, 16, v14
	v_mul_f32_e32 v23, v23, v23
	v_lshlrev_b32_e32 v24, 16, v15
	v_fmac_f32_e32 v23, v22, v22
	v_and_b32_e32 v25, 0xffff0000, v15
	v_fmac_f32_e32 v23, v24, v24
	v_lshlrev_b32_e32 v26, 16, v16
	v_fmac_f32_e32 v23, v25, v25
	v_and_b32_e32 v27, 0xffff0000, v16
	v_fmac_f32_e32 v23, v26, v26
	v_lshlrev_b32_e32 v28, 16, v17
	v_fmac_f32_e32 v23, v27, v27
	v_and_b32_e32 v29, 0xffff0000, v17
	v_fmac_f32_e32 v23, v28, v28
	v_fmac_f32_e32 v23, v29, v29
	flat_store_dwordx4 v[20:21], v[14:17] offset:192
	v_add_f32_e32 v26, v30, v23
	ds_read_b128 v[14:17], v1 offset:160
	ds_read_b128 v[22:25], v1 offset:176
	v_lshlrev_b32_e32 v27, 16, v10
	v_and_b32_e32 v10, 0xffff0000, v10
	s_waitcnt lgkmcnt(0)
	v_add_f32_e32 v14, v14, v27
	v_add_f32_e32 v10, v15, v10
	v_cvt_pk_bf16_f32 v10, v14, v10
	v_lshlrev_b32_e32 v14, 16, v11
	v_and_b32_e32 v11, 0xffff0000, v11
	v_add_f32_e32 v14, v16, v14
	v_add_f32_e32 v11, v17, v11
	v_cvt_pk_bf16_f32 v11, v14, v11
	v_lshlrev_b32_e32 v14, 16, v12
	v_and_b32_e32 v12, 0xffff0000, v12
	v_add_f32_e32 v14, v22, v14
	v_add_f32_e32 v12, v23, v12
	v_cvt_pk_bf16_f32 v12, v14, v12
	v_lshlrev_b32_e32 v14, 16, v13
	v_and_b32_e32 v13, 0xffff0000, v13
	v_add_f32_e32 v14, v24, v14
	v_add_f32_e32 v13, v25, v13
	v_and_b32_e32 v15, 0xffff0000, v10
	v_cvt_pk_bf16_f32 v13, v14, v13
	v_lshlrev_b32_e32 v14, 16, v10
	v_mul_f32_e32 v15, v15, v15
	v_lshlrev_b32_e32 v16, 16, v11
	v_fmac_f32_e32 v15, v14, v14
	v_and_b32_e32 v17, 0xffff0000, v11
	v_fmac_f32_e32 v15, v16, v16
	v_lshlrev_b32_e32 v22, 16, v12
	v_fmac_f32_e32 v15, v17, v17
	v_and_b32_e32 v23, 0xffff0000, v12
	v_fmac_f32_e32 v15, v22, v22
	v_lshlrev_b32_e32 v24, 16, v13
	v_fmac_f32_e32 v15, v23, v23
	v_and_b32_e32 v25, 0xffff0000, v13
	v_fmac_f32_e32 v15, v24, v24
	v_fmac_f32_e32 v15, v25, v25
	flat_store_dwordx4 v[20:21], v[10:13] offset:208
	v_add_f32_e32 v22, v26, v15
	ds_read_b128 v[10:13], v1 offset:192
	ds_read_b128 v[14:17], v1 offset:208
	v_lshlrev_b32_e32 v23, 16, v6
	v_and_b32_e32 v6, 0xffff0000, v6
	s_waitcnt lgkmcnt(0)
	v_add_f32_e32 v10, v10, v23
	v_add_f32_e32 v6, v11, v6
	v_cvt_pk_bf16_f32 v6, v10, v6
	v_lshlrev_b32_e32 v10, 16, v7
	v_and_b32_e32 v7, 0xffff0000, v7
	v_add_f32_e32 v10, v12, v10
	v_add_f32_e32 v7, v13, v7
	v_cvt_pk_bf16_f32 v7, v10, v7
	v_lshlrev_b32_e32 v10, 16, v8
	v_and_b32_e32 v8, 0xffff0000, v8
	v_add_f32_e32 v10, v14, v10
	v_add_f32_e32 v8, v15, v8
	v_cvt_pk_bf16_f32 v8, v10, v8
	v_lshlrev_b32_e32 v10, 16, v9
	v_and_b32_e32 v9, 0xffff0000, v9
	v_add_f32_e32 v10, v16, v10
	v_add_f32_e32 v9, v17, v9
	v_and_b32_e32 v11, 0xffff0000, v6
	v_cvt_pk_bf16_f32 v9, v10, v9
	v_lshlrev_b32_e32 v10, 16, v6
	v_mul_f32_e32 v11, v11, v11
	v_lshlrev_b32_e32 v12, 16, v7
	v_fmac_f32_e32 v11, v10, v10
	v_and_b32_e32 v13, 0xffff0000, v7
	v_fmac_f32_e32 v11, v12, v12
	v_lshlrev_b32_e32 v14, 16, v8
	v_fmac_f32_e32 v11, v13, v13
	v_and_b32_e32 v15, 0xffff0000, v8
	v_fmac_f32_e32 v11, v14, v14
	v_lshlrev_b32_e32 v16, 16, v9
	v_fmac_f32_e32 v11, v15, v15
	v_and_b32_e32 v17, 0xffff0000, v9
	v_fmac_f32_e32 v11, v16, v16
	v_fmac_f32_e32 v11, v17, v17
	flat_store_dwordx4 v[20:21], v[6:9] offset:224
	v_add_f32_e32 v14, v22, v11
	ds_read_b128 v[6:9], v1 offset:224
	ds_read_b128 v[10:13], v1 offset:240
	v_lshlrev_b32_e32 v1, 16, v2
	v_and_b32_e32 v2, 0xffff0000, v2
	s_waitcnt lgkmcnt(0)
	v_add_f32_e32 v1, v6, v1
	v_add_f32_e32 v2, v7, v2
	v_cvt_pk_bf16_f32 v2, v1, v2
	v_lshlrev_b32_e32 v1, 16, v3
	v_and_b32_e32 v3, 0xffff0000, v3
	v_add_f32_e32 v1, v8, v1
	v_add_f32_e32 v3, v9, v3
	v_cvt_pk_bf16_f32 v3, v1, v3
	v_lshlrev_b32_e32 v1, 16, v4
	v_and_b32_e32 v4, 0xffff0000, v4
	v_add_f32_e32 v1, v10, v1
	v_add_f32_e32 v4, v11, v4
	v_cvt_pk_bf16_f32 v4, v1, v4
	v_lshlrev_b32_e32 v1, 16, v5
	v_and_b32_e32 v5, 0xffff0000, v5
	v_add_f32_e32 v1, v12, v1
	v_add_f32_e32 v5, v13, v5
	v_and_b32_e32 v6, 0xffff0000, v2
	v_cvt_pk_bf16_f32 v5, v1, v5
	v_lshlrev_b32_e32 v1, 16, v2
	v_mul_f32_e32 v6, v6, v6
	v_lshlrev_b32_e32 v7, 16, v3
	v_fmac_f32_e32 v6, v1, v1
	v_and_b32_e32 v8, 0xffff0000, v3
	v_fmac_f32_e32 v6, v7, v7
	v_lshlrev_b32_e32 v9, 16, v4
	v_fmac_f32_e32 v6, v8, v8
	v_and_b32_e32 v10, 0xffff0000, v4
	v_fmac_f32_e32 v6, v9, v9
	v_lshlrev_b32_e32 v11, 16, v5
	v_fmac_f32_e32 v6, v10, v10
	v_and_b32_e32 v12, 0xffff0000, v5
	v_fmac_f32_e32 v6, v11, v11
	flat_store_dwordx4 v[20:21], v[2:5] offset:240
	v_fmac_f32_e32 v6, v12, v12
	v_add_f32_e32 v1, v14, v6
	v_lshlrev_b64 v[2:3], 6, v[18:19]
	v_lshl_add_u64 v[2:3], s[6:7], 0, v[2:3]
	v_lshl_add_u64 v[2:3], v[2:3], 0, s[18:19]
	flat_store_dword v[2:3], v1 offset:4
	s_branch .LBB0_342

.LBB0_373:
	v_mov_b32_e32 v1, v170
	s_barrier
	s_lshl_b32 s46, s41, 1
	v_ashrrev_i32_e32 v2, 7, v1
	v_add_u32_e32 v3, s46, v2
	v_cmp_lt_i32_e32 vcc, s91, v3
	s_and_saveexec_b64 s[4:5], vcc
	s_xor_b64 s[22:23], exec, s[4:5]
	v_add_u32_e32 v3, 0xfffffef0, v3
	v_mul_hi_u32 v2, v3, s96
	v_lshrrev_b32_e32 v4, 3, v2
	v_add_u32_e32 v2, 16, v4
	v_lshl_add_u32 v4, v4, 5, v4
	v_sub_u32_e32 v6, v3, v4
	s_andn2_saveexec_b64 s[22:23], s[22:23]
	v_mul_hi_i32 v2, v3, s97
	v_lshrrev_b32_e32 v4, 31, v2
	v_ashrrev_i32_e32 v2, 3, v2
	v_add_u32_e32 v2, v2, v4
	v_lshl_add_u32 v4, v2, 4, v2
	v_sub_u32_e32 v6, v3, v4
	s_or_b64 exec, exec, s[22:23]
	v_cmp_lt_i32_e32 vcc, 15, v2
	s_and_saveexec_b64 s[4:5], vcc
	s_xor_b64 s[4:5], exec, s[4:5]
	v_add_u32_e32 v2, -16, v2
	v_mov_b32_e32 v3, v0
	v_lshlrev_b64 v[2:3], 12, v[2:3]
	v_lshl_add_u64 v[4:5], v[2:3], 0, s[42:43]
	s_andn2_saveexec_b64 s[22:23], s[4:5]
	v_ashrrev_i32_e32 v3, 31, v2
	v_lshlrev_b64 v[4:5], 11, v[2:3]
	s_or_b64 exec, exec, s[22:23]
	v_mad_u64_u32 v[2:3], s[4:5], v6, s54, -1
	v_ashrrev_i32_e32 v3, 31, v2
	v_and_b32_e32 v6, 0x7f, v1
	v_mov_b32_e32 v7, v0
	v_lshl_add_u64 v[2:3], v[2:3], 0, v[6:7]
	v_lshl_add_u64 v[2:3], v[2:3], 0, v[4:5]
	v_cmp_lt_i64_e32 vcc, 0, v[2:3]
	s_nop 1
	v_cndmask_b32_e32 v3, 0, v3, vcc
	v_cndmask_b32_e32 v2, 0, v2, vcc
	v_cmp_gt_i64_e32 vcc, s[44:45], v[2:3]
	v_mov_b32_e32 v3, v0
	s_nop 0
	v_cndmask_b32_e32 v2, v174, v2, vcc
	v_lshlrev_b32_e32 v2, 6, v2
	v_lshl_add_u64 v[14:15], s[8:9], 0, v[2:3]
	flat_load_dwordx4 v[2:5], v[14:15]
	flat_load_dwordx4 v[6:9], v[14:15] offset:16
	flat_load_dwordx4 v[10:13], v[14:15] offset:32
	s_waitcnt vmcnt(0) lgkmcnt(0)
	v_mov_b32_e32 v16, v3
	v_mov_b32_e32 v17, v4
	v_mov_b32_e32 v3, v5
	v_mov_b32_e32 v18, v7
	v_mov_b32_e32 v19, v8
	v_pk_add_f32 v[2:3], v[16:17], v[2:3]
	v_mov_b32_e32 v7, v9
	v_pk_add_f32 v[16:17], v[2:3], v[2:3] op_sel:[0,1] op_sel_hi:[1,0]
	v_pk_add_f32 v[2:3], v[18:19], v[6:7]
	s_nop 0
	v_pk_add_f32 v[6:7], v[2:3], v[2:3] op_sel:[0,1] op_sel_hi:[1,0]
	v_mov_b32_e32 v2, v11
	v_pk_add_f32 v[8:9], v[10:11], v[2:3]
	v_mov_b32_e32 v2, v13
	v_pk_add_f32 v[10:11], v[12:13], v[2:3]
	flat_load_dwordx4 v[2:5], v[14:15] offset:48
	s_waitcnt vmcnt(0) lgkmcnt(0)
	v_mov_b32_e32 v17, v2
	v_mov_b32_e32 v7, v3
	v_mov_b32_e32 v9, v4
	v_mov_b32_e32 v11, v5
	v_pk_add_f32 v[2:3], v[16:17], v[6:7]
	v_pk_add_f32 v[4:5], v[8:9], v[10:11]
	v_ashrrev_i32_e32 v6, 6, v1
	v_pk_add_f32 v[2:3], v[2:3], v[4:5]
	s_nop 0
	v_add_f32_e32 v2, v2, v3
	v_fmamk_f32 v2, v2, 0x3a800000, v172
	v_cmp_gt_f32_e32 vcc, s58, v2
	v_mul_f32_e32 v3, 0x4b800000, v2
	s_nop 0
	v_cndmask_b32_e32 v2, v2, v3, vcc
	v_rsq_f32_e32 v2, v2
	s_nop 0
	v_mul_f32_e32 v3, 0x45800000, v2
	v_cndmask_b32_e32 v2, v2, v3, vcc
	v_lshl_add_u32 v3, v1, 2, v175
	ds_write_b32 v3, v2
	v_and_b32_e32 v3, 63, v1
	v_cmp_lt_i32_e32 vcc, 2, v6
	s_and_saveexec_b64 s[4:5], vcc
	s_xor_b64 s[4:5], exec, s[4:5]
	v_lshl_or_b32 v2, s20, 6, v3
	s_or_saveexec_b64 s[22:23], s[4:5]
	v_mov_b64_e32 v[4:5], s[14:15]
	s_xor_b64 exec, exec, s[22:23]
	s_movk_i32 s4, 0xac0
	v_mul_lo_u32 v2, v6, s4
	v_lshl_add_u32 v2, s20, 6, v2
	v_or_b32_e32 v2, v2, v3
	v_mov_b64_e32 v[4:5], s[12:13]
	s_or_b64 exec, exec, s[22:23]
	v_ashrrev_i32_e32 v3, 31, v2
	v_lshl_add_u64 v[2:3], v[2:3], 2, v[4:5]
	flat_load_dword v2, v[2:3]
	v_lshl_add_u32 v3, v1, 2, v254
	v_mov_b32_e32 v1, v170
	s_waitcnt vmcnt(0) lgkmcnt(0)
	ds_write_b32 v3, v2
	s_nop 0
	v_ashrrev_i32_e32 v2, 9, v1
	v_add_u32_e32 v2, s46, v2
	v_cmp_lt_i32_e32 vcc, s91, v2
	s_and_saveexec_b64 s[4:5], vcc
	s_xor_b64 s[22:23], exec, s[4:5]
	v_add_u32_e32 v2, 0xfffffef0, v2
	v_mul_hi_u32 v3, v2, s96
	v_lshrrev_b32_e32 v3, 3, v3
	v_add_u32_e32 v4, 16, v3
	v_lshl_add_u32 v3, v3, 5, v3
	v_sub_u32_e32 v13, v2, v3
	s_andn2_saveexec_b64 s[22:23], s[22:23]
	v_mul_hi_i32 v3, v2, s97
	v_lshrrev_b32_e32 v4, 31, v3
	v_ashrrev_i32_e32 v3, 3, v3
	v_add_u32_e32 v4, v3, v4
	v_lshl_add_u32 v3, v4, 4, v4
	v_sub_u32_e32 v13, v2, v3
	s_or_b64 exec, exec, s[22:23]
	v_cmp_lt_i32_e32 vcc, 15, v4
	s_and_saveexec_b64 s[4:5], vcc
	s_xor_b64 s[4:5], exec, s[4:5]
	v_add_u32_e32 v2, -16, v4
	v_mov_b32_e32 v3, v0
	v_lshlrev_b64 v[2:3], 12, v[2:3]
	v_lshl_add_u64 v[2:3], v[2:3], 0, s[42:43]
	s_andn2_saveexec_b64 s[22:23], s[4:5]
	v_ashrrev_i32_e32 v5, 31, v4
	v_lshlrev_b64 v[2:3], 11, v[4:5]
	s_or_b64 exec, exec, s[22:23]
	v_lshlrev_b32_e32 v142, 4, v1
	v_add_u32_e32 v12, 0x1000, v142
	v_ashrrev_i32_e32 v4, 13, v12
	v_add_u32_e32 v4, s46, v4
	v_cmp_lt_i32_e32 vcc, s91, v4
	s_and_saveexec_b64 s[4:5], vcc
	s_xor_b64 s[4:5], exec, s[4:5]
	v_add_u32_e32 v4, 0xfffffef0, v4
	v_mul_hi_u32 v5, v4, s96
	v_lshrrev_b32_e32 v5, 3, v5
	v_add_u32_e32 v6, 16, v5
	v_lshl_add_u32 v5, v5, 5, v5
	v_sub_u32_e32 v15, v4, v5
	s_andn2_saveexec_b64 s[22:23], s[4:5]
	v_mul_hi_i32 v5, v4, s97
	v_lshrrev_b32_e32 v6, 31, v5
	v_ashrrev_i32_e32 v5, 3, v5
	v_add_u32_e32 v6, v5, v6
	v_lshl_add_u32 v5, v6, 4, v6
	v_sub_u32_e32 v15, v4, v5
	s_or_b64 exec, exec, s[22:23]
	v_cmp_lt_i32_e32 vcc, 15, v6
	s_and_saveexec_b64 s[4:5], vcc
	s_xor_b64 s[4:5], exec, s[4:5]
	v_add_u32_e32 v4, -16, v6
	v_mov_b32_e32 v5, v0
	v_lshlrev_b64 v[4:5], 12, v[4:5]
	v_lshl_add_u64 v[4:5], v[4:5], 0, s[42:43]
	s_andn2_saveexec_b64 s[4:5], s[4:5]
	v_ashrrev_i32_e32 v7, 31, v6
	v_lshlrev_b64 v[4:5], 11, v[6:7]
	s_or_b64 exec, exec, s[4:5]
	v_add_u32_e32 v14, 0x2000, v142
	v_ashrrev_i32_e32 v6, 13, v14
	v_add_u32_e32 v6, s46, v6
	v_cmp_lt_i32_e32 vcc, s91, v6
	s_and_saveexec_b64 s[4:5], vcc
	s_xor_b64 s[4:5], exec, s[4:5]
	v_add_u32_e32 v6, 0xfffffef0, v6
	v_mul_hi_u32 v7, v6, s96
	v_lshrrev_b32_e32 v7, 3, v7
	v_add_u32_e32 v8, 16, v7
	v_lshl_add_u32 v7, v7, 5, v7
	v_sub_u32_e32 v17, v6, v7
	s_andn2_saveexec_b64 s[22:23], s[4:5]
	v_mul_hi_i32 v7, v6, s97
	v_lshrrev_b32_e32 v8, 31, v7
	v_ashrrev_i32_e32 v7, 3, v7
	v_add_u32_e32 v8, v7, v8
	v_lshl_add_u32 v7, v8, 4, v8
	v_sub_u32_e32 v17, v6, v7
	s_or_b64 exec, exec, s[22:23]
	v_cmp_lt_i32_e32 vcc, 15, v8
	s_and_saveexec_b64 s[4:5], vcc
	s_xor_b64 s[4:5], exec, s[4:5]
	v_add_u32_e32 v6, -16, v8
	v_mov_b32_e32 v7, v0
	v_lshlrev_b64 v[6:7], 12, v[6:7]
	v_lshl_add_u64 v[6:7], v[6:7], 0, s[42:43]
	s_andn2_saveexec_b64 s[4:5], s[4:5]
	v_ashrrev_i32_e32 v9, 31, v8
	v_lshlrev_b64 v[6:7], 11, v[8:9]
	s_or_b64 exec, exec, s[4:5]
	v_add_u32_e32 v16, 0x3000, v142
	v_ashrrev_i32_e32 v8, 13, v16
	v_add_u32_e32 v8, s46, v8
	v_cmp_lt_i32_e32 vcc, s91, v8
	s_and_saveexec_b64 s[4:5], vcc
	s_xor_b64 s[4:5], exec, s[4:5]
	v_add_u32_e32 v8, 0xfffffef0, v8
	v_mul_hi_u32 v9, v8, s96
	v_lshrrev_b32_e32 v9, 3, v9
	v_add_u32_e32 v10, 16, v9
	v_lshl_add_u32 v9, v9, 5, v9
	v_sub_u32_e32 v18, v8, v9
	s_andn2_saveexec_b64 s[22:23], s[4:5]
	v_mul_hi_i32 v9, v8, s97
	v_lshrrev_b32_e32 v10, 31, v9
	v_ashrrev_i32_e32 v9, 3, v9
	v_add_u32_e32 v10, v9, v10
	v_lshl_add_u32 v9, v10, 4, v10
	v_sub_u32_e32 v18, v8, v9
	s_or_b64 exec, exec, s[22:23]
	v_cmp_lt_i32_e32 vcc, 15, v10
	s_and_saveexec_b64 s[4:5], vcc
	s_xor_b64 s[4:5], exec, s[4:5]
	v_add_u32_e32 v8, -16, v10
	v_mov_b32_e32 v9, v0
	v_lshlrev_b64 v[8:9], 12, v[8:9]
	v_lshl_add_u64 v[8:9], v[8:9], 0, s[42:43]
	s_andn2_saveexec_b64 s[4:5], s[4:5]
	v_ashrrev_i32_e32 v11, 31, v10
	v_lshlrev_b64 v[8:9], 11, v[10:11]
	s_or_b64 exec, exec, s[4:5]
	v_mad_u64_u32 v[24:25], s[4:5], v17, s54, -1
	v_bfe_u32 v22, v142, 6, 7
	v_mov_b32_e32 v23, v0
	v_ashrrev_i32_e32 v25, 31, v24
	v_lshl_add_u64 v[24:25], v[24:25], 0, v[22:23]
	v_lshl_add_u64 v[6:7], v[24:25], 0, v[6:7]
	v_cmp_lt_i64_e32 vcc, 0, v[6:7]
	v_and_b32_e32 v44, 32, v1
	v_bitop3_b32 v10, v142, v44, 48 bitop3:0x6c
	v_cndmask_b32_e32 v7, 0, v7, vcc
	v_cndmask_b32_e32 v6, 0, v6, vcc
	v_cmp_gt_i64_e32 vcc, s[44:45], v[6:7]
	v_mov_b32_e32 v11, v0
	v_lshl_add_u64 v[20:21], s[6:7], 0, v[10:11]
	v_cndmask_b32_e32 v6, v174, v6, vcc
	v_lshlrev_b32_e32 v6, 11, v6
	v_mov_b32_e32 v7, v0
	v_bfe_u32 v19, v142, 6, 4
	v_lshl_add_u64 v[24:25], v[20:21], 0, v[6:7]
	v_lshrrev_b32_e32 v7, 6, v16
	v_and_or_b32 v26, v7, s82, v19
	v_lshrrev_b32_e32 v7, 6, v12
	v_mad_u64_u32 v[30:31], s[24:25], v15, s54, -1
	v_and_or_b32 v28, v7, s82, v19
	v_ashrrev_i32_e32 v31, 31, v30
	v_mov_b32_e32 v29, v0
	v_lshl_add_u64 v[28:29], v[30:31], 0, v[28:29]
	v_lshl_add_u64 v[4:5], v[28:29], 0, v[4:5]
	v_mad_u64_u32 v[30:31], s[24:25], v13, s54, -1
	v_cmp_lt_i64_e32 vcc, 0, v[4:5]
	v_ashrrev_i32_e32 v31, 31, v30
	v_lshl_add_u64 v[22:23], v[30:31], 0, v[22:23]
	v_cndmask_b32_e32 v5, 0, v5, vcc
	v_cndmask_b32_e32 v4, 0, v4, vcc
	v_cmp_gt_i64_e32 vcc, s[44:45], v[4:5]
	v_lshl_add_u64 v[2:3], v[22:23], 0, v[2:3]
	v_mad_u64_u32 v[18:19], s[66:67], v18, s54, -1
	v_cndmask_b32_e32 v4, v174, v4, vcc
	v_cmp_lt_i64_e32 vcc, 0, v[2:3]
	v_ashrrev_i32_e32 v19, 31, v18
	v_mov_b32_e32 v27, v0
	v_cndmask_b32_e32 v3, 0, v3, vcc
	v_cndmask_b32_e32 v2, 0, v2, vcc
	v_lshl_add_u64 v[18:19], v[18:19], 0, v[26:27]
	v_cmp_gt_i64_e32 vcc, s[44:45], v[2:3]
	v_lshl_add_u64 v[8:9], v[18:19], 0, v[8:9]
	v_mov_b32_e32 v3, v0
	v_cndmask_b32_e32 v2, v174, v2, vcc
	v_cmp_lt_i64_e32 vcc, 0, v[8:9]
	v_lshlrev_b32_e32 v2, 11, v2
	v_lshl_add_u64 v[22:23], v[20:21], 0, v[2:3]
	v_cndmask_b32_e32 v9, 0, v9, vcc
	v_cndmask_b32_e32 v8, 0, v8, vcc
	v_cmp_gt_i64_e32 vcc, s[44:45], v[8:9]
	s_ashr_i32 s21, s20, 31
	v_readfirstlane_b32 s5, v142
	v_cndmask_b32_e32 v3, v174, v8, vcc
	v_lshrrev_b32_e32 v32, 6, v142
	v_lshlrev_b32_e32 v4, 11, v4
	v_mov_b32_e32 v5, v0
	s_lshl_b64 s[24:25], s[20:21], 18
	v_lshlrev_b32_e32 v8, 11, v3
	v_mov_b32_e32 v9, v0
	v_ashrrev_i32_e32 v3, 2, v1
	s_waitcnt vmcnt(0)
	s_mov_b32 m0, s5
	v_readfirstlane_b32 s5, v12
	v_lshl_add_u64 v[28:29], v[20:21], 0, v[4:5]
	s_add_u32 s64, s26, s24
	v_lshl_add_u64 v[18:19], v[20:21], 0, v[8:9]
	v_bfi_b32 v20, 15, v32, v3
	v_ashrrev_i32_e32 v3, 6, v12
	s_mov_b32 m0, s5
	v_readfirstlane_b32 s5, v14
	s_addc_u32 s65, s27, s25
	v_ashrrev_i32_e32 v21, 31, v20
	v_bfi_b32 v30, -16, v3, v32
	v_add_u32_e32 v15, 0x4000, v142
	s_mov_b32 m0, s5
	v_readfirstlane_b32 s5, v16
	v_lshl_add_u64 v[10:11], s[64:65], 0, v[10:11]
	v_lshlrev_b64 v[20:21], 11, v[20:21]
	v_ashrrev_i32_e32 v31, 31, v30
	v_add_u32_e32 v17, 0x5000, v142
	s_mov_b32 m0, s5
	v_readfirstlane_b32 s5, v15
	v_lshl_add_u64 v[26:27], v[10:11], 0, v[20:21]
	v_lshlrev_b64 v[30:31], 11, v[30:31]
	v_add_u32_e32 v46, 0x6000, v142
	s_mov_b32 m0, s5
	v_readfirstlane_b32 s5, v17
	v_lshl_add_u64 v[10:11], v[10:11], 0, v[30:31]
	v_add_u32_e32 v47, 0x7000, v142
	s_mov_b32 m0, s5
	v_readfirstlane_b32 s5, v46
	v_lshl_add_u64 v[32:33], v[22:23], 0, 64
	v_add_u32_e32 v48, 0x8000, v142
	s_mov_b32 m0, s5
	v_readfirstlane_b32 s5, v47
	v_add_u32_e32 v49, 0x9000, v142
	v_lshl_add_u64 v[34:35], v[28:29], 0, 64
	s_mov_b32 m0, s5
	v_readfirstlane_b32 s5, v48
	v_add_u32_e32 v50, 0xa000, v142
	v_lshl_add_u64 v[36:37], v[24:25], 0, 64
	s_mov_b32 m0, s5
	v_readfirstlane_b32 s5, v49
	v_add_u32_e32 v51, 0xb000, v142
	v_lshl_add_u64 v[38:39], v[18:19], 0, 64
	s_mov_b32 m0, s5
	v_readfirstlane_b32 s5, v50
	v_lshl_add_u64 v[40:41], v[26:27], 0, 64
	s_mov_b32 m0, s5
	v_readfirstlane_b32 s5, v51
	v_lshl_add_u64 v[42:43], v[10:11], 0, 64
	s_mov_b32 m0, s5
	v_and_b32_e32 v45, 48, v142
	v_and_b32_e32 v143, 15, v1
	v_bfe_u32 v144, v1, 4, 2
	v_lshlrev_b32_e32 v5, 6, v1
	v_lshlrev_b32_e32 v13, 2, v1
	v_lshl_add_u64 v[10:11], s[24:25], 0, v[30:31]
	v_lshlrev_b32_e32 v3, 4, v144
	v_and_b32_e32 v7, 0x3c0, v5
	v_lshlrev_b32_e32 v9, 6, v143
	v_and_b32_e32 v13, 32, v13
	v_bitop3_b32 v10, v10, v45, v44 bitop3:0xf6
	v_bitop3_b32 v149, v3, v13, v7 bitop3:0x36
	v_bitop3_b32 v145, v3, v13, v9 bitop3:0x36
	v_lshl_add_u64 v[130:131], s[16:17], 0, v[10:11]
	v_lshl_add_u64 v[10:11], s[24:25], 0, v[20:21]
	v_bitop3_b32 v2, v2, v45, v44 bitop3:0xf6
	v_mov_b32_e32 v3, v0
	v_and_b32_e32 v147, 0xfffff000, v5
	v_bitop3_b32 v10, v10, v45, v44 bitop3:0xf6
	v_bitop3_b32 v8, v8, v45, v44 bitop3:0xf6
	v_mov_b32_e32 v9, v0
	v_bitop3_b32 v6, v6, v45, v44 bitop3:0xf6
	v_mov_b32_e32 v7, v0
	v_bitop3_b32 v4, v4, v45, v44 bitop3:0xf6
	v_mov_b32_e32 v5, v0
	v_lshl_add_u64 v[140:141], s[18:19], 0, v[2:3]
	v_mov_b32_e32 v2, 0
	s_mov_b64 s[22:23], 0
	s_mov_b32 s4, 0
	v_lshl_add_u64 v[132:133], s[16:17], 0, v[10:11]
	v_lshl_add_u64 v[134:135], s[18:19], 0, v[8:9]
	v_lshl_add_u64 v[136:137], s[18:19], 0, v[6:7]
	v_lshl_add_u64 v[138:139], s[18:19], 0, v[4:5]
	v_mov_b32_e32 v3, v2
	v_mov_b32_e32 v4, v2
	v_mov_b32_e32 v5, v2
	v_mov_b32_e32 v6, v2
	v_mov_b32_e32 v7, v2
	v_mov_b32_e32 v8, v2
	v_mov_b32_e32 v9, v2
	v_mov_b32_e32 v10, v2
	v_mov_b32_e32 v11, v2
	v_mov_b32_e32 v12, v2
	v_mov_b32_e32 v13, v2
	v_mov_b32_e32 v18, v2
	v_mov_b32_e32 v19, v2
	v_mov_b32_e32 v20, v2
	v_mov_b32_e32 v21, v2
	v_mov_b32_e32 v26, v2
	v_mov_b32_e32 v27, v2
	v_mov_b32_e32 v28, v2
	v_mov_b32_e32 v29, v2
	v_mov_b32_e32 v38, v2
	v_mov_b32_e32 v39, v2
	v_mov_b32_e32 v40, v2
	v_mov_b32_e32 v41, v2
	v_mov_b32_e32 v46, v2
	v_mov_b32_e32 v47, v2
	v_mov_b32_e32 v48, v2
	v_mov_b32_e32 v49, v2
	v_mov_b32_e32 v62, v2
	v_mov_b32_e32 v63, v2
	v_mov_b32_e32 v64, v2
	v_mov_b32_e32 v65, v2
	v_mov_b32_e32 v14, v2
	v_mov_b32_e32 v15, v2
	v_mov_b32_e32 v16, v2
	v_mov_b32_e32 v17, v2
	v_mov_b32_e32 v22, v2
	v_mov_b32_e32 v23, v2
	v_mov_b32_e32 v24, v2
	v_mov_b32_e32 v25, v2
	v_mov_b32_e32 v30, v2
	v_mov_b32_e32 v31, v2
	v_mov_b32_e32 v32, v2
	v_mov_b32_e32 v33, v2
	v_mov_b32_e32 v42, v2
	v_mov_b32_e32 v43, v2
	v_mov_b32_e32 v44, v2
	v_mov_b32_e32 v45, v2
	v_mov_b32_e32 v54, v2
	v_mov_b32_e32 v55, v2
	v_mov_b32_e32 v56, v2
	v_mov_b32_e32 v57, v2
	v_mov_b32_e32 v70, v2
	v_mov_b32_e32 v71, v2
	v_mov_b32_e32 v72, v2
	v_mov_b32_e32 v73, v2
	v_mov_b32_e32 v78, v2
	v_mov_b32_e32 v79, v2
	v_mov_b32_e32 v80, v2
	v_mov_b32_e32 v81, v2
	v_mov_b32_e32 v94, v2
	v_mov_b32_e32 v95, v2
	v_mov_b32_e32 v96, v2
	v_mov_b32_e32 v97, v2
	v_mov_b32_e32 v34, v2
	v_mov_b32_e32 v35, v2
	v_mov_b32_e32 v36, v2
	v_mov_b32_e32 v37, v2
	v_mov_b32_e32 v50, v2
	v_mov_b32_e32 v51, v2
	v_mov_b32_e32 v52, v2
	v_mov_b32_e32 v53, v2
	v_mov_b32_e32 v58, v2
	v_mov_b32_e32 v59, v2
	v_mov_b32_e32 v60, v2
	v_mov_b32_e32 v61, v2
	v_mov_b32_e32 v74, v2
	v_mov_b32_e32 v75, v2
	v_mov_b32_e32 v76, v2
	v_mov_b32_e32 v77, v2
	v_mov_b32_e32 v86, v2
	v_mov_b32_e32 v87, v2
	v_mov_b32_e32 v88, v2
	v_mov_b32_e32 v89, v2
	v_mov_b32_e32 v98, v2
	v_mov_b32_e32 v99, v2
	v_mov_b32_e32 v100, v2
	v_mov_b32_e32 v101, v2
	v_mov_b32_e32 v106, v2
	v_mov_b32_e32 v107, v2
	v_mov_b32_e32 v108, v2
	v_mov_b32_e32 v109, v2
	v_mov_b32_e32 v114, v2
	v_mov_b32_e32 v115, v2
	v_mov_b32_e32 v116, v2
	v_mov_b32_e32 v117, v2
	v_mov_b32_e32 v66, v2
	v_mov_b32_e32 v67, v2
	v_mov_b32_e32 v68, v2
	v_mov_b32_e32 v69, v2
	v_mov_b32_e32 v82, v2
	v_mov_b32_e32 v83, v2
	v_mov_b32_e32 v84, v2
	v_mov_b32_e32 v85, v2
	v_mov_b32_e32 v90, v2
	v_mov_b32_e32 v91, v2
	v_mov_b32_e32 v92, v2
	v_mov_b32_e32 v93, v2
	v_mov_b32_e32 v102, v2
	v_mov_b32_e32 v103, v2
	v_mov_b32_e32 v104, v2
	v_mov_b32_e32 v105, v2
	v_mov_b32_e32 v110, v2
	v_mov_b32_e32 v111, v2
	v_mov_b32_e32 v112, v2
	v_mov_b32_e32 v113, v2
	v_mov_b32_e32 v118, v2
	v_mov_b32_e32 v119, v2
	v_mov_b32_e32 v120, v2
	v_mov_b32_e32 v121, v2
	v_mov_b32_e32 v122, v2
	v_mov_b32_e32 v123, v2
	v_mov_b32_e32 v124, v2
	v_mov_b32_e32 v125, v2
	v_mov_b32_e32 v126, v2
	v_mov_b32_e32 v127, v2
	v_mov_b32_e32 v128, v2
	v_mov_b32_e32 v129, v2
	v_and_b32_e32 v154, 63, v170
	v_lshrrev_b32_e32 v155, 3, v154
	v_and_b32_e32 v156, 7, v154
	v_xor_b32_e32 v156, v156, v155
	v_lshrrev_b32_e32 v157, 6, v170
	v_lshlrev_b32_e32 v231, 4, v156
	v_lshrrev_b32_e32 v159, 1, v157
	v_add_u32_e32 v159, s46, v159
	v_mul_u32_u24_e32 v160, 0xf10, v159
	v_lshrrev_b32_e32 v160, 16, v160
	v_mul_u32_u24_e32 v161, 17, v160
	v_sub_u32_e32 v161, v159, v161
	v_lshlrev_b32_e32 v160, 11, v160
	v_mul_u32_u24_e32 v161, 0x7e, v161
	v_add_u32_e32 v160, v160, v161
	v_add_u32_e32 v161, 0xfffffef0, v159
	v_mul_u32_u24_e32 v162, 0x7c2, v161
	v_lshrrev_b32_e32 v162, 16, v162
	v_mul_u32_u24_e32 v224, 33, v162
	v_sub_u32_e32 v161, v161, v224
	v_lshlrev_b32_e32 v162, 12, v162
	v_mul_u32_u24_e32 v161, 0x7e, v161
	v_add_u32_e32 v161, v162, v161
	v_add_u32_e32 v161, 0x8000, v161
	v_cmp_lt_u32_e32 vcc, 0x10f, v159
	s_nop 1
	v_cndmask_b32_e32 v160, v160, v161, vcc
	v_and_b32_e32 v161, 1, v157
	v_lshl_add_u32 v161, v161, 6, v155
	v_add3_u32 v224, v160, v161, -1
	v_lshl_add_u32 v158, v157, 5, v155
	v_mul_u32_u24_e32 v225, 0x800, v158
	v_lshl_add_u32 v225, v156, 4, v225
	v_and_b32_e32 v155, 15, v154
	v_lshrrev_b32_e32 v156, 4, v154
	v_and_b32_e32 v158, 7, v155
	v_xor_b32_e32 v156, v156, v158
	v_lshlrev_b32_e32 v156, 4, v156
	v_lshl_add_u32 v229, v155, 7, v156
	v_lshl_add_u32 v227, v157, 13, v229
	v_xor_b32_e32 v228, 64, v227
	v_add_u32_e32 v229, 0xc000, v229
	v_xor_b32_e32 v230, 64, v229
	s_mov_b32 s4, s6
	s_mov_b32 s5, s7
	s_mov_b32 s22, s64
	s_mov_b32 s23, s65
	s_mov_b32 s21, 0
	v_readfirstlane_b32 s32, v142
	s_lshl_b32 m0, s32, 3
	v_add_u32_e32 v226, 0, v224
	v_max_i32_e32 v226, 0, v226
	v_min_i32_e32 v226, 0xffff, v226
	v_lshl_add_u32 v226, v226, 11, v231
	global_load_lds_dwordx4 v226, s[4:5]
	s_add_u32 m0, m0, 0x400
	v_add_u32_e32 v226, 8, v224
	v_max_i32_e32 v226, 0, v226
	v_min_i32_e32 v226, 0xffff, v226
	v_lshl_add_u32 v226, v226, 11, v231
	global_load_lds_dwordx4 v226, s[4:5]
	s_add_u32 m0, m0, 0x400
	v_add_u32_e32 v226, 16, v224
	v_max_i32_e32 v226, 0, v226
	v_min_i32_e32 v226, 0xffff, v226
	v_lshl_add_u32 v226, v226, 11, v231
	global_load_lds_dwordx4 v226, s[4:5]
	s_add_u32 m0, m0, 0x400
	v_add_u32_e32 v226, 24, v224
	v_max_i32_e32 v226, 0, v226
	v_min_i32_e32 v226, 0xffff, v226
	v_lshl_add_u32 v226, v226, 11, v231
	global_load_lds_dwordx4 v226, s[4:5]
	s_add_u32 m0, m0, 0x400
	v_add_u32_e32 v226, 32, v224
	v_max_i32_e32 v226, 0, v226
	v_min_i32_e32 v226, 0xffff, v226
	v_lshl_add_u32 v226, v226, 11, v231
	global_load_lds_dwordx4 v226, s[4:5]
	s_add_u32 m0, m0, 0x400
	v_add_u32_e32 v226, 40, v224
	v_max_i32_e32 v226, 0, v226
	v_min_i32_e32 v226, 0xffff, v226
	v_lshl_add_u32 v226, v226, 11, v231
	global_load_lds_dwordx4 v226, s[4:5]
	s_add_u32 m0, m0, 0x400
	v_add_u32_e32 v226, 48, v224
	v_max_i32_e32 v226, 0, v226
	v_min_i32_e32 v226, 0xffff, v226
	v_lshl_add_u32 v226, v226, 11, v231
	global_load_lds_dwordx4 v226, s[4:5]
	s_add_u32 m0, m0, 0x400
	v_add_u32_e32 v226, 56, v224
	v_max_i32_e32 v226, 0, v226
	v_min_i32_e32 v226, 0xffff, v226
	v_lshl_add_u32 v226, v226, 11, v231
	global_load_lds_dwordx4 v226, s[4:5]
	v_readfirstlane_b32 s32, v142
	s_lshl_b32 s32, s32, 2
	s_add_u32 m0, s32, 0xc000
	v_mov_b32_e32 v226, v225
	global_load_lds_dwordx4 v226, s[22:23]
	s_add_u32 m0, m0, 0x400
	v_add_u32_e32 v226, 0x4000, v225
	global_load_lds_dwordx4 v226, s[22:23]
	s_add_u32 m0, m0, 0x400
	v_add_u32_e32 v226, 0x8000, v225
	global_load_lds_dwordx4 v226, s[22:23]
	s_add_u32 m0, m0, 0x400
	v_add_u32_e32 v226, 0xc000, v225
	global_load_lds_dwordx4 v226, s[22:23]
.Lbk64_418:
	s_waitcnt vmcnt(0)
	s_barrier
	ds_read_b128 v[192:195], v227
	ds_read_b128 v[196:199], v228
	ds_read_b128 v[200:203], v227 offset:2048
	ds_read_b128 v[204:207], v228 offset:2048
	ds_read_b128 v[208:211], v227 offset:4096
	ds_read_b128 v[212:215], v228 offset:4096
	ds_read_b128 v[216:219], v227 offset:6144
	ds_read_b128 v[220:223], v228 offset:6144
	s_add_u32 s4, s4, 0x80
	s_addc_u32 s5, s5, 0
	s_add_u32 s22, s22, 0x80
	s_addc_u32 s23, s23, 0
	s_waitcnt lgkmcnt(0)
	s_barrier
	ds_read_b128 v[154:157], v229 offset:0
	ds_read_b128 v[158:161], v230 offset:0
	ds_read_b128 v[162:165], v229 offset:2048
	ds_read_b128 v[166:169], v230 offset:2048
	s_waitcnt lgkmcnt(2)
	v_mfma_f32_16x16x32_bf16 v[126:129], v[192:195], v[154:157], v[126:129]
	v_mfma_f32_16x16x32_bf16 v[114:117], v[200:203], v[154:157], v[114:117]
	v_mfma_f32_16x16x32_bf16 v[94:97], v[208:211], v[154:157], v[94:97]
	v_mfma_f32_16x16x32_bf16 v[62:65], v[216:219], v[154:157], v[62:65]
	v_readfirstlane_b32 s32, v142
	s_lshl_b32 m0, s32, 3
	v_add_u32_e32 v226, 0, v224
	v_max_i32_e32 v226, 0, v226
	v_min_i32_e32 v226, 0xffff, v226
	v_lshl_add_u32 v226, v226, 11, v231
	global_load_lds_dwordx4 v226, s[4:5]
	v_mfma_f32_16x16x32_bf16 v[126:129], v[196:199], v[158:161], v[126:129]
	v_mfma_f32_16x16x32_bf16 v[114:117], v[204:207], v[158:161], v[114:117]
	v_mfma_f32_16x16x32_bf16 v[94:97], v[212:215], v[158:161], v[94:97]
	v_mfma_f32_16x16x32_bf16 v[62:65], v[220:223], v[158:161], v[62:65]
	s_add_u32 m0, m0, 0x400
	v_add_u32_e32 v226, 8, v224
	v_max_i32_e32 v226, 0, v226
	v_min_i32_e32 v226, 0xffff, v226
	v_lshl_add_u32 v226, v226, 11, v231
	global_load_lds_dwordx4 v226, s[4:5]
	ds_read_b128 v[154:157], v229 offset:4096
	ds_read_b128 v[158:161], v230 offset:4096
	s_waitcnt lgkmcnt(2)
	v_mfma_f32_16x16x32_bf16 v[122:125], v[192:195], v[162:165], v[122:125]
	v_mfma_f32_16x16x32_bf16 v[106:109], v[200:203], v[162:165], v[106:109]
	v_mfma_f32_16x16x32_bf16 v[78:81], v[208:211], v[162:165], v[78:81]
	v_mfma_f32_16x16x32_bf16 v[46:49], v[216:219], v[162:165], v[46:49]
	s_add_u32 m0, m0, 0x400
	v_add_u32_e32 v226, 16, v224
	v_max_i32_e32 v226, 0, v226
	v_min_i32_e32 v226, 0xffff, v226
	v_lshl_add_u32 v226, v226, 11, v231
	global_load_lds_dwordx4 v226, s[4:5]
	v_mfma_f32_16x16x32_bf16 v[122:125], v[196:199], v[166:169], v[122:125]
	v_mfma_f32_16x16x32_bf16 v[106:109], v[204:207], v[166:169], v[106:109]
	v_mfma_f32_16x16x32_bf16 v[78:81], v[212:215], v[166:169], v[78:81]
	v_mfma_f32_16x16x32_bf16 v[46:49], v[220:223], v[166:169], v[46:49]
	s_add_u32 m0, m0, 0x400
	v_add_u32_e32 v226, 24, v224
	v_max_i32_e32 v226, 0, v226
	v_min_i32_e32 v226, 0xffff, v226
	v_lshl_add_u32 v226, v226, 11, v231
	global_load_lds_dwordx4 v226, s[4:5]
	ds_read_b128 v[162:165], v229 offset:6144
	ds_read_b128 v[166:169], v230 offset:6144
	s_waitcnt lgkmcnt(2)
	v_mfma_f32_16x16x32_bf16 v[118:121], v[192:195], v[154:157], v[118:121]
	v_mfma_f32_16x16x32_bf16 v[98:101], v[200:203], v[154:157], v[98:101]
	v_mfma_f32_16x16x32_bf16 v[70:73], v[208:211], v[154:157], v[70:73]
	v_mfma_f32_16x16x32_bf16 v[38:41], v[216:219], v[154:157], v[38:41]
	s_add_u32 m0, m0, 0x400
	v_add_u32_e32 v226, 32, v224
	v_max_i32_e32 v226, 0, v226
	v_min_i32_e32 v226, 0xffff, v226
	v_lshl_add_u32 v226, v226, 11, v231
	global_load_lds_dwordx4 v226, s[4:5]
	v_mfma_f32_16x16x32_bf16 v[118:121], v[196:199], v[158:161], v[118:121]
	v_mfma_f32_16x16x32_bf16 v[98:101], v[204:207], v[158:161], v[98:101]
	v_mfma_f32_16x16x32_bf16 v[70:73], v[212:215], v[158:161], v[70:73]
	v_mfma_f32_16x16x32_bf16 v[38:41], v[220:223], v[158:161], v[38:41]
	s_add_u32 m0, m0, 0x400
	v_add_u32_e32 v226, 40, v224
	v_max_i32_e32 v226, 0, v226
	v_min_i32_e32 v226, 0xffff, v226
	v_lshl_add_u32 v226, v226, 11, v231
	global_load_lds_dwordx4 v226, s[4:5]
	ds_read_b128 v[154:157], v229 offset:8192
	ds_read_b128 v[158:161], v230 offset:8192
	s_waitcnt lgkmcnt(2)
	v_mfma_f32_16x16x32_bf16 v[110:113], v[192:195], v[162:165], v[110:113]
	v_mfma_f32_16x16x32_bf16 v[86:89], v[200:203], v[162:165], v[86:89]
	v_mfma_f32_16x16x32_bf16 v[54:57], v[208:211], v[162:165], v[54:57]
	v_mfma_f32_16x16x32_bf16 v[26:29], v[216:219], v[162:165], v[26:29]
	s_add_u32 m0, m0, 0x400
	v_add_u32_e32 v226, 48, v224
	v_max_i32_e32 v226, 0, v226
	v_min_i32_e32 v226, 0xffff, v226
	v_lshl_add_u32 v226, v226, 11, v231
	global_load_lds_dwordx4 v226, s[4:5]
	v_mfma_f32_16x16x32_bf16 v[110:113], v[196:199], v[166:169], v[110:113]
	v_mfma_f32_16x16x32_bf16 v[86:89], v[204:207], v[166:169], v[86:89]
	v_mfma_f32_16x16x32_bf16 v[54:57], v[212:215], v[166:169], v[54:57]
	v_mfma_f32_16x16x32_bf16 v[26:29], v[220:223], v[166:169], v[26:29]
	s_add_u32 m0, m0, 0x400
	v_add_u32_e32 v226, 56, v224
	v_max_i32_e32 v226, 0, v226
	v_min_i32_e32 v226, 0xffff, v226
	v_lshl_add_u32 v226, v226, 11, v231
	global_load_lds_dwordx4 v226, s[4:5]
	ds_read_b128 v[162:165], v229 offset:10240
	ds_read_b128 v[166:169], v230 offset:10240
	s_waitcnt lgkmcnt(2)
	v_mfma_f32_16x16x32_bf16 v[102:105], v[192:195], v[154:157], v[102:105]
	v_mfma_f32_16x16x32_bf16 v[74:77], v[200:203], v[154:157], v[74:77]
	v_mfma_f32_16x16x32_bf16 v[42:45], v[208:211], v[154:157], v[42:45]
	v_mfma_f32_16x16x32_bf16 v[18:21], v[216:219], v[154:157], v[18:21]
	s_add_u32 m0, s21, 16
	s_and_b32 m0, m0, 1
	s_lshl_b32 m0, m0, 14
	s_add_u32 m0, m0, 0x8000
	v_readfirstlane_b32 s32, v142
	s_lshl_b32 s32, s32, 2
	s_add_u32 m0, m0, s32
	v_mov_b32_e32 v226, v225
	global_load_lds_dwordx4 v226, s[22:23]
	v_mfma_f32_16x16x32_bf16 v[102:105], v[196:199], v[158:161], v[102:105]
	v_mfma_f32_16x16x32_bf16 v[74:77], v[204:207], v[158:161], v[74:77]
	v_mfma_f32_16x16x32_bf16 v[42:45], v[212:215], v[158:161], v[42:45]
	v_mfma_f32_16x16x32_bf16 v[18:21], v[220:223], v[158:161], v[18:21]
	s_add_u32 m0, m0, 0x400
	v_add_u32_e32 v226, 0x4000, v225
	global_load_lds_dwordx4 v226, s[22:23]
	ds_read_b128 v[154:157], v229 offset:12288
	ds_read_b128 v[158:161], v230 offset:12288
	s_waitcnt lgkmcnt(2)
	v_mfma_f32_16x16x32_bf16 v[90:93], v[192:195], v[162:165], v[90:93]
	v_mfma_f32_16x16x32_bf16 v[58:61], v[200:203], v[162:165], v[58:61]
	v_mfma_f32_16x16x32_bf16 v[30:33], v[208:211], v[162:165], v[30:33]
	v_mfma_f32_16x16x32_bf16 v[10:13], v[216:219], v[162:165], v[10:13]
	s_add_u32 m0, m0, 0x400
	v_add_u32_e32 v226, 0x8000, v225
	global_load_lds_dwordx4 v226, s[22:23]
	v_mfma_f32_16x16x32_bf16 v[90:93], v[196:199], v[166:169], v[90:93]
	v_mfma_f32_16x16x32_bf16 v[58:61], v[204:207], v[166:169], v[58:61]
	v_mfma_f32_16x16x32_bf16 v[30:33], v[212:215], v[166:169], v[30:33]
	v_mfma_f32_16x16x32_bf16 v[10:13], v[220:223], v[166:169], v[10:13]
	s_add_u32 m0, m0, 0x400
	v_add_u32_e32 v226, 0xc000, v225
	global_load_lds_dwordx4 v226, s[22:23]
	ds_read_b128 v[162:165], v229 offset:14336
	ds_read_b128 v[166:169], v230 offset:14336
	s_waitcnt lgkmcnt(2)
	v_mfma_f32_16x16x32_bf16 v[82:85], v[192:195], v[154:157], v[82:85]
	v_mfma_f32_16x16x32_bf16 v[50:53], v[200:203], v[154:157], v[50:53]
	v_mfma_f32_16x16x32_bf16 v[22:25], v[208:211], v[154:157], v[22:25]
	v_mfma_f32_16x16x32_bf16 v[6:9], v[216:219], v[154:157], v[6:9]
	v_mfma_f32_16x16x32_bf16 v[82:85], v[196:199], v[158:161], v[82:85]
	v_mfma_f32_16x16x32_bf16 v[50:53], v[204:207], v[158:161], v[50:53]
	v_mfma_f32_16x16x32_bf16 v[22:25], v[212:215], v[158:161], v[22:25]
	v_mfma_f32_16x16x32_bf16 v[6:9], v[220:223], v[158:161], v[6:9]
	s_waitcnt lgkmcnt(0)
	v_mfma_f32_16x16x32_bf16 v[66:69], v[192:195], v[162:165], v[66:69]
	v_mfma_f32_16x16x32_bf16 v[34:37], v[200:203], v[162:165], v[34:37]
	v_mfma_f32_16x16x32_bf16 v[14:17], v[208:211], v[162:165], v[14:17]
	v_mfma_f32_16x16x32_bf16 v[2:5], v[216:219], v[162:165], v[2:5]
	v_mfma_f32_16x16x32_bf16 v[66:69], v[196:199], v[166:169], v[66:69]
	v_mfma_f32_16x16x32_bf16 v[34:37], v[204:207], v[166:169], v[34:37]
	v_mfma_f32_16x16x32_bf16 v[14:17], v[212:215], v[166:169], v[14:17]
	v_mfma_f32_16x16x32_bf16 v[2:5], v[220:223], v[166:169], v[2:5]
	v_xor_b32_e32 v229, 0x4000, v229
	v_xor_b32_e32 v230, 0x4000, v230
	s_add_i32 s21, s21, 1
	s_cmp_lg_u32 s21, 14
	s_cbranch_scc1 .Lbk64_418
	s_waitcnt vmcnt(0)
	s_barrier
	ds_read_b128 v[192:195], v227
	ds_read_b128 v[196:199], v228
	ds_read_b128 v[200:203], v227 offset:2048
	ds_read_b128 v[204:207], v228 offset:2048
	ds_read_b128 v[208:211], v227 offset:4096
	ds_read_b128 v[212:215], v228 offset:4096
	ds_read_b128 v[216:219], v227 offset:6144
	ds_read_b128 v[220:223], v228 offset:6144
	s_waitcnt lgkmcnt(0)
	s_barrier
	ds_read_b128 v[154:157], v229 offset:0
	ds_read_b128 v[158:161], v230 offset:0
	ds_read_b128 v[162:165], v229 offset:2048
	ds_read_b128 v[166:169], v230 offset:2048
	s_waitcnt lgkmcnt(2)
	v_mfma_f32_16x16x32_bf16 v[126:129], v[192:195], v[154:157], v[126:129]
	v_mfma_f32_16x16x32_bf16 v[114:117], v[200:203], v[154:157], v[114:117]
	v_mfma_f32_16x16x32_bf16 v[94:97], v[208:211], v[154:157], v[94:97]
	v_mfma_f32_16x16x32_bf16 v[62:65], v[216:219], v[154:157], v[62:65]
	s_mov_b64 s[4:5], 0x700
	v_readfirstlane_b32 s32, v142
	s_mov_b32 m0, s32
	v_lshl_add_u64 v[224:225], v[140:141], 0, s[4:5]
	global_load_lds_dwordx4 v[224:225], off
	v_mfma_f32_16x16x32_bf16 v[126:129], v[196:199], v[158:161], v[126:129]
	v_mfma_f32_16x16x32_bf16 v[114:117], v[204:207], v[158:161], v[114:117]
	v_mfma_f32_16x16x32_bf16 v[94:97], v[212:215], v[158:161], v[94:97]
	v_mfma_f32_16x16x32_bf16 v[62:65], v[220:223], v[158:161], v[62:65]
	s_add_u32 m0, m0, 0x1000
	v_lshl_add_u64 v[224:225], v[138:139], 0, s[4:5]
	global_load_lds_dwordx4 v[224:225], off
	ds_read_b128 v[154:157], v229 offset:4096
	ds_read_b128 v[158:161], v230 offset:4096
	s_waitcnt lgkmcnt(2)
	v_mfma_f32_16x16x32_bf16 v[122:125], v[192:195], v[162:165], v[122:125]
	v_mfma_f32_16x16x32_bf16 v[106:109], v[200:203], v[162:165], v[106:109]
	v_mfma_f32_16x16x32_bf16 v[78:81], v[208:211], v[162:165], v[78:81]
	v_mfma_f32_16x16x32_bf16 v[46:49], v[216:219], v[162:165], v[46:49]
	s_add_u32 m0, m0, 0x1000
	v_lshl_add_u64 v[224:225], v[136:137], 0, s[4:5]
	global_load_lds_dwordx4 v[224:225], off
	v_mfma_f32_16x16x32_bf16 v[122:125], v[196:199], v[166:169], v[122:125]
	v_mfma_f32_16x16x32_bf16 v[106:109], v[204:207], v[166:169], v[106:109]
	v_mfma_f32_16x16x32_bf16 v[78:81], v[212:215], v[166:169], v[78:81]
	v_mfma_f32_16x16x32_bf16 v[46:49], v[220:223], v[166:169], v[46:49]
	s_add_u32 m0, m0, 0x1000
	v_lshl_add_u64 v[224:225], v[134:135], 0, s[4:5]
	global_load_lds_dwordx4 v[224:225], off
	ds_read_b128 v[162:165], v229 offset:6144
	ds_read_b128 v[166:169], v230 offset:6144
	s_waitcnt lgkmcnt(2)
	v_mfma_f32_16x16x32_bf16 v[118:121], v[192:195], v[154:157], v[118:121]
	v_mfma_f32_16x16x32_bf16 v[98:101], v[200:203], v[154:157], v[98:101]
	v_mfma_f32_16x16x32_bf16 v[70:73], v[208:211], v[154:157], v[70:73]
	v_mfma_f32_16x16x32_bf16 v[38:41], v[216:219], v[154:157], v[38:41]
	s_add_u32 m0, m0, 0x1000
	v_lshl_add_u64 v[224:225], v[132:133], 0, s[4:5]
	global_load_lds_dwordx4 v[224:225], off
	v_mfma_f32_16x16x32_bf16 v[118:121], v[196:199], v[158:161], v[118:121]
	v_mfma_f32_16x16x32_bf16 v[98:101], v[204:207], v[158:161], v[98:101]
	v_mfma_f32_16x16x32_bf16 v[70:73], v[212:215], v[158:161], v[70:73]
	v_mfma_f32_16x16x32_bf16 v[38:41], v[220:223], v[158:161], v[38:41]
	s_add_u32 m0, m0, 0x1000
	v_lshl_add_u64 v[224:225], v[130:131], 0, s[4:5]
	global_load_lds_dwordx4 v[224:225], off
	ds_read_b128 v[154:157], v229 offset:8192
	ds_read_b128 v[158:161], v230 offset:8192
	s_waitcnt lgkmcnt(2)
	v_mfma_f32_16x16x32_bf16 v[110:113], v[192:195], v[162:165], v[110:113]
	v_mfma_f32_16x16x32_bf16 v[86:89], v[200:203], v[162:165], v[86:89]
	v_mfma_f32_16x16x32_bf16 v[54:57], v[208:211], v[162:165], v[54:57]
	v_mfma_f32_16x16x32_bf16 v[26:29], v[216:219], v[162:165], v[26:29]
	s_mov_b64 s[4:5], 0x740
	v_readfirstlane_b32 s32, v142
	s_add_u32 m0, s32, 0x6000
	v_lshl_add_u64 v[224:225], v[140:141], 0, s[4:5]
	global_load_lds_dwordx4 v[224:225], off
	v_mfma_f32_16x16x32_bf16 v[110:113], v[196:199], v[166:169], v[110:113]
	v_mfma_f32_16x16x32_bf16 v[86:89], v[204:207], v[166:169], v[86:89]
	v_mfma_f32_16x16x32_bf16 v[54:57], v[212:215], v[166:169], v[54:57]
	v_mfma_f32_16x16x32_bf16 v[26:29], v[220:223], v[166:169], v[26:29]
	s_add_u32 m0, m0, 0x1000
	v_lshl_add_u64 v[224:225], v[138:139], 0, s[4:5]
	global_load_lds_dwordx4 v[224:225], off
	ds_read_b128 v[162:165], v229 offset:10240
	ds_read_b128 v[166:169], v230 offset:10240
	s_waitcnt lgkmcnt(2)
	v_mfma_f32_16x16x32_bf16 v[102:105], v[192:195], v[154:157], v[102:105]
	v_mfma_f32_16x16x32_bf16 v[74:77], v[200:203], v[154:157], v[74:77]
	v_mfma_f32_16x16x32_bf16 v[42:45], v[208:211], v[154:157], v[42:45]
	v_mfma_f32_16x16x32_bf16 v[18:21], v[216:219], v[154:157], v[18:21]
	s_add_u32 m0, m0, 0x1000
	v_lshl_add_u64 v[224:225], v[136:137], 0, s[4:5]
	global_load_lds_dwordx4 v[224:225], off
	v_mfma_f32_16x16x32_bf16 v[102:105], v[196:199], v[158:161], v[102:105]
	v_mfma_f32_16x16x32_bf16 v[74:77], v[204:207], v[158:161], v[74:77]
	v_mfma_f32_16x16x32_bf16 v[42:45], v[212:215], v[158:161], v[42:45]
	v_mfma_f32_16x16x32_bf16 v[18:21], v[220:223], v[158:161], v[18:21]
	s_add_u32 m0, m0, 0x1000
	v_lshl_add_u64 v[224:225], v[134:135], 0, s[4:5]
	global_load_lds_dwordx4 v[224:225], off
	ds_read_b128 v[154:157], v229 offset:12288
	ds_read_b128 v[158:161], v230 offset:12288
	s_waitcnt lgkmcnt(2)
	v_mfma_f32_16x16x32_bf16 v[90:93], v[192:195], v[162:165], v[90:93]
	v_mfma_f32_16x16x32_bf16 v[58:61], v[200:203], v[162:165], v[58:61]
	v_mfma_f32_16x16x32_bf16 v[30:33], v[208:211], v[162:165], v[30:33]
	v_mfma_f32_16x16x32_bf16 v[10:13], v[216:219], v[162:165], v[10:13]
	s_add_u32 m0, m0, 0x1000
	v_lshl_add_u64 v[224:225], v[132:133], 0, s[4:5]
	global_load_lds_dwordx4 v[224:225], off
	v_mfma_f32_16x16x32_bf16 v[90:93], v[196:199], v[166:169], v[90:93]
	v_mfma_f32_16x16x32_bf16 v[58:61], v[204:207], v[166:169], v[58:61]
	v_mfma_f32_16x16x32_bf16 v[30:33], v[212:215], v[166:169], v[30:33]
	v_mfma_f32_16x16x32_bf16 v[10:13], v[220:223], v[166:169], v[10:13]
	s_add_u32 m0, m0, 0x1000
	v_lshl_add_u64 v[224:225], v[130:131], 0, s[4:5]
	global_load_lds_dwordx4 v[224:225], off
	ds_read_b128 v[162:165], v229 offset:14336
	ds_read_b128 v[166:169], v230 offset:14336
	s_waitcnt lgkmcnt(2)
	v_mfma_f32_16x16x32_bf16 v[82:85], v[192:195], v[154:157], v[82:85]
	v_mfma_f32_16x16x32_bf16 v[50:53], v[200:203], v[154:157], v[50:53]
	v_mfma_f32_16x16x32_bf16 v[22:25], v[208:211], v[154:157], v[22:25]
	v_mfma_f32_16x16x32_bf16 v[6:9], v[216:219], v[154:157], v[6:9]
	v_mfma_f32_16x16x32_bf16 v[82:85], v[196:199], v[158:161], v[82:85]
	v_mfma_f32_16x16x32_bf16 v[50:53], v[204:207], v[158:161], v[50:53]
	v_mfma_f32_16x16x32_bf16 v[22:25], v[212:215], v[158:161], v[22:25]
	v_mfma_f32_16x16x32_bf16 v[6:9], v[220:223], v[158:161], v[6:9]
	s_waitcnt lgkmcnt(0)
	v_mfma_f32_16x16x32_bf16 v[66:69], v[192:195], v[162:165], v[66:69]
	v_mfma_f32_16x16x32_bf16 v[34:37], v[200:203], v[162:165], v[34:37]
	v_mfma_f32_16x16x32_bf16 v[14:17], v[208:211], v[162:165], v[14:17]
	v_mfma_f32_16x16x32_bf16 v[2:5], v[216:219], v[162:165], v[2:5]
	v_mfma_f32_16x16x32_bf16 v[66:69], v[196:199], v[166:169], v[66:69]
	v_mfma_f32_16x16x32_bf16 v[34:37], v[204:207], v[166:169], v[34:37]
	v_mfma_f32_16x16x32_bf16 v[14:17], v[212:215], v[166:169], v[14:17]
	v_mfma_f32_16x16x32_bf16 v[2:5], v[220:223], v[166:169], v[2:5]
	s_waitcnt vmcnt(6)
	s_barrier
	v_add_u32_e32 v142, v149, v147
	ds_read_b128 v[130:133], v142
	ds_read_b128 v[134:137], v145 offset:16384
	ds_read_b128 v[138:141], v142 offset:1024
	ds_read_b128 v[154:157], v142 offset:2048
	ds_read_b128 v[158:161], v142 offset:3072
	s_waitcnt lgkmcnt(0)
	v_mfma_f32_16x16x32_bf16 v[126:129], v[130:133], v[134:137], v[126:129]
	v_and_b32_e32 v1, 0xfffffc0, v1
	v_lshl_or_b32 v1, v144, 2, v1
	v_mul_lo_u32 v1, v1, s33
	v_mfma_f32_16x16x32_bf16 v[114:117], v[138:141], v[134:137], v[114:117]
	v_lshl_or_b32 v1, v143, 2, v1
	v_mfma_f32_16x16x32_bf16 v[94:97], v[154:157], v[134:137], v[94:97]
	v_mfma_f32_16x16x32_bf16 v[62:65], v[158:161], v[134:137], v[62:65]
	ds_read_b128 v[134:137], v145 offset:17408
	s_waitcnt lgkmcnt(0)
	v_mfma_f32_16x16x32_bf16 v[122:125], v[130:133], v[134:137], v[122:125]
	v_mfma_f32_16x16x32_bf16 v[106:109], v[138:141], v[134:137], v[106:109]
	v_mfma_f32_16x16x32_bf16 v[78:81], v[154:157], v[134:137], v[78:81]
	v_mfma_f32_16x16x32_bf16 v[46:49], v[158:161], v[134:137], v[46:49]
	ds_read_b128 v[134:137], v145 offset:18432
	s_waitcnt lgkmcnt(0)
	v_mfma_f32_16x16x32_bf16 v[118:121], v[130:133], v[134:137], v[118:121]
	v_mfma_f32_16x16x32_bf16 v[98:101], v[138:141], v[134:137], v[98:101]
	v_mfma_f32_16x16x32_bf16 v[70:73], v[154:157], v[134:137], v[70:73]
	v_mfma_f32_16x16x32_bf16 v[38:41], v[158:161], v[134:137], v[38:41]
	ds_read_b128 v[134:137], v145 offset:19456
	s_waitcnt lgkmcnt(0)
	v_mfma_f32_16x16x32_bf16 v[110:113], v[130:133], v[134:137], v[110:113]
	v_mfma_f32_16x16x32_bf16 v[86:89], v[138:141], v[134:137], v[86:89]
	v_mfma_f32_16x16x32_bf16 v[54:57], v[154:157], v[134:137], v[54:57]
	v_mfma_f32_16x16x32_bf16 v[26:29], v[158:161], v[134:137], v[26:29]
	ds_read_b128 v[134:137], v145 offset:20480
	s_waitcnt lgkmcnt(0)
	v_mfma_f32_16x16x32_bf16 v[102:105], v[130:133], v[134:137], v[102:105]
	v_mfma_f32_16x16x32_bf16 v[74:77], v[138:141], v[134:137], v[74:77]
	v_mfma_f32_16x16x32_bf16 v[42:45], v[154:157], v[134:137], v[42:45]
	v_mfma_f32_16x16x32_bf16 v[18:21], v[158:161], v[134:137], v[18:21]
	ds_read_b128 v[134:137], v145 offset:21504
	s_waitcnt lgkmcnt(0)
	v_mfma_f32_16x16x32_bf16 v[90:93], v[130:133], v[134:137], v[90:93]
	v_mfma_f32_16x16x32_bf16 v[58:61], v[138:141], v[134:137], v[58:61]
	v_mfma_f32_16x16x32_bf16 v[162:165], v[154:157], v[134:137], v[30:33]
	v_mfma_f32_16x16x32_bf16 v[134:137], v[158:161], v[134:137], v[10:13]
	s_nop 2
	ds_read_b128 v[10:13], v145 offset:22528
	s_waitcnt lgkmcnt(0)
	v_mfma_f32_16x16x32_bf16 v[180:183], v[158:161], v[10:13], v[6:9]
	s_nop 2
	ds_read_b128 v[6:9], v145 offset:23552
	s_waitcnt vmcnt(0)
	s_barrier
	v_mfma_f32_16x16x32_bf16 v[82:85], v[130:133], v[10:13], v[82:85]
	v_mfma_f32_16x16x32_bf16 v[50:53], v[138:141], v[10:13], v[50:53]
	v_mfma_f32_16x16x32_bf16 v[166:169], v[154:157], v[10:13], v[22:25]
	s_waitcnt lgkmcnt(0)
	v_mfma_f32_16x16x32_bf16 v[66:69], v[130:133], v[6:9], v[66:69]
	v_mfma_f32_16x16x32_bf16 v[130:133], v[138:141], v[6:9], v[34:37]
	v_mfma_f32_16x16x32_bf16 v[138:141], v[154:157], v[6:9], v[14:17]
	ds_read_b128 v[154:157], v142 offset:24576
	v_mfma_f32_16x16x32_bf16 v[158:161], v[158:161], v[6:9], v[2:5]
	ds_read_b128 v[192:195], v142 offset:25600
	s_nop 1
	ds_read_b128 v[2:5], v145 offset:40960
	ds_read_b128 v[6:9], v145 offset:41984
	s_waitcnt lgkmcnt(0)
	v_mfma_f32_16x16x32_bf16 v[22:25], v[154:157], v[2:5], v[126:129]
	s_nop 2
	ds_read_b128 v[126:129], v142 offset:26624
	v_mfma_f32_16x16x32_bf16 v[32:35], v[192:195], v[2:5], v[114:117]
	s_nop 2
	ds_read_b128 v[114:117], v142 offset:27648
	s_waitcnt lgkmcnt(0)
	v_mfma_f32_16x16x32_bf16 v[94:97], v[126:129], v[2:5], v[94:97]
	v_mfma_f32_16x16x32_bf16 v[62:65], v[114:117], v[2:5], v[62:65]
	v_mfma_f32_16x16x32_bf16 v[2:5], v[154:157], v[6:9], v[122:125]
	v_mfma_f32_16x16x32_bf16 v[106:109], v[192:195], v[6:9], v[106:109]
	v_mfma_f32_16x16x32_bf16 v[78:81], v[126:129], v[6:9], v[78:81]
	v_mfma_f32_16x16x32_bf16 v[122:125], v[114:117], v[6:9], v[46:49]
	ds_read_b128 v[6:9], v145 offset:43008
	ds_read_b128 v[10:13], v145 offset:44032
	s_waitcnt lgkmcnt(0)
	v_mfma_f32_16x16x32_bf16 v[46:49], v[154:157], v[6:9], v[118:121]
	v_mfma_f32_16x16x32_bf16 v[118:121], v[114:117], v[6:9], v[38:41]
	v_mfma_f32_16x16x32_bf16 v[36:39], v[154:157], v[10:13], v[110:113]
	s_nop 2
	ds_read_b128 v[110:113], v145 offset:45056
	ds_read_b128 v[196:199], v145 offset:46080
	ds_read_b128 v[204:207], v145 offset:47104
	ds_read_b128 v[208:211], v145 offset:48128
	s_waitcnt vmcnt(0) lgkmcnt(0)
	v_mfma_f32_16x16x32_bf16 v[98:101], v[192:195], v[6:9], v[98:101]
	s_barrier
	ds_write2_b32 v1, v22, v2 offset1:16
	ds_write2_b32 v1, v23, v3 offset0:68 offset1:84
	ds_write2_b32 v1, v24, v4 offset0:136 offset1:152
	v_mfma_f32_16x16x32_bf16 v[70:73], v[126:129], v[6:9], v[70:73]
	ds_write2_b32 v1, v25, v5 offset0:204 offset1:220
	ds_write2_b32 v1, v46, v36 offset0:32 offset1:48
	ds_write2_b32 v1, v47, v37 offset0:100 offset1:116
	ds_write2_b32 v1, v48, v38 offset0:168 offset1:184
	ds_write2_b32 v1, v49, v39 offset0:236 offset1:252
	v_mfma_f32_16x16x32_bf16 v[200:203], v[192:195], v[10:13], v[86:89]
	v_mfma_f32_16x16x32_bf16 v[54:57], v[126:129], v[10:13], v[54:57]
	s_nop 1
	v_add_u32_e32 v88, 0x1000, v1
	ds_write2_b32 v88, v32, v106 offset0:64 offset1:80
	ds_write2_b32 v88, v33, v107 offset0:132 offset1:148
	ds_write2_b32 v88, v34, v108 offset0:200 offset1:216
	v_add_u32_e32 v89, 0x1400, v1
	v_mfma_f32_16x16x32_bf16 v[212:215], v[114:117], v[10:13], v[26:29]
	ds_write2_b32 v89, v35, v109 offset0:12 offset1:28
	ds_write2_b32 v88, v98, v200 offset0:96 offset1:112
	ds_write2_b32 v88, v99, v201 offset0:164 offset1:180
	ds_write2_b32 v88, v100, v202 offset0:232 offset1:248
	ds_write2_b32 v89, v101, v203 offset0:44 offset1:60
	v_mfma_f32_16x16x32_bf16 v[30:33], v[154:157], v[196:199], v[90:93]
	s_nop 2
	v_add_u32_e32 v90, 0x2000, v1
	v_add_u32_e32 v91, 0x2400, v1
	ds_write2_b32 v90, v94, v78 offset0:128 offset1:144
	ds_write2_b32 v90, v95, v79 offset0:196 offset1:212
	ds_write2_b32 v91, v96, v80 offset0:8 offset1:24
	ds_write2_b32 v91, v97, v81 offset0:76 offset1:92
	ds_write2_b32 v90, v70, v54 offset0:160 offset1:176
	ds_write2_b32 v90, v71, v55 offset0:228 offset1:244
	ds_write2_b32 v91, v72, v56 offset0:40 offset1:56
	v_add_u32_e32 v92, 0x3000, v1
	v_add_u32_e32 v93, 0x3400, v1
	v_mov_b32_e32 v70, v170
	v_mfma_f32_16x16x32_bf16 v[6:9], v[126:129], v[110:113], v[42:45]
	ds_write2_b32 v91, v73, v57 offset0:108 offset1:124
	ds_write2_b32 v92, v62, v122 offset0:192 offset1:208
	ds_write2_b32 v93, v63, v123 offset0:4 offset1:20
	ds_write2_b32 v93, v64, v124 offset0:72 offset1:88
	v_mfma_f32_16x16x32_bf16 v[42:45], v[192:195], v[204:207], v[50:53]
	ds_write2_b32 v93, v65, v125 offset0:140 offset1:156
	ds_write2_b32 v92, v118, v212 offset0:224 offset1:240
	ds_write2_b32 v93, v119, v213 offset0:36 offset1:52
	ds_write2_b32 v93, v120, v214 offset0:104 offset1:120
	ds_write2_b32 v93, v121, v215 offset0:172 offset1:188
	s_waitcnt lgkmcnt(0)
	s_barrier
	v_mfma_f32_16x16x32_bf16 v[14:17], v[154:157], v[110:113], v[102:105]
	v_ashrrev_i32_e32 v50, 7, v70
	v_mfma_f32_16x16x32_bf16 v[10:13], v[192:195], v[110:113], v[74:77]
	v_mfma_f32_16x16x32_bf16 v[2:5], v[114:117], v[110:113], v[18:21]
	v_mfma_f32_16x16x32_bf16 v[26:29], v[192:195], v[196:199], v[58:61]
	v_mfma_f32_16x16x32_bf16 v[22:25], v[126:129], v[196:199], v[162:165]
	v_mfma_f32_16x16x32_bf16 v[18:21], v[114:117], v[196:199], v[134:137]
	v_mfma_f32_16x16x32_bf16 v[46:49], v[154:157], v[204:207], v[82:85]
	v_mfma_f32_16x16x32_bf16 v[38:41], v[126:129], v[204:207], v[166:169]
	v_mfma_f32_16x16x32_bf16 v[34:37], v[114:117], v[204:207], v[180:183]
	v_mfma_f32_16x16x32_bf16 v[62:65], v[154:157], v[208:211], v[66:69]
	v_mfma_f32_16x16x32_bf16 v[58:61], v[192:195], v[208:211], v[130:133]
	s_nop 1
	v_add_u32_e32 v66, s46, v50
	v_cmp_lt_i32_e32 vcc, s91, v66
	v_mfma_f32_16x16x32_bf16 v[54:57], v[126:129], v[208:211], v[138:141]
	v_mfma_f32_16x16x32_bf16 v[50:53], v[114:117], v[208:211], v[158:161]
	s_and_saveexec_b64 s[4:5], vcc
	s_xor_b64 s[22:23], exec, s[4:5]
	v_add_u32_e32 v66, 0xfffffef0, v66
	v_mul_hi_u32 v67, v66, s96
	v_lshrrev_b32_e32 v67, 3, v67
	v_add_u32_e32 v68, 16, v67
	v_lshl_add_u32 v67, v67, 5, v67
	v_sub_u32_e32 v71, v66, v67
	s_or_saveexec_b64 s[22:23], s[22:23]
	v_mov_b32_e32 v72, 0x1000
	s_xor_b64 exec, exec, s[22:23]
	v_mul_hi_i32 v67, v66, s97
	v_lshrrev_b32_e32 v68, 31, v67
	v_ashrrev_i32_e32 v67, 3, v67
	v_add_u32_e32 v68, v67, v68
	v_lshl_add_u32 v67, v68, 4, v68
	v_sub_u32_e32 v71, v66, v67
	v_mov_b32_e32 v72, 0x800
	s_or_b64 exec, exec, s[22:23]
	v_cmp_lt_i32_e32 vcc, 15, v68
	s_and_saveexec_b64 s[4:5], vcc
	s_xor_b64 s[4:5], exec, s[4:5]
	v_add_u32_e32 v66, -16, v68
	v_mov_b32_e32 v67, v0
	v_lshlrev_b64 v[66:67], 12, v[66:67]
	v_lshl_add_u64 v[66:67], v[66:67], 0, s[42:43]
	s_andn2_saveexec_b64 s[22:23], s[4:5]
	v_ashrrev_i32_e32 v69, 31, v68
	v_lshlrev_b64 v[66:67], 11, v[68:69]
	s_or_b64 exec, exec, s[22:23]
	v_and_b32_e32 v69, 0x7f, v70
	v_cmp_gt_i32_e32 vcc, s79, v69
	s_and_saveexec_b64 s[22:23], vcc
	s_cbranch_execz .LBB0_436
	v_cmp_ne_u32_e32 vcc, 0, v69
	s_and_b64 exec, exec, vcc
	s_cbranch_execz .LBB0_436
	v_mul_lo_u32 v71, v71, s54
	v_add3_u32 v68, v69, v71, -1
	v_cmp_lt_i32_e32 vcc, v68, v72
	s_and_b64 exec, exec, vcc
	s_cbranch_execz .LBB0_436
	v_cmp_lt_i32_e32 vcc, 0, v68
	v_mov_b32_e32 v83, 0
	v_mov_b32_e32 v82, 0
	s_and_saveexec_b64 s[4:5], vcc
	v_mov_b32_e32 v73, 0x11ffc
	v_lshl_add_u32 v73, v70, 2, v73
	ds_read_b32 v82, v73
	s_or_b64 exec, exec, s[4:5]
	v_add_u32_e32 v69, v71, v69
	v_cmp_lt_i32_e32 vcc, v69, v72
	v_lshl_add_u32 v69, v70, 2, v175
	ds_read_b32 v84, v69
	s_and_saveexec_b64 s[4:5], vcc
	ds_read_b32 v83, v69 offset:4
	s_or_b64 exec, exec, s[4:5]
	s_lshl_b32 s4, s20, 6
	s_ashr_i32 s5, s4, 31
	s_lshl_b64 s[4:5], s[4:5], 1
	v_ashrrev_i32_e32 v69, 31, v68
	s_add_u32 s4, s38, s4
	v_lshl_add_u64 v[66:67], v[66:67], 0, v[68:69]
	v_mul_lo_u32 v68, v70, s33
	s_addc_u32 s5, s39, s5
	v_add_u32_e32 v94, 0xfffffef0, v68
	v_mov_b64_e32 v[68:69], s[4:5]
	v_mad_u64_u32 v[86:87], s[4:5], v66, s3, v[68:69]
	v_mov_b32_e32 v66, v87
	v_mad_u64_u32 v[66:67], s[4:5], v67, s3, v[66:67]
	v_mov_b32_e32 v87, v66
	s_mov_b32 s4, 0

.LBB0_555:
	s_and_b64 vcc, exec, s[4:5]
	s_cbranch_vccz .LBB0_537
	v_mov_b32_e32 v1, v170
	s_ashr_i32 s31, s30, 31
	v_add_u32_e32 v2, s71, v1
	v_ashrrev_i32_e32 v3, 31, v2
	v_lshlrev_b64 v[2:3], 6, v[2:3]
	v_lshl_add_u64 v[2:3], s[14:15], 0, v[2:3]
	v_mov_b32_e32 v1, v170
	flat_load_dwordx4 v[14:17], v[2:3]
	flat_load_dwordx4 v[10:13], v[2:3] offset:16
	flat_load_dwordx4 v[6:9], v[2:3] offset:32
	s_nop 0
	flat_load_dwordx4 v[2:5], v[2:3] offset:48
	s_lshl_b64 s[6:7], s[30:31], 18
	v_lshlrev_b32_e32 v153, 4, v1
	v_bfe_u32 v51, v1, 2, 4
	v_ashrrev_i32_e32 v30, 2, v1
	v_add_u32_e32 v53, 0x1000, v153
	v_add_u32_e32 v54, 0x2000, v153
	v_add_u32_e32 v56, 0x3000, v153
	v_or_b32_e32 v28, s71, v51
	v_and_b32_e32 v22, -16, v30
	v_ashrrev_i32_e32 v35, 6, v53
	v_ashrrev_i32_e32 v26, 6, v54
	v_ashrrev_i32_e32 v29, 6, v56
	s_add_u32 s4, s57, s6
	v_and_b32_e32 v50, 32, v1
	v_add_u32_e32 v22, v28, v22
	v_and_b32_e32 v24, -16, v35
	v_and_b32_e32 v55, -16, v26
	v_and_b32_e32 v57, -16, v29
	s_addc_u32 s5, s62, s7
	v_bitop3_b32 v18, v153, v50, 48 bitop3:0x6c
	v_mov_b32_e32 v19, v0
	v_ashrrev_i32_e32 v23, 31, v22
	v_add_u32_e32 v24, v24, v28
	v_add_u32_e32 v26, v55, v28
	v_add_u32_e32 v28, v57, v28
	v_lshl_add_u64 v[20:21], s[8:9], 0, v[18:19]
	v_lshlrev_b64 v[22:23], 11, v[22:23]
	v_ashrrev_i32_e32 v25, 31, v24
	v_ashrrev_i32_e32 v27, 31, v26
	v_ashrrev_i32_e32 v29, 31, v28
	v_lshl_add_u64 v[18:19], s[4:5], 0, v[18:19]
	v_readfirstlane_b32 s4, v153
	v_lshrrev_b32_e32 v34, 2, v1
	v_lshl_add_u64 v[22:23], v[20:21], 0, v[22:23]
	v_lshlrev_b64 v[24:25], 11, v[24:25]
	v_lshlrev_b64 v[26:27], 11, v[26:27]
	v_lshlrev_b64 v[28:29], 11, v[28:29]
	s_waitcnt vmcnt(0)
	s_mov_b32 m0, s4
	v_readfirstlane_b32 s4, v53
	v_lshl_add_u64 v[24:25], v[20:21], 0, v[24:25]
	v_lshl_add_u64 v[26:27], v[20:21], 0, v[26:27]
	v_lshl_add_u64 v[20:21], v[20:21], 0, v[28:29]
	v_bfi_b32 v28, 15, v34, v30
	s_mov_b32 m0, s4
	v_readfirstlane_b32 s4, v54
	v_ashrrev_i32_e32 v29, 31, v28
	v_bfi_b32 v34, -16, v35, v34
	v_add_u32_e32 v58, 0x4000, v153
	s_mov_b32 m0, s4
	v_readfirstlane_b32 s4, v56
	v_lshlrev_b64 v[30:31], 11, v[28:29]
	v_ashrrev_i32_e32 v35, 31, v34
	v_add_u32_e32 v59, 0x5000, v153
	s_mov_b32 m0, s4
	v_readfirstlane_b32 s4, v58
	v_lshl_add_u64 v[32:33], v[18:19], 0, v[30:31]
	v_lshlrev_b64 v[36:37], 11, v[34:35]
	v_add_u32_e32 v60, 0x6000, v153
	s_mov_b32 m0, s4
	v_readfirstlane_b32 s4, v59
	v_and_b32_e32 v147, 15, v1
	v_lshl_add_u64 v[18:19], v[18:19], 0, v[36:37]
	v_bfe_u32 v149, v1, 4, 2
	v_lshlrev_b32_e32 v35, 6, v1
	v_lshlrev_b32_e32 v38, 2, v1
	v_add_u32_e32 v61, 0x7000, v153
	s_mov_b32 m0, s4
	v_readfirstlane_b32 s4, v60
	v_lshlrev_b32_e32 v29, 4, v149
	v_and_b32_e32 v40, 0x3c0, v35
	v_lshlrev_b32_e32 v41, 6, v147
	v_and_b32_e32 v42, 32, v38
	v_lshl_add_u64 v[38:39], v[22:23], 0, 64
	v_add_u32_e32 v62, 0x8000, v153
	s_mov_b32 m0, s4
	v_readfirstlane_b32 s4, v61
	v_add_u32_e32 v63, 0x9000, v153
	v_bitop3_b32 v157, v29, v42, v40 bitop3:0x36
	v_bitop3_b32 v151, v29, v42, v41 bitop3:0x36
	v_lshl_add_u64 v[40:41], v[24:25], 0, 64
	s_mov_b32 m0, s4
	v_readfirstlane_b32 s4, v62
	v_add_u32_e32 v64, 0xa000, v153
	v_lshl_add_u64 v[42:43], v[26:27], 0, 64
	s_mov_b32 m0, s4
	v_readfirstlane_b32 s4, v63
	v_add_u32_e32 v65, 0xb000, v153
	v_lshl_add_u64 v[44:45], v[20:21], 0, 64
	s_mov_b32 m0, s4
	v_readfirstlane_b32 s4, v64
	v_lshl_add_u64 v[46:47], v[32:33], 0, 64
	s_mov_b32 m0, s4
	v_readfirstlane_b32 s4, v65
	v_lshl_add_u64 v[48:49], v[18:19], 0, 64
	s_mov_b32 m0, s4
	v_and_b32_e32 v52, 48, v153
	v_lshl_add_u64 v[18:19], s[6:7], 0, v[36:37]
	v_bitop3_b32 v18, v18, v52, v50 bitop3:0xf6
	v_lshl_add_u64 v[158:159], s[26:27], 0, v[18:19]
	v_lshl_add_u64 v[18:19], s[6:7], 0, v[30:31]
	v_bitop3_b32 v18, v18, v52, v50 bitop3:0xf6
	v_lshl_add_u64 v[160:161], s[26:27], 0, v[18:19]
	v_add3_u32 v18, s71, v57, v51
	v_ashrrev_i32_e32 v19, 31, v18
	v_lshlrev_b64 v[18:19], 11, v[18:19]
	v_bitop3_b32 v18, v18, v52, v50 bitop3:0xf6
	v_lshl_add_u64 v[162:163], s[28:29], 0, v[18:19]
	v_add3_u32 v18, s71, v55, v51
	v_ashrrev_i32_e32 v19, 31, v18
	v_lshlrev_b64 v[18:19], 11, v[18:19]
	v_bitop3_b32 v18, v18, v52, v50 bitop3:0xf6
	v_lshl_add_u64 v[164:165], s[28:29], 0, v[18:19]
	v_add_u32_e32 v18, s71, v34
	v_ashrrev_i32_e32 v19, 31, v18
	v_lshlrev_b64 v[18:19], 11, v[18:19]
	v_bitop3_b32 v18, v18, v52, v50 bitop3:0xf6
	v_lshl_add_u64 v[166:167], s[28:29], 0, v[18:19]
	v_add_u32_e32 v18, s71, v28
	v_ashrrev_i32_e32 v19, 31, v18
	v_lshlrev_b64 v[18:19], 11, v[18:19]
	v_bitop3_b32 v18, v18, v52, v50 bitop3:0xf6
	v_lshl_add_u64 v[168:169], s[28:29], 0, v[18:19]
	v_mov_b32_e32 v18, 0
	v_and_b32_e32 v155, 0xfffff000, v35
	s_mov_b32 s4, 0
	s_mov_b64 s[6:7], 0
	v_mov_b32_e32 v19, v18
	v_mov_b32_e32 v20, v18
	v_mov_b32_e32 v21, v18
	v_mov_b32_e32 v22, v18
	v_mov_b32_e32 v23, v18
	v_mov_b32_e32 v24, v18
	v_mov_b32_e32 v25, v18
	v_mov_b32_e32 v26, v18
	v_mov_b32_e32 v27, v18
	v_mov_b32_e32 v28, v18
	v_mov_b32_e32 v29, v18
	v_mov_b32_e32 v34, v18
	v_mov_b32_e32 v35, v18
	v_mov_b32_e32 v36, v18
	v_mov_b32_e32 v37, v18
	v_mov_b32_e32 v42, v18
	v_mov_b32_e32 v43, v18
	v_mov_b32_e32 v44, v18
	v_mov_b32_e32 v45, v18
	v_mov_b32_e32 v54, v18
	v_mov_b32_e32 v55, v18
	v_mov_b32_e32 v56, v18
	v_mov_b32_e32 v57, v18
	v_mov_b32_e32 v62, v18
	v_mov_b32_e32 v63, v18
	v_mov_b32_e32 v64, v18
	v_mov_b32_e32 v65, v18
	v_mov_b32_e32 v78, v18
	v_mov_b32_e32 v79, v18
	v_mov_b32_e32 v80, v18
	v_mov_b32_e32 v81, v18
	v_mov_b32_e32 v30, v18
	v_mov_b32_e32 v31, v18
	v_mov_b32_e32 v32, v18
	v_mov_b32_e32 v33, v18
	v_mov_b32_e32 v38, v18
	v_mov_b32_e32 v39, v18
	v_mov_b32_e32 v40, v18
	v_mov_b32_e32 v41, v18
	v_mov_b32_e32 v46, v18
	v_mov_b32_e32 v47, v18
	v_mov_b32_e32 v48, v18
	v_mov_b32_e32 v49, v18
	v_mov_b32_e32 v58, v18
	v_mov_b32_e32 v59, v18
	v_mov_b32_e32 v60, v18
	v_mov_b32_e32 v61, v18
	v_mov_b32_e32 v70, v18
	v_mov_b32_e32 v71, v18
	v_mov_b32_e32 v72, v18
	v_mov_b32_e32 v73, v18
	v_mov_b32_e32 v86, v18
	v_mov_b32_e32 v87, v18
	v_mov_b32_e32 v88, v18
	v_mov_b32_e32 v89, v18
	v_mov_b32_e32 v94, v18
	v_mov_b32_e32 v95, v18
	v_mov_b32_e32 v96, v18
	v_mov_b32_e32 v97, v18
	v_mov_b32_e32 v110, v18
	v_mov_b32_e32 v111, v18
	v_mov_b32_e32 v112, v18
	v_mov_b32_e32 v113, v18
	v_mov_b32_e32 v50, v18
	v_mov_b32_e32 v51, v18
	v_mov_b32_e32 v52, v18
	v_mov_b32_e32 v53, v18
	v_mov_b32_e32 v66, v18
	v_mov_b32_e32 v67, v18
	v_mov_b32_e32 v68, v18
	v_mov_b32_e32 v69, v18
	v_mov_b32_e32 v74, v18
	v_mov_b32_e32 v75, v18
	v_mov_b32_e32 v76, v18
	v_mov_b32_e32 v77, v18
	v_mov_b32_e32 v90, v18
	v_mov_b32_e32 v91, v18
	v_mov_b32_e32 v92, v18
	v_mov_b32_e32 v93, v18
	v_mov_b32_e32 v102, v18
	v_mov_b32_e32 v103, v18
	v_mov_b32_e32 v104, v18
	v_mov_b32_e32 v105, v18
	v_mov_b32_e32 v114, v18
	v_mov_b32_e32 v115, v18
	v_mov_b32_e32 v116, v18
	v_mov_b32_e32 v117, v18
	v_mov_b32_e32 v122, v18
	v_mov_b32_e32 v123, v18
	v_mov_b32_e32 v124, v18
	v_mov_b32_e32 v125, v18
	v_mov_b32_e32 v130, v18
	v_mov_b32_e32 v131, v18
	v_mov_b32_e32 v132, v18
	v_mov_b32_e32 v133, v18
	v_mov_b32_e32 v82, v18
	v_mov_b32_e32 v83, v18
	v_mov_b32_e32 v84, v18
	v_mov_b32_e32 v85, v18
	v_mov_b32_e32 v98, v18
	v_mov_b32_e32 v99, v18
	v_mov_b32_e32 v100, v18
	v_mov_b32_e32 v101, v18
	v_mov_b32_e32 v106, v18
	v_mov_b32_e32 v107, v18
	v_mov_b32_e32 v108, v18
	v_mov_b32_e32 v109, v18
	v_mov_b32_e32 v118, v18
	v_mov_b32_e32 v119, v18
	v_mov_b32_e32 v120, v18
	v_mov_b32_e32 v121, v18
	v_mov_b32_e32 v126, v18
	v_mov_b32_e32 v127, v18
	v_mov_b32_e32 v128, v18
	v_mov_b32_e32 v129, v18
	v_mov_b32_e32 v134, v18
	v_mov_b32_e32 v135, v18
	v_mov_b32_e32 v136, v18
	v_mov_b32_e32 v137, v18
	v_mov_b32_e32 v138, v18
	v_mov_b32_e32 v139, v18
	v_mov_b32_e32 v140, v18
	v_mov_b32_e32 v141, v18
	v_mov_b32_e32 v142, v18
	v_mov_b32_e32 v143, v18
	v_mov_b32_e32 v144, v18
	v_mov_b32_e32 v145, v18
	v_and_b32_e32 v224, 63, v170
	v_lshrrev_b32_e32 v225, 3, v224
	v_and_b32_e32 v226, 7, v224
	v_xor_b32_e32 v226, v226, v225
	v_lshrrev_b32_e32 v227, 6, v170
	v_lshl_add_u32 v228, v227, 6, v225
	v_add_u32_e32 v228, s71, v228
	v_mul_u32_u24_e32 v240, 0x800, v228
	v_lshl_add_u32 v240, v226, 4, v240
	v_lshl_add_u32 v228, v227, 5, v225
	v_mul_u32_u24_e32 v241, 0x800, v228
	v_lshl_add_u32 v241, v226, 4, v241
	v_and_b32_e32 v225, 15, v224
	v_lshrrev_b32_e32 v226, 4, v224
	v_and_b32_e32 v228, 7, v225
	v_xor_b32_e32 v226, v226, v228
	v_lshlrev_b32_e32 v226, 4, v226
	v_lshl_add_u32 v245, v225, 7, v226
	v_lshl_add_u32 v243, v227, 13, v245
	v_xor_b32_e32 v244, 64, v243
	v_add_u32_e32 v245, 0xc000, v245
	v_xor_b32_e32 v246, 64, v245
	s_mov_b32 s4, s8
	s_mov_b32 s5, s9
	s_lshl_b32 s32, s30, 18
	s_add_u32 s6, s57, s32
	s_addc_u32 s7, s62, 0
	s_mov_b32 s31, 0
	v_readfirstlane_b32 s32, v153
	s_lshl_b32 m0, s32, 3
	v_mov_b32_e32 v242, v240
	global_load_lds_dwordx4 v242, s[4:5]
	s_add_u32 m0, m0, 0x400
	v_add_u32_e32 v242, 0x4000, v240
	global_load_lds_dwordx4 v242, s[4:5]
	s_add_u32 m0, m0, 0x400
	v_add_u32_e32 v242, 0x8000, v240
	global_load_lds_dwordx4 v242, s[4:5]
	s_add_u32 m0, m0, 0x400
	v_add_u32_e32 v242, 0xc000, v240
	global_load_lds_dwordx4 v242, s[4:5]
	s_add_u32 m0, m0, 0x400
	v_add_u32_e32 v242, 0x10000, v240
	global_load_lds_dwordx4 v242, s[4:5]
	s_add_u32 m0, m0, 0x400
	v_add_u32_e32 v242, 0x14000, v240
	global_load_lds_dwordx4 v242, s[4:5]
	s_add_u32 m0, m0, 0x400
	v_add_u32_e32 v242, 0x18000, v240
	global_load_lds_dwordx4 v242, s[4:5]
	s_add_u32 m0, m0, 0x400
	v_add_u32_e32 v242, 0x1c000, v240
	global_load_lds_dwordx4 v242, s[4:5]
	v_readfirstlane_b32 s32, v153
	s_lshl_b32 s32, s32, 2
	s_add_u32 m0, s32, 0xc000
	v_mov_b32_e32 v242, v241
	global_load_lds_dwordx4 v242, s[6:7]
	s_add_u32 m0, m0, 0x400
	v_add_u32_e32 v242, 0x4000, v241
	global_load_lds_dwordx4 v242, s[6:7]
	s_add_u32 m0, m0, 0x400
	v_add_u32_e32 v242, 0x8000, v241
	global_load_lds_dwordx4 v242, s[6:7]
	s_add_u32 m0, m0, 0x400
	v_add_u32_e32 v242, 0xc000, v241
	global_load_lds_dwordx4 v242, s[6:7]
.Lbk64_557:
	s_waitcnt vmcnt(0)
	s_barrier
	ds_read_b128 v[192:195], v243
	ds_read_b128 v[196:199], v244
	ds_read_b128 v[200:203], v243 offset:2048
	ds_read_b128 v[204:207], v244 offset:2048
	ds_read_b128 v[208:211], v243 offset:4096
	ds_read_b128 v[212:215], v244 offset:4096
	ds_read_b128 v[216:219], v243 offset:6144
	ds_read_b128 v[220:223], v244 offset:6144
	s_add_u32 s4, s4, 0x80
	s_addc_u32 s5, s5, 0
	s_add_u32 s6, s6, 0x80
	s_addc_u32 s7, s7, 0
	s_waitcnt lgkmcnt(0)
	s_barrier
	ds_read_b128 v[224:227], v245 offset:0
	ds_read_b128 v[228:231], v246 offset:0
	ds_read_b128 v[232:235], v245 offset:2048
	ds_read_b128 v[236:239], v246 offset:2048
	s_waitcnt lgkmcnt(2)
	v_mfma_f32_16x16x32_bf16 v[142:145], v[192:195], v[224:227], v[142:145]
	v_mfma_f32_16x16x32_bf16 v[130:133], v[200:203], v[224:227], v[130:133]
	v_mfma_f32_16x16x32_bf16 v[110:113], v[208:211], v[224:227], v[110:113]
	v_mfma_f32_16x16x32_bf16 v[78:81], v[216:219], v[224:227], v[78:81]
	v_readfirstlane_b32 s32, v153
	s_lshl_b32 m0, s32, 3
	v_mov_b32_e32 v242, v240
	global_load_lds_dwordx4 v242, s[4:5]
	v_mfma_f32_16x16x32_bf16 v[142:145], v[196:199], v[228:231], v[142:145]
	v_mfma_f32_16x16x32_bf16 v[130:133], v[204:207], v[228:231], v[130:133]
	v_mfma_f32_16x16x32_bf16 v[110:113], v[212:215], v[228:231], v[110:113]
	v_mfma_f32_16x16x32_bf16 v[78:81], v[220:223], v[228:231], v[78:81]
	s_add_u32 m0, m0, 0x400
	v_add_u32_e32 v242, 0x4000, v240
	global_load_lds_dwordx4 v242, s[4:5]
	ds_read_b128 v[224:227], v245 offset:4096
	ds_read_b128 v[228:231], v246 offset:4096
	s_waitcnt lgkmcnt(2)
	v_mfma_f32_16x16x32_bf16 v[138:141], v[192:195], v[232:235], v[138:141]
	v_mfma_f32_16x16x32_bf16 v[122:125], v[200:203], v[232:235], v[122:125]
	v_mfma_f32_16x16x32_bf16 v[94:97], v[208:211], v[232:235], v[94:97]
	v_mfma_f32_16x16x32_bf16 v[62:65], v[216:219], v[232:235], v[62:65]
	s_add_u32 m0, m0, 0x400
	v_add_u32_e32 v242, 0x8000, v240
	global_load_lds_dwordx4 v242, s[4:5]
	v_mfma_f32_16x16x32_bf16 v[138:141], v[196:199], v[236:239], v[138:141]
	v_mfma_f32_16x16x32_bf16 v[122:125], v[204:207], v[236:239], v[122:125]
	v_mfma_f32_16x16x32_bf16 v[94:97], v[212:215], v[236:239], v[94:97]
	v_mfma_f32_16x16x32_bf16 v[62:65], v[220:223], v[236:239], v[62:65]
	s_add_u32 m0, m0, 0x400
	v_add_u32_e32 v242, 0xc000, v240
	global_load_lds_dwordx4 v242, s[4:5]
	ds_read_b128 v[232:235], v245 offset:6144
	ds_read_b128 v[236:239], v246 offset:6144
	s_waitcnt lgkmcnt(2)
	v_mfma_f32_16x16x32_bf16 v[134:137], v[192:195], v[224:227], v[134:137]
	v_mfma_f32_16x16x32_bf16 v[114:117], v[200:203], v[224:227], v[114:117]
	v_mfma_f32_16x16x32_bf16 v[86:89], v[208:211], v[224:227], v[86:89]
	v_mfma_f32_16x16x32_bf16 v[54:57], v[216:219], v[224:227], v[54:57]
	s_add_u32 m0, m0, 0x400
	v_add_u32_e32 v242, 0x10000, v240
	global_load_lds_dwordx4 v242, s[4:5]
	v_mfma_f32_16x16x32_bf16 v[134:137], v[196:199], v[228:231], v[134:137]
	v_mfma_f32_16x16x32_bf16 v[114:117], v[204:207], v[228:231], v[114:117]
	v_mfma_f32_16x16x32_bf16 v[86:89], v[212:215], v[228:231], v[86:89]
	v_mfma_f32_16x16x32_bf16 v[54:57], v[220:223], v[228:231], v[54:57]
	s_add_u32 m0, m0, 0x400
	v_add_u32_e32 v242, 0x14000, v240
	global_load_lds_dwordx4 v242, s[4:5]
	ds_read_b128 v[224:227], v245 offset:8192
	ds_read_b128 v[228:231], v246 offset:8192
	s_waitcnt lgkmcnt(2)
	v_mfma_f32_16x16x32_bf16 v[126:129], v[192:195], v[232:235], v[126:129]
	v_mfma_f32_16x16x32_bf16 v[102:105], v[200:203], v[232:235], v[102:105]
	v_mfma_f32_16x16x32_bf16 v[70:73], v[208:211], v[232:235], v[70:73]
	v_mfma_f32_16x16x32_bf16 v[42:45], v[216:219], v[232:235], v[42:45]
	s_add_u32 m0, m0, 0x400
	v_add_u32_e32 v242, 0x18000, v240
	global_load_lds_dwordx4 v242, s[4:5]
	v_mfma_f32_16x16x32_bf16 v[126:129], v[196:199], v[236:239], v[126:129]
	v_mfma_f32_16x16x32_bf16 v[102:105], v[204:207], v[236:239], v[102:105]
	v_mfma_f32_16x16x32_bf16 v[70:73], v[212:215], v[236:239], v[70:73]
	v_mfma_f32_16x16x32_bf16 v[42:45], v[220:223], v[236:239], v[42:45]
	s_add_u32 m0, m0, 0x400
	v_add_u32_e32 v242, 0x1c000, v240
	global_load_lds_dwordx4 v242, s[4:5]
	ds_read_b128 v[232:235], v245 offset:10240
	ds_read_b128 v[236:239], v246 offset:10240
	s_waitcnt lgkmcnt(2)
	v_mfma_f32_16x16x32_bf16 v[118:121], v[192:195], v[224:227], v[118:121]
	v_mfma_f32_16x16x32_bf16 v[90:93], v[200:203], v[224:227], v[90:93]
	v_mfma_f32_16x16x32_bf16 v[58:61], v[208:211], v[224:227], v[58:61]
	v_mfma_f32_16x16x32_bf16 v[34:37], v[216:219], v[224:227], v[34:37]
	s_add_u32 m0, s31, 16
	s_and_b32 m0, m0, 1
	s_lshl_b32 m0, m0, 14
	s_add_u32 m0, m0, 0x8000
	v_readfirstlane_b32 s32, v153
	s_lshl_b32 s32, s32, 2
	s_add_u32 m0, m0, s32
	v_mov_b32_e32 v242, v241
	global_load_lds_dwordx4 v242, s[6:7]
	v_mfma_f32_16x16x32_bf16 v[118:121], v[196:199], v[228:231], v[118:121]
	v_mfma_f32_16x16x32_bf16 v[90:93], v[204:207], v[228:231], v[90:93]
	v_mfma_f32_16x16x32_bf16 v[58:61], v[212:215], v[228:231], v[58:61]
	v_mfma_f32_16x16x32_bf16 v[34:37], v[220:223], v[228:231], v[34:37]
	s_add_u32 m0, m0, 0x400
	v_add_u32_e32 v242, 0x4000, v241
	global_load_lds_dwordx4 v242, s[6:7]
	ds_read_b128 v[224:227], v245 offset:12288
	ds_read_b128 v[228:231], v246 offset:12288
	s_waitcnt lgkmcnt(2)
	v_mfma_f32_16x16x32_bf16 v[106:109], v[192:195], v[232:235], v[106:109]
	v_mfma_f32_16x16x32_bf16 v[74:77], v[200:203], v[232:235], v[74:77]
	v_mfma_f32_16x16x32_bf16 v[46:49], v[208:211], v[232:235], v[46:49]
	v_mfma_f32_16x16x32_bf16 v[26:29], v[216:219], v[232:235], v[26:29]
	s_add_u32 m0, m0, 0x400
	v_add_u32_e32 v242, 0x8000, v241
	global_load_lds_dwordx4 v242, s[6:7]
	v_mfma_f32_16x16x32_bf16 v[106:109], v[196:199], v[236:239], v[106:109]
	v_mfma_f32_16x16x32_bf16 v[74:77], v[204:207], v[236:239], v[74:77]
	v_mfma_f32_16x16x32_bf16 v[46:49], v[212:215], v[236:239], v[46:49]
	v_mfma_f32_16x16x32_bf16 v[26:29], v[220:223], v[236:239], v[26:29]
	s_add_u32 m0, m0, 0x400
	v_add_u32_e32 v242, 0xc000, v241
	global_load_lds_dwordx4 v242, s[6:7]
	ds_read_b128 v[232:235], v245 offset:14336
	ds_read_b128 v[236:239], v246 offset:14336
	s_waitcnt lgkmcnt(2)
	v_mfma_f32_16x16x32_bf16 v[98:101], v[192:195], v[224:227], v[98:101]
	v_mfma_f32_16x16x32_bf16 v[66:69], v[200:203], v[224:227], v[66:69]
	v_mfma_f32_16x16x32_bf16 v[38:41], v[208:211], v[224:227], v[38:41]
	v_mfma_f32_16x16x32_bf16 v[22:25], v[216:219], v[224:227], v[22:25]
	v_mfma_f32_16x16x32_bf16 v[98:101], v[196:199], v[228:231], v[98:101]
	v_mfma_f32_16x16x32_bf16 v[66:69], v[204:207], v[228:231], v[66:69]
	v_mfma_f32_16x16x32_bf16 v[38:41], v[212:215], v[228:231], v[38:41]
	v_mfma_f32_16x16x32_bf16 v[22:25], v[220:223], v[228:231], v[22:25]
	s_waitcnt lgkmcnt(0)
	v_mfma_f32_16x16x32_bf16 v[82:85], v[192:195], v[232:235], v[82:85]
	v_mfma_f32_16x16x32_bf16 v[50:53], v[200:203], v[232:235], v[50:53]
	v_mfma_f32_16x16x32_bf16 v[30:33], v[208:211], v[232:235], v[30:33]
	v_mfma_f32_16x16x32_bf16 v[18:21], v[216:219], v[232:235], v[18:21]
	v_mfma_f32_16x16x32_bf16 v[82:85], v[196:199], v[236:239], v[82:85]
	v_mfma_f32_16x16x32_bf16 v[50:53], v[204:207], v[236:239], v[50:53]
	v_mfma_f32_16x16x32_bf16 v[30:33], v[212:215], v[236:239], v[30:33]
	v_mfma_f32_16x16x32_bf16 v[18:21], v[220:223], v[236:239], v[18:21]
	v_xor_b32_e32 v245, 0x4000, v245
	v_xor_b32_e32 v246, 0x4000, v246
	s_add_i32 s31, s31, 1
	s_cmp_lg_u32 s31, 14
	s_cbranch_scc1 .Lbk64_557
	s_waitcnt vmcnt(0)
	s_barrier
	ds_read_b128 v[192:195], v243
	ds_read_b128 v[196:199], v244
	ds_read_b128 v[200:203], v243 offset:2048
	ds_read_b128 v[204:207], v244 offset:2048
	ds_read_b128 v[208:211], v243 offset:4096
	ds_read_b128 v[212:215], v244 offset:4096
	ds_read_b128 v[216:219], v243 offset:6144
	ds_read_b128 v[220:223], v244 offset:6144
	s_waitcnt lgkmcnt(0)
	s_barrier
	ds_read_b128 v[224:227], v245 offset:0
	ds_read_b128 v[228:231], v246 offset:0
	ds_read_b128 v[232:235], v245 offset:2048
	ds_read_b128 v[236:239], v246 offset:2048
	s_waitcnt lgkmcnt(2)
	v_mfma_f32_16x16x32_bf16 v[142:145], v[192:195], v[224:227], v[142:145]
	v_mfma_f32_16x16x32_bf16 v[130:133], v[200:203], v[224:227], v[130:133]
	v_mfma_f32_16x16x32_bf16 v[110:113], v[208:211], v[224:227], v[110:113]
	v_mfma_f32_16x16x32_bf16 v[78:81], v[216:219], v[224:227], v[78:81]
	s_mov_b64 s[4:5], 0x700
	v_readfirstlane_b32 s32, v153
	s_mov_b32 m0, s32
	v_lshl_add_u64 v[240:241], v[168:169], 0, s[4:5]
	global_load_lds_dwordx4 v[240:241], off
	v_mfma_f32_16x16x32_bf16 v[142:145], v[196:199], v[228:231], v[142:145]
	v_mfma_f32_16x16x32_bf16 v[130:133], v[204:207], v[228:231], v[130:133]
	v_mfma_f32_16x16x32_bf16 v[110:113], v[212:215], v[228:231], v[110:113]
	v_mfma_f32_16x16x32_bf16 v[78:81], v[220:223], v[228:231], v[78:81]
	s_add_u32 m0, m0, 0x1000
	v_lshl_add_u64 v[240:241], v[166:167], 0, s[4:5]
	global_load_lds_dwordx4 v[240:241], off
	ds_read_b128 v[224:227], v245 offset:4096
	ds_read_b128 v[228:231], v246 offset:4096
	s_waitcnt lgkmcnt(2)
	v_mfma_f32_16x16x32_bf16 v[138:141], v[192:195], v[232:235], v[138:141]
	v_mfma_f32_16x16x32_bf16 v[122:125], v[200:203], v[232:235], v[122:125]
	v_mfma_f32_16x16x32_bf16 v[94:97], v[208:211], v[232:235], v[94:97]
	v_mfma_f32_16x16x32_bf16 v[62:65], v[216:219], v[232:235], v[62:65]
	s_add_u32 m0, m0, 0x1000
	v_lshl_add_u64 v[240:241], v[164:165], 0, s[4:5]
	global_load_lds_dwordx4 v[240:241], off
	v_mfma_f32_16x16x32_bf16 v[138:141], v[196:199], v[236:239], v[138:141]
	v_mfma_f32_16x16x32_bf16 v[122:125], v[204:207], v[236:239], v[122:125]
	v_mfma_f32_16x16x32_bf16 v[94:97], v[212:215], v[236:239], v[94:97]
	v_mfma_f32_16x16x32_bf16 v[62:65], v[220:223], v[236:239], v[62:65]
	s_add_u32 m0, m0, 0x1000
	v_lshl_add_u64 v[240:241], v[162:163], 0, s[4:5]
	global_load_lds_dwordx4 v[240:241], off
	ds_read_b128 v[232:235], v245 offset:6144
	ds_read_b128 v[236:239], v246 offset:6144
	s_waitcnt lgkmcnt(2)
	v_mfma_f32_16x16x32_bf16 v[134:137], v[192:195], v[224:227], v[134:137]
	v_mfma_f32_16x16x32_bf16 v[114:117], v[200:203], v[224:227], v[114:117]
	v_mfma_f32_16x16x32_bf16 v[86:89], v[208:211], v[224:227], v[86:89]
	v_mfma_f32_16x16x32_bf16 v[54:57], v[216:219], v[224:227], v[54:57]
	s_add_u32 m0, m0, 0x1000
	v_lshl_add_u64 v[240:241], v[160:161], 0, s[4:5]
	global_load_lds_dwordx4 v[240:241], off
	v_mfma_f32_16x16x32_bf16 v[134:137], v[196:199], v[228:231], v[134:137]
	v_mfma_f32_16x16x32_bf16 v[114:117], v[204:207], v[228:231], v[114:117]
	v_mfma_f32_16x16x32_bf16 v[86:89], v[212:215], v[228:231], v[86:89]
	v_mfma_f32_16x16x32_bf16 v[54:57], v[220:223], v[228:231], v[54:57]
	s_add_u32 m0, m0, 0x1000
	v_lshl_add_u64 v[240:241], v[158:159], 0, s[4:5]
	global_load_lds_dwordx4 v[240:241], off
	ds_read_b128 v[224:227], v245 offset:8192
	ds_read_b128 v[228:231], v246 offset:8192
	s_waitcnt lgkmcnt(2)
	v_mfma_f32_16x16x32_bf16 v[126:129], v[192:195], v[232:235], v[126:129]
	v_mfma_f32_16x16x32_bf16 v[102:105], v[200:203], v[232:235], v[102:105]
	v_mfma_f32_16x16x32_bf16 v[70:73], v[208:211], v[232:235], v[70:73]
	v_mfma_f32_16x16x32_bf16 v[42:45], v[216:219], v[232:235], v[42:45]
	s_mov_b64 s[4:5], 0x740
	v_readfirstlane_b32 s32, v153
	s_add_u32 m0, s32, 0x6000
	v_lshl_add_u64 v[240:241], v[168:169], 0, s[4:5]
	global_load_lds_dwordx4 v[240:241], off
	v_mfma_f32_16x16x32_bf16 v[126:129], v[196:199], v[236:239], v[126:129]
	v_mfma_f32_16x16x32_bf16 v[102:105], v[204:207], v[236:239], v[102:105]
	v_mfma_f32_16x16x32_bf16 v[70:73], v[212:215], v[236:239], v[70:73]
	v_mfma_f32_16x16x32_bf16 v[42:45], v[220:223], v[236:239], v[42:45]
	s_add_u32 m0, m0, 0x1000
	v_lshl_add_u64 v[240:241], v[166:167], 0, s[4:5]
	global_load_lds_dwordx4 v[240:241], off
	ds_read_b128 v[232:235], v245 offset:10240
	ds_read_b128 v[236:239], v246 offset:10240
	s_waitcnt lgkmcnt(2)
	v_mfma_f32_16x16x32_bf16 v[118:121], v[192:195], v[224:227], v[118:121]
	v_mfma_f32_16x16x32_bf16 v[90:93], v[200:203], v[224:227], v[90:93]
	v_mfma_f32_16x16x32_bf16 v[58:61], v[208:211], v[224:227], v[58:61]
	v_mfma_f32_16x16x32_bf16 v[34:37], v[216:219], v[224:227], v[34:37]
	s_add_u32 m0, m0, 0x1000
	v_lshl_add_u64 v[240:241], v[164:165], 0, s[4:5]
	global_load_lds_dwordx4 v[240:241], off
	v_mfma_f32_16x16x32_bf16 v[118:121], v[196:199], v[228:231], v[118:121]
	v_mfma_f32_16x16x32_bf16 v[90:93], v[204:207], v[228:231], v[90:93]
	v_mfma_f32_16x16x32_bf16 v[58:61], v[212:215], v[228:231], v[58:61]
	v_mfma_f32_16x16x32_bf16 v[34:37], v[220:223], v[228:231], v[34:37]
	s_add_u32 m0, m0, 0x1000
	v_lshl_add_u64 v[240:241], v[162:163], 0, s[4:5]
	global_load_lds_dwordx4 v[240:241], off
	ds_read_b128 v[224:227], v245 offset:12288
	ds_read_b128 v[228:231], v246 offset:12288
	s_waitcnt lgkmcnt(2)
	v_mfma_f32_16x16x32_bf16 v[106:109], v[192:195], v[232:235], v[106:109]
	v_mfma_f32_16x16x32_bf16 v[74:77], v[200:203], v[232:235], v[74:77]
	v_mfma_f32_16x16x32_bf16 v[46:49], v[208:211], v[232:235], v[46:49]
	v_mfma_f32_16x16x32_bf16 v[26:29], v[216:219], v[232:235], v[26:29]
	s_add_u32 m0, m0, 0x1000
	v_lshl_add_u64 v[240:241], v[160:161], 0, s[4:5]
	global_load_lds_dwordx4 v[240:241], off
	v_mfma_f32_16x16x32_bf16 v[106:109], v[196:199], v[236:239], v[106:109]
	v_mfma_f32_16x16x32_bf16 v[74:77], v[204:207], v[236:239], v[74:77]
	v_mfma_f32_16x16x32_bf16 v[46:49], v[212:215], v[236:239], v[46:49]
	v_mfma_f32_16x16x32_bf16 v[26:29], v[220:223], v[236:239], v[26:29]
	s_add_u32 m0, m0, 0x1000
	v_lshl_add_u64 v[240:241], v[158:159], 0, s[4:5]
	global_load_lds_dwordx4 v[240:241], off
	ds_read_b128 v[232:235], v245 offset:14336
	ds_read_b128 v[236:239], v246 offset:14336
	s_waitcnt lgkmcnt(2)
	v_mfma_f32_16x16x32_bf16 v[98:101], v[192:195], v[224:227], v[98:101]
	v_mfma_f32_16x16x32_bf16 v[66:69], v[200:203], v[224:227], v[66:69]
	v_mfma_f32_16x16x32_bf16 v[38:41], v[208:211], v[224:227], v[38:41]
	v_mfma_f32_16x16x32_bf16 v[22:25], v[216:219], v[224:227], v[22:25]
	v_mfma_f32_16x16x32_bf16 v[98:101], v[196:199], v[228:231], v[98:101]
	v_mfma_f32_16x16x32_bf16 v[66:69], v[204:207], v[228:231], v[66:69]
	v_mfma_f32_16x16x32_bf16 v[38:41], v[212:215], v[228:231], v[38:41]
	v_mfma_f32_16x16x32_bf16 v[22:25], v[220:223], v[228:231], v[22:25]
	s_waitcnt lgkmcnt(0)
	v_mfma_f32_16x16x32_bf16 v[82:85], v[192:195], v[232:235], v[82:85]
	v_mfma_f32_16x16x32_bf16 v[50:53], v[200:203], v[232:235], v[50:53]
	v_mfma_f32_16x16x32_bf16 v[30:33], v[208:211], v[232:235], v[30:33]
	v_mfma_f32_16x16x32_bf16 v[18:21], v[216:219], v[232:235], v[18:21]
	v_mfma_f32_16x16x32_bf16 v[82:85], v[196:199], v[236:239], v[82:85]
	v_mfma_f32_16x16x32_bf16 v[50:53], v[204:207], v[236:239], v[50:53]
	v_mfma_f32_16x16x32_bf16 v[30:33], v[212:215], v[236:239], v[30:33]
	v_mfma_f32_16x16x32_bf16 v[18:21], v[220:223], v[236:239], v[18:21]
	s_waitcnt vmcnt(6)
	s_barrier
	v_add_u32_e32 v153, v157, v155
	ds_read_b128 v[158:161], v153
	ds_read_b128 v[162:165], v151 offset:16384
	ds_read_b128 v[166:169], v153 offset:1024
	ds_read_b128 v[192:195], v153 offset:2048
	ds_read_b128 v[196:199], v153 offset:3072
	s_waitcnt lgkmcnt(0)
	v_mfma_f32_16x16x32_bf16 v[142:145], v[158:161], v[162:165], v[142:145]
	v_and_b32_e32 v1, 0xfffffc0, v1
	v_lshl_or_b32 v1, v149, 2, v1
	v_mul_lo_u32 v1, v1, s33
	v_mfma_f32_16x16x32_bf16 v[130:133], v[166:169], v[162:165], v[130:133]
	v_lshl_or_b32 v1, v147, 2, v1
	s_lshl_b32 s31, s30, 1
	s_mov_b64 s[4:5], -1
	v_mfma_f32_16x16x32_bf16 v[110:113], v[192:195], v[162:165], v[110:113]
	s_cmp_lg_u32 s30, 20
	v_mfma_f32_16x16x32_bf16 v[78:81], v[196:199], v[162:165], v[78:81]
	ds_read_b128 v[162:165], v151 offset:17408
	s_waitcnt lgkmcnt(0)
	v_mfma_f32_16x16x32_bf16 v[138:141], v[158:161], v[162:165], v[138:141]
	v_mfma_f32_16x16x32_bf16 v[122:125], v[166:169], v[162:165], v[122:125]
	v_mfma_f32_16x16x32_bf16 v[94:97], v[192:195], v[162:165], v[94:97]
	v_mfma_f32_16x16x32_bf16 v[62:65], v[196:199], v[162:165], v[62:65]
	ds_read_b128 v[162:165], v151 offset:18432
	s_waitcnt lgkmcnt(0)
	v_mfma_f32_16x16x32_bf16 v[134:137], v[158:161], v[162:165], v[134:137]
	v_mfma_f32_16x16x32_bf16 v[114:117], v[166:169], v[162:165], v[114:117]
	v_mfma_f32_16x16x32_bf16 v[86:89], v[192:195], v[162:165], v[86:89]
	v_mfma_f32_16x16x32_bf16 v[54:57], v[196:199], v[162:165], v[54:57]
	ds_read_b128 v[162:165], v151 offset:19456
	s_waitcnt lgkmcnt(0)
	v_mfma_f32_16x16x32_bf16 v[126:129], v[158:161], v[162:165], v[126:129]
	v_mfma_f32_16x16x32_bf16 v[102:105], v[166:169], v[162:165], v[102:105]
	v_mfma_f32_16x16x32_bf16 v[70:73], v[192:195], v[162:165], v[70:73]
	v_mfma_f32_16x16x32_bf16 v[42:45], v[196:199], v[162:165], v[42:45]
	ds_read_b128 v[162:165], v151 offset:20480
	s_waitcnt lgkmcnt(0)
	v_mfma_f32_16x16x32_bf16 v[118:121], v[158:161], v[162:165], v[118:121]
	v_mfma_f32_16x16x32_bf16 v[90:93], v[166:169], v[162:165], v[90:93]
	v_mfma_f32_16x16x32_bf16 v[58:61], v[192:195], v[162:165], v[58:61]
	v_mfma_f32_16x16x32_bf16 v[34:37], v[196:199], v[162:165], v[34:37]
	ds_read_b128 v[162:165], v151 offset:21504
	s_waitcnt lgkmcnt(0)
	v_mfma_f32_16x16x32_bf16 v[106:109], v[158:161], v[162:165], v[106:109]
	v_mfma_f32_16x16x32_bf16 v[74:77], v[166:169], v[162:165], v[74:77]
	v_mfma_f32_16x16x32_bf16 v[46:49], v[192:195], v[162:165], v[46:49]
	v_mfma_f32_16x16x32_bf16 v[162:165], v[196:199], v[162:165], v[26:29]
	s_nop 2
	ds_read_b128 v[26:29], v151 offset:22528
	s_waitcnt lgkmcnt(0)
	v_mfma_f32_16x16x32_bf16 v[204:207], v[196:199], v[26:29], v[22:25]
	s_nop 2
	ds_read_b128 v[22:25], v151 offset:23552
	s_waitcnt vmcnt(0)
	s_barrier
	v_mfma_f32_16x16x32_bf16 v[98:101], v[158:161], v[26:29], v[98:101]
	v_mfma_f32_16x16x32_bf16 v[200:203], v[166:169], v[26:29], v[66:69]
	v_mfma_f32_16x16x32_bf16 v[38:41], v[192:195], v[26:29], v[38:41]
	s_waitcnt vmcnt(0)
	s_nop 0
	v_mov_b32_e32 v66, v15
	v_mov_b32_e32 v67, v16
	v_mov_b32_e32 v68, v11
	s_waitcnt lgkmcnt(0)
	v_mfma_f32_16x16x32_bf16 v[50:53], v[166:169], v[22:25], v[50:53]
	ds_read_b128 v[166:169], v153 offset:24576
	ds_read_b128 v[26:29], v151 offset:40960
	v_mov_b32_e32 v69, v12
	v_mov_b32_e32 v15, v17
	v_mfma_f32_16x16x32_bf16 v[82:85], v[158:161], v[22:25], v[82:85]
	v_mov_b32_e32 v11, v13
	v_pk_add_f32 v[14:15], v[66:67], v[14:15]
	v_pk_add_f32 v[10:11], v[68:69], v[10:11]
	v_mfma_f32_16x16x32_bf16 v[158:161], v[192:195], v[22:25], v[30:33]
	v_pk_add_f32 v[14:15], v[14:15], v[14:15] op_sel:[0,1] op_sel_hi:[1,0]
	v_pk_add_f32 v[16:17], v[10:11], v[10:11] op_sel:[0,1] op_sel_hi:[1,0]
	v_mov_b32_e32 v15, v2
	v_mfma_f32_16x16x32_bf16 v[192:195], v[196:199], v[22:25], v[18:21]
	ds_read_b128 v[196:199], v153 offset:25600
	s_nop 1
	ds_read_b128 v[18:21], v151 offset:41984
	ds_read_b128 v[208:211], v153 offset:27648
	v_mov_b32_e32 v17, v3
	s_waitcnt lgkmcnt(3)
	v_mfma_f32_16x16x32_bf16 v[22:25], v[166:169], v[26:29], v[142:145]
	v_add_f32_e64 v14, v14, v16
	v_add_f32_e64 v15, v15, v17
	s_nop 0
	ds_read_b128 v[142:145], v153 offset:26624
	s_waitcnt lgkmcnt(3)
	v_mfma_f32_16x16x32_bf16 v[30:33], v[196:199], v[26:29], v[130:133]
	s_waitcnt lgkmcnt(0)
	v_mfma_f32_16x16x32_bf16 v[110:113], v[142:145], v[26:29], v[110:113]
	v_mfma_f32_16x16x32_bf16 v[78:81], v[208:211], v[26:29], v[78:81]
	v_mov_b32_e32 v26, v7
	v_pk_add_f32 v[66:67], v[6:7], v[26:27]
	v_mov_b32_e32 v6, v9
	v_pk_add_f32 v[68:69], v[8:9], v[6:7]
	v_mov_b32_e32 v67, v4
	v_mov_b32_e32 v69, v5
	v_pk_add_f32 v[16:17], v[66:67], v[68:69]
	ds_read_b128 v[6:9], v151 offset:43008
	ds_read_b128 v[2:5], v151 offset:44032
	v_pk_add_f32 v[14:15], v[14:15], v[16:17]
	v_mfma_f32_16x16x32_bf16 v[26:29], v[196:199], v[18:21], v[122:125]
	v_add_f32_e32 v14, v14, v15
	v_fmamk_f32 v14, v14, 0x3a800000, v172
	v_mul_f32_e32 v15, 0x4b800000, v14
	v_cmp_gt_f32_e32 vcc, s58, v14
	v_mfma_f32_16x16x32_bf16 v[122:125], v[142:145], v[18:21], v[94:97]
	s_nop 2
	ds_read_b128 v[94:97], v151 offset:45056
	ds_read_b128 v[130:133], v151 offset:46080
	v_cndmask_b32_e32 v14, v14, v15, vcc
	v_rsq_f32_e32 v14, v14
	v_mfma_f32_16x16x32_bf16 v[10:13], v[166:169], v[18:21], v[138:141]
	v_add_u32_e32 v67, 0x1000, v1
	v_mul_f32_e32 v15, 0x45800000, v14
	v_mfma_f32_16x16x32_bf16 v[62:65], v[208:211], v[18:21], v[62:65]
	v_cndmask_b32_e32 v66, v14, v15, vcc
	s_waitcnt lgkmcnt(3)
	v_mfma_f32_16x16x32_bf16 v[18:21], v[166:169], v[6:9], v[134:137]
	v_mfma_f32_16x16x32_bf16 v[114:117], v[196:199], v[6:9], v[114:117]
	v_mfma_f32_16x16x32_bf16 v[86:89], v[142:145], v[6:9], v[86:89]
	v_mfma_f32_16x16x32_bf16 v[54:57], v[208:211], v[6:9], v[54:57]
	s_waitcnt lgkmcnt(2)
	v_mfma_f32_16x16x32_bf16 v[6:9], v[166:169], v[2:5], v[126:129]
	s_nop 2
	ds_read_b128 v[126:129], v151 offset:47104
	ds_read_b128 v[134:137], v151 offset:48128
	s_waitcnt lgkmcnt(0)
	s_barrier
	v_mfma_f32_16x16x32_bf16 v[102:105], v[196:199], v[2:5], v[102:105]
	ds_write2_b32 v1, v22, v10 offset1:16
	ds_write2_b32 v1, v23, v11 offset0:68 offset1:84
	ds_write2_b32 v1, v24, v12 offset0:136 offset1:152
	ds_write2_b32 v1, v25, v13 offset0:204 offset1:220
	ds_write2_b32 v1, v18, v6 offset0:32 offset1:48
	ds_write2_b32 v1, v19, v7 offset0:100 offset1:116
	v_mfma_f32_16x16x32_bf16 v[68:71], v[142:145], v[2:5], v[70:73]
	ds_write2_b32 v1, v20, v8 offset0:168 offset1:184
	ds_write2_b32 v1, v21, v9 offset0:236 offset1:252
	ds_write2_b32 v67, v30, v26 offset0:64 offset1:80
	ds_write2_b32 v67, v31, v27 offset0:132 offset1:148
	ds_write2_b32 v67, v32, v28 offset0:200 offset1:216
	v_mfma_f32_16x16x32_bf16 v[138:141], v[208:211], v[2:5], v[42:45]
	v_mfma_f32_16x16x32_bf16 v[14:17], v[166:169], v[94:97], v[118:121]
	v_mfma_f32_16x16x32_bf16 v[10:13], v[196:199], v[94:97], v[90:93]
	v_mfma_f32_16x16x32_bf16 v[6:9], v[142:145], v[94:97], v[58:61]
	v_mfma_f32_16x16x32_bf16 v[2:5], v[208:211], v[94:97], v[34:37]
	v_add_u32_e32 v94, 0x1400, v1
	v_add_u32_e32 v95, 0x2000, v1
	v_add_u32_e32 v96, 0x2400, v1
	v_mfma_f32_16x16x32_bf16 v[22:25], v[142:145], v[130:133], v[46:49]
	v_add_u32_e32 v97, 0x3000, v1
	ds_write2_b32 v94, v33, v29 offset0:12 offset1:28
	ds_write2_b32 v67, v114, v102 offset0:96 offset1:112
	ds_write2_b32 v67, v115, v103 offset0:164 offset1:180
	ds_write2_b32 v67, v116, v104 offset0:232 offset1:248
	ds_write2_b32 v94, v117, v105 offset0:44 offset1:60
	v_mfma_f32_16x16x32_bf16 v[46:49], v[166:169], v[126:129], v[98:101]
	ds_write2_b32 v95, v110, v122 offset0:128 offset1:144
	ds_write2_b32 v95, v111, v123 offset0:196 offset1:212
	ds_write2_b32 v96, v112, v124 offset0:8 offset1:24
	ds_write2_b32 v96, v113, v125 offset0:76 offset1:92
	v_add_u32_e32 v98, 0x3400, v1
	v_mfma_f32_16x16x32_bf16 v[30:33], v[166:169], v[130:133], v[106:109]
	ds_write2_b32 v95, v86, v68 offset0:160 offset1:176
	ds_write2_b32 v95, v87, v69 offset0:228 offset1:244
	ds_write2_b32 v96, v88, v70 offset0:40 offset1:56
	ds_write2_b32 v96, v89, v71 offset0:108 offset1:124
	ds_write2_b32 v97, v78, v62 offset0:192 offset1:208
	v_mfma_f32_16x16x32_bf16 v[26:29], v[196:199], v[130:133], v[74:77]
	ds_write2_b32 v98, v79, v63 offset0:4 offset1:20
	ds_write2_b32 v98, v80, v64 offset0:72 offset1:88
	ds_write2_b32 v98, v81, v65 offset0:140 offset1:156
	ds_write2_b32 v97, v54, v138 offset0:224 offset1:240
	ds_write2_b32 v98, v55, v139 offset0:36 offset1:52
	ds_write2_b32 v98, v56, v140 offset0:104 offset1:120
	ds_write2_b32 v98, v57, v141 offset0:172 offset1:188
	v_mfma_f32_16x16x32_bf16 v[18:21], v[208:211], v[130:133], v[162:165]
	v_mov_b32_e32 v100, v170
	s_waitcnt lgkmcnt(0)
	s_barrier
	v_mfma_f32_16x16x32_bf16 v[42:45], v[196:199], v[126:129], v[200:203]
	v_mfma_f32_16x16x32_bf16 v[38:41], v[142:145], v[126:129], v[38:41]
	v_add_u32_e32 v68, s71, v100
	v_ashrrev_i32_e32 v69, 31, v68
	v_mul_lo_u32 v99, v100, s33
	v_mfma_f32_16x16x32_bf16 v[34:37], v[208:211], v[126:129], v[204:207]
	v_mfma_f32_16x16x32_bf16 v[62:65], v[166:169], v[134:137], v[82:85]
	v_mfma_f32_16x16x32_bf16 v[58:61], v[196:199], v[134:137], v[50:53]
	v_mfma_f32_16x16x32_bf16 v[54:57], v[142:145], v[134:137], v[158:161]
	v_mfma_f32_16x16x32_bf16 v[50:53], v[208:211], v[134:137], v[192:195]
	s_cbranch_scc0 .LBB0_570
	v_cmp_gt_i32_e32 vcc, s78, v68
	s_nop 1
	v_cndmask_b32_e32 v70, v179, v173, vcc
	v_and_b32_e32 v101, v70, v68
	v_mov_b64_e32 v[70:71], s[38:39]
	v_mad_i64_i32 v[70:71], s[4:5], v68, s59, v[70:71]
	s_lshl_b32 s4, s30, 7
	s_ashr_i32 s5, s4, 31
	v_lshl_add_u64 v[70:71], s[4:5], 1, v[70:71]
	s_sub_i32 s4, s31, 28
	s_cmp_gt_u32 s4, 9
	s_mov_b64 s[4:5], -1
	s_cbranch_scc0 .LBB0_566
	s_cmp_lt_i32 s30, 2
	v_mul_f32_e32 v72, 0x3e38aa3b, v66
	s_cselect_b64 vcc, -1, 0
	s_cmp_lt_i32 s30, 4
	v_cndmask_b32_e32 v72, v66, v72, vcc
	s_cselect_b64 s[6:7], -1, 0
	v_lshlrev_b32_e32 v74, 6, v101
	v_mov_b32_e32 v75, v0
	v_lshl_add_u64 v[74:75], s[16:17], 0, v[74:75]
	v_mov_b32_e32 v73, v72
	s_mov_b32 s4, 0
	s_xor_b64 s[6:7], s[6:7], -1
	v_mov_b64_e32 v[76:77], v[70:71]
	s_branch .LBB0_562
